# v50 + fragment ds_reads issued first in every mainloop load segment, m0 writes reordered so the s_nop before each LDS-DMA issue is dropped
# baseline (speedup 1.0000x reference)
; #define PG8_STAGE(bufoff, gbase, voff) do { _Pragma("unroll") for (int _i = 0; _i < 2; ++_i) \
;         __builtin_amdgcn_global_load_lds((const unsigned*)((const char*)(gbase) + (voff)[_i]), (PG8_LAS unsigned*)(lds + (bufoff) + ldsw + _i * (8 * USTR)), 16, 0, 0); } while (0)
; #define PG8_LDA(dst, b, h) do { _Pragma("unroll") for (int m = 0; m < 4; ++m) _Pragma("unroll") for (int k = 0; k < 2; ++k) dst[m][k] = *(const PG8_LAS bf16x8*)(lds + PG8_SA(b, h) + aoff + m * (2 * USTR) + k * 64); } while (0)
; #define PG8_LDB(dst, b, h) do { _Pragma("unroll") for (int n = 0; n < 2; ++n) _Pragma("unroll") for (int k = 0; k < 2; ++k) dst[n][k] = *(const PG8_LAS bf16x8*)(lds + PG8_SB(b, h) + boff + n * (2 * USTR) + k * 64); } while (0)
; #define PG8_MMA(ai, bj, At, Bt) do { __builtin_amdgcn_s_setprio(1); _Pragma("unroll") for (int m = 0; m < 4; ++m) _Pragma("unroll") for (int n = 0; n < 2; ++n) _Pragma("unroll") for (int k = 0; k < 2; ++k) \
;         acc[ai][bj][m][n] = __builtin_amdgcn_mfma_f32_16x16x32_bf16(Bt[n][k], At[m][k], acc[ai][bj][m][n], 0, 0, 0); __builtin_amdgcn_s_setprio(0); } while (0)
; #define PG8_WAIT_V(n) asm volatile("s_waitcnt vmcnt(" #n ")" ::: "memory")
; #define PG8_WAIT_L(n) asm volatile("s_waitcnt lgkmcnt(" #n ")" ::: "memory")
; #define PG8_BAR __builtin_amdgcn_s_barrier()
; #define PG8_SCHED __builtin_amdgcn_sched_barrier(0)
; template <class Epi, class Sched, bool ALIGN_EPI, bool SP2>
; __device__ __forceinline__ void gemm_phase(PG8_LAS unsigned char* lds, const Gemm g, const Sched& S, const Epi& E, int wid) {
;     ...
;             PG8_LDB(B0, 0, 0); PG8_LDB(B1, 0, 1); PG8_SCHED; PG8_LDA(At, 0, 0); PG8_STAGE(PG8_SA(1, 1), a1 + hstepA, voffA);
;             PG8_WAIT_V(8); PG8_WAIT_L(0); PG8_BAR; PG8_MMA(0, 0, At, B0); PG8_MMA(0, 1, At, B1); PG8_BAR; PG8_SCHED;
;             PG8_LDA(At, 0, 1); PG8_STAGE(PG8_SB(0, 0), b2, voffB); PG8_STAGE(PG8_SB(0, 1), b2 + hstepB, voffB); PG8_STAGE(PG8_SA(0, 0), a2, voffA);
;             PG8_WAIT_V(8); PG8_WAIT_L(0); PG8_BAR; PG8_MMA(1, 0, At, B0); PG8_MMA(1, 1, At, B1); PG8_BAR; PG8_SCHED;
.Lhb_mixout:
	s_add_i32 s95, 0, 0x11000
	s_add_i32 s44, 0, 0x15400
	v_add_u32_e32 v60, s95, v216
	v_add_u32_e32 v156, s44, v216
	ds_read_b128 v[48:51], v60
	ds_read_b128 v[52:55], v60 offset:64
	ds_read_b128 v[56:59], v60 offset:2176
	ds_read_b128 v[60:63], v60 offset:2240
	ds_read_b128 v[144:147], v156
	ds_read_b128 v[148:151], v156 offset:64
	ds_read_b128 v[152:155], v156 offset:2176
	ds_read_b128 v[156:159], v156 offset:2240
	ds_read_b128 v[172:175], v217
	ds_read_b128 v[176:179], v217 offset:64
	ds_read_b128 v[180:183], v217 offset:2176
	ds_read_b128 v[184:187], v217 offset:2240
	ds_read_b128 v[188:191], v217 offset:4352
	ds_read_b128 v[208:211], v217 offset:4416
	ds_read_b128 v[212:215], v217 offset:6528
	ds_read_b128 v[218:221], v217 offset:6592
	s_add_i32 m0, s0, 0xcc00
	v_lshl_add_u64 v[198:199], s[38:39], 0, v[168:169]
	global_load_lds_dwordx4 v[198:199], off
	s_add_i32 m0, s0, 0xee00
	v_lshl_add_u64 v[198:199], s[38:39], 0, v[170:171]
	global_load_lds_dwordx4 v[198:199], off
	s_add_u32 s40, s38, 0xfff80080
	s_addc_u32 s41, s39, -1
	s_cmp_eq_u32 s89, 12
	s_cselect_b32 s75, s26, s41
	s_cselect_b32 s74, s27, s40
	s_cselect_b32 s41, s23, s79
	s_cselect_b32 s40, s69, s78
	s_waitcnt vmcnt(8)
	s_waitcnt lgkmcnt(0)
	s_barrier
	s_setprio 1
	s_waitcnt lgkmcnt(0)
	v_mfma_f32_16x16x32_bf16 v[140:143], v[48:51], v[172:175], 0
	v_mfma_f32_16x16x32_bf16 v[136:139], v[56:59], v[172:175], 0
	v_mfma_f32_16x16x32_bf16 v[124:127], v[48:51], v[180:183], 0
	v_mfma_f32_16x16x32_bf16 v[120:123], v[56:59], v[180:183], 0
	v_mfma_f32_16x16x32_bf16 v[108:111], v[48:51], v[188:191], 0
	v_mfma_f32_16x16x32_bf16 v[104:107], v[56:59], v[188:191], 0
	v_mfma_f32_16x16x32_bf16 v[92:95], v[48:51], v[212:215], 0
	v_mfma_f32_16x16x32_bf16 v[88:91], v[56:59], v[212:215], 0
	v_mfma_f32_16x16x32_bf16 v[140:143], v[52:55], v[176:179], v[140:143]
	v_mfma_f32_16x16x32_bf16 v[136:139], v[60:63], v[176:179], v[136:139]
	v_mfma_f32_16x16x32_bf16 v[124:127], v[52:55], v[184:187], v[124:127]
	v_mfma_f32_16x16x32_bf16 v[120:123], v[60:63], v[184:187], v[120:123]
	v_mfma_f32_16x16x32_bf16 v[108:111], v[52:55], v[208:211], v[108:111]
	v_mfma_f32_16x16x32_bf16 v[104:107], v[60:63], v[208:211], v[104:107]
	v_mfma_f32_16x16x32_bf16 v[92:95], v[52:55], v[218:221], v[92:95]
	v_mfma_f32_16x16x32_bf16 v[88:91], v[60:63], v[218:221], v[88:91]
	s_setprio 0
	s_setprio 1
	v_mfma_f32_16x16x32_bf16 v[132:135], v[144:147], v[172:175], 0
	v_mfma_f32_16x16x32_bf16 v[128:131], v[152:155], v[172:175], 0
	v_mfma_f32_16x16x32_bf16 v[116:119], v[144:147], v[180:183], 0
	v_mfma_f32_16x16x32_bf16 v[112:115], v[152:155], v[180:183], 0
	v_mfma_f32_16x16x32_bf16 v[100:103], v[144:147], v[188:191], 0
	v_mfma_f32_16x16x32_bf16 v[96:99], v[152:155], v[188:191], 0
	v_mfma_f32_16x16x32_bf16 v[84:87], v[144:147], v[212:215], 0
	v_mfma_f32_16x16x32_bf16 v[80:83], v[152:155], v[212:215], 0
	v_mfma_f32_16x16x32_bf16 v[132:135], v[148:151], v[176:179], v[132:135]
	v_mfma_f32_16x16x32_bf16 v[128:131], v[156:159], v[176:179], v[128:131]
	v_mfma_f32_16x16x32_bf16 v[116:119], v[148:151], v[184:187], v[116:119]
	v_mfma_f32_16x16x32_bf16 v[112:115], v[156:159], v[184:187], v[112:115]
	v_mfma_f32_16x16x32_bf16 v[100:103], v[148:151], v[208:211], v[100:103]
	v_mfma_f32_16x16x32_bf16 v[96:99], v[156:159], v[208:211], v[96:99]
	v_mfma_f32_16x16x32_bf16 v[84:87], v[148:151], v[218:221], v[84:87]
	v_mfma_f32_16x16x32_bf16 v[80:83], v[156:159], v[218:221], v[80:83]
	s_setprio 0
	s_barrier
	ds_read_b128 v[172:175], v217 offset:17408
	ds_read_b128 v[176:179], v217 offset:17472
	ds_read_b128 v[180:183], v217 offset:19584
	ds_read_b128 v[184:187], v217 offset:19648
	ds_read_b128 v[188:191], v217 offset:21760
	ds_read_b128 v[208:211], v217 offset:21824
	ds_read_b128 v[212:215], v217 offset:23936
	ds_read_b128 v[218:221], v217 offset:24000
	s_add_i32 s45, s95, s33
	s_mov_b32 m0, s45
	v_lshl_add_u64 v[198:199], s[40:41], 0, v[192:193]
	global_load_lds_dwordx4 v[198:199], off
	s_add_i32 m0, s45, 0x2200
	s_add_u32 vcc_lo, s40, 0x40000
	v_lshl_add_u64 v[200:201], s[40:41], 0, v[160:161]
	s_addc_u32 vcc_hi, s41, 0
	s_add_i32 s44, s44, s33
	global_load_lds_dwordx4 v[200:201], off
	v_lshl_add_u64 v[222:223], vcc, 0, v[192:193]
	s_mov_b32 m0, s44
	v_lshl_add_u64 v[224:225], s[74:75], 0, v[162:163]
	global_load_lds_dwordx4 v[222:223], off
	s_add_i32 m0, s44, 0x2200
	v_lshl_add_u64 v[222:223], vcc, 0, v[160:161]
	global_load_lds_dwordx4 v[222:223], off
	s_mov_b32 m0, s0
	v_lshl_add_u64 v[222:223], s[74:75], 0, v[164:165]
	global_load_lds_dwordx4 v[222:223], off
	s_mov_b32 m0, s5
	s_nop 0
	global_load_lds_dwordx4 v[224:225], off
	s_waitcnt vmcnt(8)
	s_waitcnt lgkmcnt(0)
	s_barrier
; #define PG8_STAGE(bufoff, gbase, voff) do { _Pragma("unroll") for (int _i = 0; _i < 2; ++_i) \
;         __builtin_amdgcn_global_load_lds((const unsigned*)((const char*)(gbase) + (voff)[_i]), (PG8_LAS unsigned*)(lds + (bufoff) + ldsw + _i * (8 * USTR)), 16, 0, 0); } while (0)
; #define PG8_LDA(dst, b, h) do { _Pragma("unroll") for (int m = 0; m < 4; ++m) _Pragma("unroll") for (int k = 0; k < 2; ++k) dst[m][k] = *(const PG8_LAS bf16x8*)(lds + PG8_SA(b, h) + aoff + m * (2 * USTR) + k * 64); } while (0)
; #define PG8_LDB(dst, b, h) do { _Pragma("unroll") for (int n = 0; n < 2; ++n) _Pragma("unroll") for (int k = 0; k < 2; ++k) dst[n][k] = *(const PG8_LAS bf16x8*)(lds + PG8_SB(b, h) + boff + n * (2 * USTR) + k * 64); } while (0)
; #define PG8_MMA(ai, bj, At, Bt) do { __builtin_amdgcn_s_setprio(1); _Pragma("unroll") for (int m = 0; m < 4; ++m) _Pragma("unroll") for (int n = 0; n < 2; ++n) _Pragma("unroll") for (int k = 0; k < 2; ++k) \
;         acc[ai][bj][m][n] = __builtin_amdgcn_mfma_f32_16x16x32_bf16(Bt[n][k], At[m][k], acc[ai][bj][m][n], 0, 0, 0); __builtin_amdgcn_s_setprio(0); } while (0)
; #define PG8_WAIT_V(n) asm volatile("s_waitcnt vmcnt(" #n ")" ::: "memory")
; #define PG8_WAIT_L(n) asm volatile("s_waitcnt lgkmcnt(" #n ")" ::: "memory")
; #define PG8_BAR __builtin_amdgcn_s_barrier()
; #define PG8_SCHED __builtin_amdgcn_sched_barrier(0)
; template <class Epi, class Sched, bool ALIGN_EPI, bool SP2>
; __device__ __forceinline__ void gemm_phase(PG8_LAS unsigned char* lds, const Gemm g, const Sched& S, const Epi& E, int wid) {
;     ...
;             PG8_WAIT_V(8); PG8_WAIT_L(0); PG8_BAR; PG8_MMA(1, 0, At, B0); PG8_MMA(1, 1, At, B1); PG8_BAR; PG8_SCHED;
;             PG8_LDB(B0, 1, 0); PG8_LDB(B1, 1, 1); PG8_SCHED; PG8_LDA(At, 1, 0); PG8_STAGE(PG8_SA(0, 1), a2 + hstepA, voffA);
;             PG8_WAIT_V(8); PG8_WAIT_L(0); PG8_BAR; PG8_MMA(0, 0, At, B0); PG8_MMA(0, 1, At, B1); PG8_BAR; PG8_SCHED;
	s_setprio 1
	s_waitcnt lgkmcnt(0)
	v_mfma_f32_16x16x32_bf16 v[76:79], v[48:51], v[172:175], 0
	v_mfma_f32_16x16x32_bf16 v[72:75], v[56:59], v[172:175], 0
	v_mfma_f32_16x16x32_bf16 v[44:47], v[48:51], v[180:183], 0
	v_mfma_f32_16x16x32_bf16 v[40:43], v[56:59], v[180:183], 0
	v_mfma_f32_16x16x32_bf16 v[24:27], v[48:51], v[188:191], 0
	v_mfma_f32_16x16x32_bf16 v[28:31], v[56:59], v[188:191], 0
	v_mfma_f32_16x16x32_bf16 v[4:7], v[48:51], v[212:215], 0
	v_mfma_f32_16x16x32_bf16 v[12:15], v[56:59], v[212:215], 0
	v_mfma_f32_16x16x32_bf16 v[76:79], v[52:55], v[176:179], v[76:79]
	v_mfma_f32_16x16x32_bf16 v[72:75], v[60:63], v[176:179], v[72:75]
	v_mfma_f32_16x16x32_bf16 v[44:47], v[52:55], v[184:187], v[44:47]
	v_mfma_f32_16x16x32_bf16 v[40:43], v[60:63], v[184:187], v[40:43]
	v_mfma_f32_16x16x32_bf16 v[24:27], v[52:55], v[208:211], v[24:27]
	v_mfma_f32_16x16x32_bf16 v[28:31], v[60:63], v[208:211], v[28:31]
	v_mfma_f32_16x16x32_bf16 v[4:7], v[52:55], v[218:221], v[4:7]
	v_mfma_f32_16x16x32_bf16 v[12:15], v[60:63], v[218:221], v[12:15]
	s_setprio 0
	s_setprio 1
	v_mfma_f32_16x16x32_bf16 v[36:39], v[144:147], v[180:183], 0
	v_mfma_f32_16x16x32_bf16 v[32:35], v[152:155], v[180:183], 0
	v_mfma_f32_16x16x32_bf16 v[20:23], v[144:147], v[188:191], 0
	v_mfma_f32_16x16x32_bf16 v[16:19], v[152:155], v[188:191], 0
	v_mfma_f32_16x16x32_bf16 v[8:11], v[144:147], v[212:215], 0
	v_mfma_f32_16x16x32_bf16 v[0:3], v[152:155], v[212:215], 0
	v_mfma_f32_16x16x32_bf16 v[48:51], v[144:147], v[172:175], 0
	v_mfma_f32_16x16x32_bf16 v[52:55], v[152:155], v[172:175], 0
	v_mfma_f32_16x16x32_bf16 v[36:39], v[148:151], v[184:187], v[36:39]
	v_mfma_f32_16x16x32_bf16 v[32:35], v[156:159], v[184:187], v[32:35]
	v_mfma_f32_16x16x32_bf16 v[20:23], v[148:151], v[208:211], v[20:23]
	v_mfma_f32_16x16x32_bf16 v[16:19], v[156:159], v[208:211], v[16:19]
	v_mfma_f32_16x16x32_bf16 v[8:11], v[148:151], v[218:221], v[8:11]
	v_mfma_f32_16x16x32_bf16 v[0:3], v[156:159], v[218:221], v[0:3]
	v_mfma_f32_16x16x32_bf16 v[48:51], v[148:151], v[176:179], v[48:51]
	v_mfma_f32_16x16x32_bf16 v[52:55], v[156:159], v[176:179], v[52:55]
	s_setprio 0
	s_barrier
	s_add_i32 s44, 0, 0x19800
	s_add_i32 s45, 0, 0x1dc00
	v_add_u32_e32 v68, s44, v216
	v_add_u32_e32 v156, s45, v216
	ds_read_b128 v[56:59], v68
	ds_read_b128 v[60:63], v68 offset:64
	ds_read_b128 v[64:67], v68 offset:2176
	ds_read_b128 v[68:71], v68 offset:2240
	ds_read_b128 v[144:147], v156
	ds_read_b128 v[148:151], v156 offset:64
	ds_read_b128 v[152:155], v156 offset:2176
	ds_read_b128 v[156:159], v156 offset:2240
	ds_read_b128 v[172:175], v217 offset:34816
	ds_read_b128 v[176:179], v217 offset:34880
	ds_read_b128 v[180:183], v217 offset:36992
	ds_read_b128 v[184:187], v217 offset:37056
	ds_read_b128 v[188:191], v217 offset:39168
	ds_read_b128 v[208:211], v217 offset:39232
	ds_read_b128 v[212:215], v217 offset:41344
	ds_read_b128 v[218:221], v217 offset:41408
	s_add_u32 s74, s74, 0x80000
	s_addc_u32 s75, s75, 0
	s_mov_b32 m0, s29
	v_lshl_add_u64 v[226:227], s[74:75], 0, v[164:165]
	global_load_lds_dwordx4 v[226:227], off
	s_mov_b32 m0, s56
	v_lshl_add_u64 v[226:227], s[74:75], 0, v[162:163]
	global_load_lds_dwordx4 v[226:227], off
	s_waitcnt vmcnt(8)
	s_waitcnt lgkmcnt(0)
	s_barrier
	s_setprio 1
	s_waitcnt lgkmcnt(0)
	v_mfma_f32_16x16x32_bf16 v[140:143], v[56:59], v[172:175], v[140:143]
	v_mfma_f32_16x16x32_bf16 v[136:139], v[64:67], v[172:175], v[136:139]
	v_mfma_f32_16x16x32_bf16 v[124:127], v[56:59], v[180:183], v[124:127]
	v_mfma_f32_16x16x32_bf16 v[120:123], v[64:67], v[180:183], v[120:123]
	v_mfma_f32_16x16x32_bf16 v[108:111], v[56:59], v[188:191], v[108:111]
	v_mfma_f32_16x16x32_bf16 v[104:107], v[64:67], v[188:191], v[104:107]
	v_mfma_f32_16x16x32_bf16 v[92:95], v[56:59], v[212:215], v[92:95]
	v_mfma_f32_16x16x32_bf16 v[88:91], v[64:67], v[212:215], v[88:91]
	v_mfma_f32_16x16x32_bf16 v[140:143], v[60:63], v[176:179], v[140:143]
	v_mfma_f32_16x16x32_bf16 v[136:139], v[68:71], v[176:179], v[136:139]
	v_mfma_f32_16x16x32_bf16 v[124:127], v[60:63], v[184:187], v[124:127]
	v_mfma_f32_16x16x32_bf16 v[120:123], v[68:71], v[184:187], v[120:123]
	v_mfma_f32_16x16x32_bf16 v[108:111], v[60:63], v[208:211], v[108:111]
	v_mfma_f32_16x16x32_bf16 v[104:107], v[68:71], v[208:211], v[104:107]
	v_mfma_f32_16x16x32_bf16 v[92:95], v[60:63], v[218:221], v[92:95]
	v_mfma_f32_16x16x32_bf16 v[88:91], v[68:71], v[218:221], v[88:91]
	s_setprio 0
	s_setprio 1
	v_mfma_f32_16x16x32_bf16 v[132:135], v[144:147], v[172:175], v[132:135]
	v_mfma_f32_16x16x32_bf16 v[128:131], v[152:155], v[172:175], v[128:131]
	v_mfma_f32_16x16x32_bf16 v[116:119], v[144:147], v[180:183], v[116:119]
	v_mfma_f32_16x16x32_bf16 v[112:115], v[152:155], v[180:183], v[112:115]
	v_mfma_f32_16x16x32_bf16 v[100:103], v[144:147], v[188:191], v[100:103]
	v_mfma_f32_16x16x32_bf16 v[96:99], v[152:155], v[188:191], v[96:99]
	v_mfma_f32_16x16x32_bf16 v[84:87], v[144:147], v[212:215], v[84:87]
	v_mfma_f32_16x16x32_bf16 v[80:83], v[152:155], v[212:215], v[80:83]
	v_mfma_f32_16x16x32_bf16 v[132:135], v[148:151], v[176:179], v[132:135]
	v_mfma_f32_16x16x32_bf16 v[128:131], v[156:159], v[176:179], v[128:131]
	v_mfma_f32_16x16x32_bf16 v[116:119], v[148:151], v[184:187], v[116:119]
	v_mfma_f32_16x16x32_bf16 v[112:115], v[156:159], v[184:187], v[112:115]
	v_mfma_f32_16x16x32_bf16 v[100:103], v[148:151], v[208:211], v[100:103]
	v_mfma_f32_16x16x32_bf16 v[96:99], v[156:159], v[208:211], v[96:99]
	v_mfma_f32_16x16x32_bf16 v[84:87], v[148:151], v[218:221], v[84:87]
	v_mfma_f32_16x16x32_bf16 v[80:83], v[156:159], v[218:221], v[80:83]
	s_setprio 0
	s_barrier
; #define PG8_STAGE(bufoff, gbase, voff) do { _Pragma("unroll") for (int _i = 0; _i < 2; ++_i) \
;         __builtin_amdgcn_global_load_lds((const unsigned*)((const char*)(gbase) + (voff)[_i]), (PG8_LAS unsigned*)(lds + (bufoff) + ldsw + _i * (8 * USTR)), 16, 0, 0); } while (0)
; #define PG8_LDA(dst, b, h) do { _Pragma("unroll") for (int m = 0; m < 4; ++m) _Pragma("unroll") for (int k = 0; k < 2; ++k) dst[m][k] = *(const PG8_LAS bf16x8*)(lds + PG8_SA(b, h) + aoff + m * (2 * USTR) + k * 64); } while (0)
; #define PG8_LDB(dst, b, h) do { _Pragma("unroll") for (int n = 0; n < 2; ++n) _Pragma("unroll") for (int k = 0; k < 2; ++k) dst[n][k] = *(const PG8_LAS bf16x8*)(lds + PG8_SB(b, h) + boff + n * (2 * USTR) + k * 64); } while (0)
; #define PG8_MMA(ai, bj, At, Bt) do { __builtin_amdgcn_s_setprio(1); _Pragma("unroll") for (int m = 0; m < 4; ++m) _Pragma("unroll") for (int n = 0; n < 2; ++n) _Pragma("unroll") for (int k = 0; k < 2; ++k) \
;         acc[ai][bj][m][n] = __builtin_amdgcn_mfma_f32_16x16x32_bf16(Bt[n][k], At[m][k], acc[ai][bj][m][n], 0, 0, 0); __builtin_amdgcn_s_setprio(0); } while (0)
; #define PG8_BAR __builtin_amdgcn_s_barrier()
; template <class Epi, class Sched, bool ALIGN_EPI, bool SP2>
; __device__ __forceinline__ void gemm_phase(PG8_LAS unsigned char* lds, const Gemm g, const Sched& S, const Epi& E, int wid) {
;     ...
;             PG8_LDB(B0, 0, 0); PG8_LDB(B1, 0, 1); PG8_SCHED; PG8_LDA(At, 0, 0); PG8_STAGE(PG8_SA(1, 1), a1 + hstepA, voffA);
;             PG8_WAIT_V(8); PG8_WAIT_L(0); PG8_BAR; PG8_MMA(0, 0, At, B0); PG8_MMA(0, 1, At, B1); PG8_BAR; PG8_SCHED;
;             PG8_LDA(At, 0, 1); PG8_STAGE(PG8_SB(0, 0), b2, voffB); PG8_STAGE(PG8_SB(0, 1), b2 + hstepB, voffB); PG8_STAGE(PG8_SA(0, 0), a2, voffA);
;             PG8_WAIT_V(8); PG8_WAIT_L(0); PG8_BAR; PG8_MMA(1, 0, At, B0); PG8_MMA(1, 1, At, B1); PG8_BAR; PG8_SCHED;
;             PG8_LDB(B0, 1, 0); PG8_LDB(B1, 1, 1); PG8_SCHED; PG8_LDA(At, 1, 0); PG8_STAGE(PG8_SA(0, 1), a2 + hstepA, voffA);
;             PG8_WAIT_V(8); PG8_WAIT_L(0); PG8_BAR; PG8_MMA(0, 0, At, B0); PG8_MMA(0, 1, At, B1); PG8_BAR; PG8_SCHED;
;             PG8_LDA(At, 1, 1); PG8_STAGE(PG8_SB(1, 0), b3, voffB); PG8_STAGE(PG8_SB(1, 1), b3 + hstepB, voffB); PG8_STAGE(PG8_SA(1, 0), a3, voffA);
;             PG8_WAIT_V(8); PG8_WAIT_L(0); PG8_BAR; PG8_MMA(1, 0, At, B0); PG8_MMA(1, 1, At, B1); PG8_BAR; PG8_SCHED;
	ds_read_b128 v[172:175], v217 offset:52224
	ds_read_b128 v[176:179], v217 offset:52288
	ds_read_b128 v[180:183], v217 offset:54400
	ds_read_b128 v[184:187], v217 offset:54464
	ds_read_b128 v[188:191], v217 offset:56576
	ds_read_b128 v[208:211], v217 offset:56640
	ds_read_b128 v[212:215], v217 offset:58752
	ds_read_b128 v[218:221], v217 offset:58816
	s_add_i32 s44, s44, s33
	s_mov_b32 m0, s44
	v_lshl_add_u64 v[198:199], v[198:199], 0, s[6:7]
	global_load_lds_dwordx4 v[198:199], off
	s_add_i32 m0, s44, 0x2200
	s_add_u32 s40, s40, 0x40080
	v_lshl_add_u64 v[198:199], v[200:201], 0, s[6:7]
	s_addc_u32 s41, s41, 0
	s_add_i32 s44, s45, s33
	global_load_lds_dwordx4 v[198:199], off
	s_mov_b32 m0, s44
	v_lshl_add_u64 v[198:199], s[40:41], 0, v[192:193]
	global_load_lds_dwordx4 v[198:199], off
	s_add_i32 m0, s44, 0x2200
	v_lshl_add_u64 v[198:199], s[40:41], 0, v[160:161]
	global_load_lds_dwordx4 v[198:199], off
	s_mov_b32 m0, s57
	v_lshl_add_u64 v[198:199], v[222:223], 0, s[6:7]
	global_load_lds_dwordx4 v[198:199], off
	s_mov_b32 m0, s76
	v_lshl_add_u64 v[198:199], v[224:225], 0, s[6:7]
	global_load_lds_dwordx4 v[198:199], off
	s_add_i32 s89, s89, 2
	s_add_u32 s38, s38, 0x100
	s_addc_u32 s39, s39, 0
	s_add_u32 s78, s78, 0x100
	s_addc_u32 s79, s79, 0
	s_waitcnt vmcnt(8)
	s_waitcnt lgkmcnt(0)
	s_barrier
	s_setprio 1
	s_waitcnt lgkmcnt(0)
	v_mfma_f32_16x16x32_bf16 v[76:79], v[56:59], v[172:175], v[76:79]
	v_mfma_f32_16x16x32_bf16 v[72:75], v[64:67], v[172:175], v[72:75]
	v_mfma_f32_16x16x32_bf16 v[44:47], v[56:59], v[180:183], v[44:47]
	v_mfma_f32_16x16x32_bf16 v[40:43], v[64:67], v[180:183], v[40:43]
	v_mfma_f32_16x16x32_bf16 v[24:27], v[56:59], v[188:191], v[24:27]
	v_mfma_f32_16x16x32_bf16 v[28:31], v[64:67], v[188:191], v[28:31]
	v_mfma_f32_16x16x32_bf16 v[4:7], v[56:59], v[212:215], v[4:7]
	v_mfma_f32_16x16x32_bf16 v[12:15], v[64:67], v[212:215], v[12:15]
	v_mfma_f32_16x16x32_bf16 v[76:79], v[60:63], v[176:179], v[76:79]
	v_mfma_f32_16x16x32_bf16 v[72:75], v[68:71], v[176:179], v[72:75]
	v_mfma_f32_16x16x32_bf16 v[44:47], v[60:63], v[184:187], v[44:47]
	v_mfma_f32_16x16x32_bf16 v[40:43], v[68:71], v[184:187], v[40:43]
	v_mfma_f32_16x16x32_bf16 v[24:27], v[60:63], v[208:211], v[24:27]
	v_mfma_f32_16x16x32_bf16 v[28:31], v[68:71], v[208:211], v[28:31]
	v_mfma_f32_16x16x32_bf16 v[4:7], v[60:63], v[218:221], v[4:7]
	v_mfma_f32_16x16x32_bf16 v[12:15], v[68:71], v[218:221], v[12:15]
	s_setprio 0
	s_setprio 1
	v_mfma_f32_16x16x32_bf16 v[48:51], v[144:147], v[172:175], v[48:51]
	v_mfma_f32_16x16x32_bf16 v[68:71], v[148:151], v[176:179], v[48:51]
	v_mfma_f32_16x16x32_bf16 v[48:51], v[152:155], v[172:175], v[52:55]
	v_mfma_f32_16x16x32_bf16 v[36:39], v[144:147], v[180:183], v[36:39]
	v_mfma_f32_16x16x32_bf16 v[32:35], v[152:155], v[180:183], v[32:35]
	v_mfma_f32_16x16x32_bf16 v[20:23], v[144:147], v[188:191], v[20:23]
	v_mfma_f32_16x16x32_bf16 v[16:19], v[152:155], v[188:191], v[16:19]
	v_mfma_f32_16x16x32_bf16 v[8:11], v[144:147], v[212:215], v[8:11]
	v_mfma_f32_16x16x32_bf16 v[0:3], v[152:155], v[212:215], v[0:3]
	v_mfma_f32_16x16x32_bf16 v[64:67], v[156:159], v[176:179], v[48:51]
	v_mfma_f32_16x16x32_bf16 v[36:39], v[148:151], v[184:187], v[36:39]
	v_mfma_f32_16x16x32_bf16 v[32:35], v[156:159], v[184:187], v[32:35]
	v_mfma_f32_16x16x32_bf16 v[20:23], v[148:151], v[208:211], v[20:23]
	v_mfma_f32_16x16x32_bf16 v[16:19], v[156:159], v[208:211], v[16:19]
	v_mfma_f32_16x16x32_bf16 v[8:11], v[148:151], v[218:221], v[8:11]
	v_mfma_f32_16x16x32_bf16 v[0:3], v[156:159], v[218:221], v[0:3]
	s_setprio 0
	s_barrier
	s_cmp_gt_u32 s89, 13
.LBB0_150:
	s_add_i32 s95, 0, 0x11000
	s_add_i32 s44, 0, 0x15400
	v_add_u32_e32 v60, s95, v216
	v_add_u32_e32 v156, s44, v216
	ds_read_b128 v[48:51], v60
	ds_read_b128 v[52:55], v60 offset:64
	ds_read_b128 v[56:59], v60 offset:2176
	ds_read_b128 v[60:63], v60 offset:2240
	ds_read_b128 v[144:147], v156
	ds_read_b128 v[148:151], v156 offset:64
	ds_read_b128 v[152:155], v156 offset:2176
	ds_read_b128 v[156:159], v156 offset:2240
	ds_read_b128 v[172:175], v217
	ds_read_b128 v[176:179], v217 offset:64
	ds_read_b128 v[180:183], v217 offset:2176
	ds_read_b128 v[184:187], v217 offset:2240
	ds_read_b128 v[188:191], v217 offset:4352
	ds_read_b128 v[208:211], v217 offset:4416
	ds_read_b128 v[212:215], v217 offset:6528
	ds_read_b128 v[218:221], v217 offset:6592
	s_add_i32 m0, s0, 0xcc00
	v_lshl_add_u64 v[198:199], s[38:39], 0, v[168:169]
	global_load_lds_dwordx4 v[198:199], off
	s_add_i32 m0, s0, 0xee00
	v_lshl_add_u64 v[198:199], s[38:39], 0, v[170:171]
	global_load_lds_dwordx4 v[198:199], off
	s_add_u32 s40, s38, 0xfff80080
	s_addc_u32 s41, s39, -1
	s_cmp_eq_u32 s89, 12
	s_cselect_b32 s75, s26, s41
	s_cselect_b32 s74, s27, s40
	s_cselect_b32 s41, s23, s79
	s_cselect_b32 s40, s69, s78
	s_waitcnt vmcnt(8)
	s_waitcnt lgkmcnt(0)
	s_barrier
; #define PG8_STAGE(bufoff, gbase, voff) do { _Pragma("unroll") for (int _i = 0; _i < 2; ++_i) \
;         __builtin_amdgcn_global_load_lds((const unsigned*)((const char*)(gbase) + (voff)[_i]), (PG8_LAS unsigned*)(lds + (bufoff) + ldsw + _i * (8 * USTR)), 16, 0, 0); } while (0)
; #define PG8_LDA(dst, b, h) do { _Pragma("unroll") for (int m = 0; m < 4; ++m) _Pragma("unroll") for (int k = 0; k < 2; ++k) dst[m][k] = *(const PG8_LAS bf16x8*)(lds + PG8_SA(b, h) + aoff + m * (2 * USTR) + k * 64); } while (0)
; #define PG8_MMA(ai, bj, At, Bt) do { __builtin_amdgcn_s_setprio(1); _Pragma("unroll") for (int m = 0; m < 4; ++m) _Pragma("unroll") for (int n = 0; n < 2; ++n) _Pragma("unroll") for (int k = 0; k < 2; ++k) \
;         acc[ai][bj][m][n] = __builtin_amdgcn_mfma_f32_16x16x32_bf16(Bt[n][k], At[m][k], acc[ai][bj][m][n], 0, 0, 0); __builtin_amdgcn_s_setprio(0); } while (0)
; #define PG8_WAIT_V(n) asm volatile("s_waitcnt vmcnt(" #n ")" ::: "memory")
; #define PG8_WAIT_L(n) asm volatile("s_waitcnt lgkmcnt(" #n ")" ::: "memory")
; #define PG8_BAR __builtin_amdgcn_s_barrier()
; #define PG8_SCHED __builtin_amdgcn_sched_barrier(0)
; template <class Epi, class Sched, bool ALIGN_EPI, bool SP2>
; __device__ __forceinline__ void gemm_phase(PG8_LAS unsigned char* lds, const Gemm g, const Sched& S, const Epi& E, int wid) {
;     ...
;             PG8_WAIT_V(8); PG8_WAIT_L(0); PG8_BAR; PG8_MMA(0, 0, At, B0); PG8_MMA(0, 1, At, B1); PG8_BAR; PG8_SCHED;
;             PG8_LDA(At, 0, 1); PG8_STAGE(PG8_SB(0, 0), b2, voffB); PG8_STAGE(PG8_SB(0, 1), b2 + hstepB, voffB); PG8_STAGE(PG8_SA(0, 0), a2, voffA);
;             PG8_WAIT_V(8); PG8_WAIT_L(0); PG8_BAR; PG8_MMA(1, 0, At, B0); PG8_MMA(1, 1, At, B1); PG8_BAR; PG8_SCHED;
	s_setprio 1
	s_waitcnt lgkmcnt(0)
	v_mfma_f32_16x16x32_bf16 v[140:143], v[48:51], v[172:175], v[140:143]
	v_mfma_f32_16x16x32_bf16 v[136:139], v[56:59], v[172:175], v[136:139]
	v_mfma_f32_16x16x32_bf16 v[124:127], v[48:51], v[180:183], v[124:127]
	v_mfma_f32_16x16x32_bf16 v[120:123], v[56:59], v[180:183], v[120:123]
	v_mfma_f32_16x16x32_bf16 v[108:111], v[48:51], v[188:191], v[108:111]
	v_mfma_f32_16x16x32_bf16 v[104:107], v[56:59], v[188:191], v[104:107]
	v_mfma_f32_16x16x32_bf16 v[92:95], v[48:51], v[212:215], v[92:95]
	v_mfma_f32_16x16x32_bf16 v[88:91], v[56:59], v[212:215], v[88:91]
	v_mfma_f32_16x16x32_bf16 v[140:143], v[52:55], v[176:179], v[140:143]
	v_mfma_f32_16x16x32_bf16 v[136:139], v[60:63], v[176:179], v[136:139]
	v_mfma_f32_16x16x32_bf16 v[124:127], v[52:55], v[184:187], v[124:127]
	v_mfma_f32_16x16x32_bf16 v[120:123], v[60:63], v[184:187], v[120:123]
	v_mfma_f32_16x16x32_bf16 v[108:111], v[52:55], v[208:211], v[108:111]
	v_mfma_f32_16x16x32_bf16 v[104:107], v[60:63], v[208:211], v[104:107]
	v_mfma_f32_16x16x32_bf16 v[92:95], v[52:55], v[218:221], v[92:95]
	v_mfma_f32_16x16x32_bf16 v[88:91], v[60:63], v[218:221], v[88:91]
	s_setprio 0
	s_setprio 1
	v_mfma_f32_16x16x32_bf16 v[132:135], v[144:147], v[172:175], v[132:135]
	v_mfma_f32_16x16x32_bf16 v[128:131], v[152:155], v[172:175], v[128:131]
	v_mfma_f32_16x16x32_bf16 v[116:119], v[144:147], v[180:183], v[116:119]
	v_mfma_f32_16x16x32_bf16 v[112:115], v[152:155], v[180:183], v[112:115]
	v_mfma_f32_16x16x32_bf16 v[100:103], v[144:147], v[188:191], v[100:103]
	v_mfma_f32_16x16x32_bf16 v[96:99], v[152:155], v[188:191], v[96:99]
	v_mfma_f32_16x16x32_bf16 v[84:87], v[144:147], v[212:215], v[84:87]
	v_mfma_f32_16x16x32_bf16 v[80:83], v[152:155], v[212:215], v[80:83]
	v_mfma_f32_16x16x32_bf16 v[132:135], v[148:151], v[176:179], v[132:135]
	v_mfma_f32_16x16x32_bf16 v[128:131], v[156:159], v[176:179], v[128:131]
	v_mfma_f32_16x16x32_bf16 v[116:119], v[148:151], v[184:187], v[116:119]
	v_mfma_f32_16x16x32_bf16 v[112:115], v[156:159], v[184:187], v[112:115]
	v_mfma_f32_16x16x32_bf16 v[100:103], v[148:151], v[208:211], v[100:103]
	v_mfma_f32_16x16x32_bf16 v[96:99], v[156:159], v[208:211], v[96:99]
	v_mfma_f32_16x16x32_bf16 v[84:87], v[148:151], v[218:221], v[84:87]
	v_mfma_f32_16x16x32_bf16 v[80:83], v[156:159], v[218:221], v[80:83]
	s_setprio 0
	s_barrier
	ds_read_b128 v[172:175], v217 offset:17408
	ds_read_b128 v[176:179], v217 offset:17472
	ds_read_b128 v[180:183], v217 offset:19584
	ds_read_b128 v[184:187], v217 offset:19648
	ds_read_b128 v[188:191], v217 offset:21760
	ds_read_b128 v[208:211], v217 offset:21824
	ds_read_b128 v[212:215], v217 offset:23936
	ds_read_b128 v[218:221], v217 offset:24000
	s_add_i32 s45, s95, s33
	s_mov_b32 m0, s45
	v_lshl_add_u64 v[198:199], s[40:41], 0, v[192:193]
	global_load_lds_dwordx4 v[198:199], off
	s_add_i32 m0, s45, 0x2200
	s_add_u32 vcc_lo, s40, 0x40000
	v_lshl_add_u64 v[200:201], s[40:41], 0, v[160:161]
	s_addc_u32 vcc_hi, s41, 0
	s_add_i32 s44, s44, s33
	global_load_lds_dwordx4 v[200:201], off
	v_lshl_add_u64 v[222:223], vcc, 0, v[192:193]
	s_mov_b32 m0, s44
	v_lshl_add_u64 v[224:225], s[74:75], 0, v[162:163]
	global_load_lds_dwordx4 v[222:223], off
	s_add_i32 m0, s44, 0x2200
	v_lshl_add_u64 v[222:223], vcc, 0, v[160:161]
	global_load_lds_dwordx4 v[222:223], off
	s_mov_b32 m0, s0
	v_lshl_add_u64 v[222:223], s[74:75], 0, v[164:165]
	global_load_lds_dwordx4 v[222:223], off
	s_mov_b32 m0, s5
	s_nop 0
	global_load_lds_dwordx4 v[224:225], off
	s_waitcnt vmcnt(8)
	s_waitcnt lgkmcnt(0)
	s_barrier
	s_setprio 1
	s_waitcnt lgkmcnt(0)
	v_mfma_f32_16x16x32_bf16 v[76:79], v[48:51], v[172:175], v[76:79]
	v_mfma_f32_16x16x32_bf16 v[72:75], v[56:59], v[172:175], v[72:75]
	v_mfma_f32_16x16x32_bf16 v[44:47], v[48:51], v[180:183], v[44:47]
	v_mfma_f32_16x16x32_bf16 v[40:43], v[56:59], v[180:183], v[40:43]
	v_mfma_f32_16x16x32_bf16 v[24:27], v[48:51], v[188:191], v[24:27]
	v_mfma_f32_16x16x32_bf16 v[28:31], v[56:59], v[188:191], v[28:31]
	v_mfma_f32_16x16x32_bf16 v[4:7], v[48:51], v[212:215], v[4:7]
	v_mfma_f32_16x16x32_bf16 v[12:15], v[56:59], v[212:215], v[12:15]
	v_mfma_f32_16x16x32_bf16 v[76:79], v[52:55], v[176:179], v[76:79]
	v_mfma_f32_16x16x32_bf16 v[72:75], v[60:63], v[176:179], v[72:75]
	v_mfma_f32_16x16x32_bf16 v[44:47], v[52:55], v[184:187], v[44:47]
	v_mfma_f32_16x16x32_bf16 v[40:43], v[60:63], v[184:187], v[40:43]
	v_mfma_f32_16x16x32_bf16 v[24:27], v[52:55], v[208:211], v[24:27]
	v_mfma_f32_16x16x32_bf16 v[28:31], v[60:63], v[208:211], v[28:31]
	v_mfma_f32_16x16x32_bf16 v[4:7], v[52:55], v[218:221], v[4:7]
	v_mfma_f32_16x16x32_bf16 v[12:15], v[60:63], v[218:221], v[12:15]
	s_setprio 0
	s_setprio 1
	v_mfma_f32_16x16x32_bf16 v[36:39], v[144:147], v[180:183], v[36:39]
	v_mfma_f32_16x16x32_bf16 v[32:35], v[152:155], v[180:183], v[32:35]
	v_mfma_f32_16x16x32_bf16 v[20:23], v[144:147], v[188:191], v[20:23]
	v_mfma_f32_16x16x32_bf16 v[16:19], v[152:155], v[188:191], v[16:19]
	v_mfma_f32_16x16x32_bf16 v[8:11], v[144:147], v[212:215], v[8:11]
	v_mfma_f32_16x16x32_bf16 v[0:3], v[152:155], v[212:215], v[0:3]
	v_mfma_f32_16x16x32_bf16 v[48:51], v[144:147], v[172:175], v[68:71]
	v_mfma_f32_16x16x32_bf16 v[52:55], v[152:155], v[172:175], v[64:67]
	v_mfma_f32_16x16x32_bf16 v[36:39], v[148:151], v[184:187], v[36:39]
	v_mfma_f32_16x16x32_bf16 v[32:35], v[156:159], v[184:187], v[32:35]
	v_mfma_f32_16x16x32_bf16 v[20:23], v[148:151], v[208:211], v[20:23]
	v_mfma_f32_16x16x32_bf16 v[16:19], v[156:159], v[208:211], v[16:19]
	v_mfma_f32_16x16x32_bf16 v[8:11], v[148:151], v[218:221], v[8:11]
	v_mfma_f32_16x16x32_bf16 v[0:3], v[156:159], v[218:221], v[0:3]
	v_mfma_f32_16x16x32_bf16 v[48:51], v[148:151], v[176:179], v[48:51]
	v_mfma_f32_16x16x32_bf16 v[52:55], v[156:159], v[176:179], v[52:55]
	s_setprio 0
	s_barrier
; #define PG8_STAGE(bufoff, gbase, voff) do { _Pragma("unroll") for (int _i = 0; _i < 2; ++_i) \
;         __builtin_amdgcn_global_load_lds((const unsigned*)((const char*)(gbase) + (voff)[_i]), (PG8_LAS unsigned*)(lds + (bufoff) + ldsw + _i * (8 * USTR)), 16, 0, 0); } while (0)
; #define PG8_LDA(dst, b, h) do { _Pragma("unroll") for (int m = 0; m < 4; ++m) _Pragma("unroll") for (int k = 0; k < 2; ++k) dst[m][k] = *(const PG8_LAS bf16x8*)(lds + PG8_SA(b, h) + aoff + m * (2 * USTR) + k * 64); } while (0)
; #define PG8_LDB(dst, b, h) do { _Pragma("unroll") for (int n = 0; n < 2; ++n) _Pragma("unroll") for (int k = 0; k < 2; ++k) dst[n][k] = *(const PG8_LAS bf16x8*)(lds + PG8_SB(b, h) + boff + n * (2 * USTR) + k * 64); } while (0)
; #define PG8_MMA(ai, bj, At, Bt) do { __builtin_amdgcn_s_setprio(1); _Pragma("unroll") for (int m = 0; m < 4; ++m) _Pragma("unroll") for (int n = 0; n < 2; ++n) _Pragma("unroll") for (int k = 0; k < 2; ++k) \
;         acc[ai][bj][m][n] = __builtin_amdgcn_mfma_f32_16x16x32_bf16(Bt[n][k], At[m][k], acc[ai][bj][m][n], 0, 0, 0); __builtin_amdgcn_s_setprio(0); } while (0)
; #define PG8_WAIT_V(n) asm volatile("s_waitcnt vmcnt(" #n ")" ::: "memory")
; #define PG8_WAIT_L(n) asm volatile("s_waitcnt lgkmcnt(" #n ")" ::: "memory")
; #define PG8_BAR __builtin_amdgcn_s_barrier()
; #define PG8_SCHED __builtin_amdgcn_sched_barrier(0)
; template <class Epi, class Sched, bool ALIGN_EPI, bool SP2>
; __device__ __forceinline__ void gemm_phase(PG8_LAS unsigned char* lds, const Gemm g, const Sched& S, const Epi& E, int wid) {
;     ...
;             PG8_LDB(B0, 1, 0); PG8_LDB(B1, 1, 1); PG8_SCHED; PG8_LDA(At, 1, 0); PG8_STAGE(PG8_SA(0, 1), a2 + hstepA, voffA);
;             PG8_WAIT_V(8); PG8_WAIT_L(0); PG8_BAR; PG8_MMA(0, 0, At, B0); PG8_MMA(0, 1, At, B1); PG8_BAR; PG8_SCHED;
	s_add_i32 s44, 0, 0x19800
	s_add_i32 s45, 0, 0x1dc00
	v_add_u32_e32 v68, s44, v216
	v_add_u32_e32 v156, s45, v216
	ds_read_b128 v[56:59], v68
	ds_read_b128 v[60:63], v68 offset:64
	ds_read_b128 v[64:67], v68 offset:2176
	ds_read_b128 v[68:71], v68 offset:2240
	ds_read_b128 v[144:147], v156
	ds_read_b128 v[148:151], v156 offset:64
	ds_read_b128 v[152:155], v156 offset:2176
	ds_read_b128 v[156:159], v156 offset:2240
	ds_read_b128 v[172:175], v217 offset:34816
	ds_read_b128 v[176:179], v217 offset:34880
	ds_read_b128 v[180:183], v217 offset:36992
	ds_read_b128 v[184:187], v217 offset:37056
	ds_read_b128 v[188:191], v217 offset:39168
	ds_read_b128 v[208:211], v217 offset:39232
	ds_read_b128 v[212:215], v217 offset:41344
	ds_read_b128 v[218:221], v217 offset:41408
	s_add_u32 s74, s74, 0x80000
	s_addc_u32 s75, s75, 0
	s_mov_b32 m0, s29
	v_lshl_add_u64 v[226:227], s[74:75], 0, v[164:165]
	global_load_lds_dwordx4 v[226:227], off
	s_mov_b32 m0, s56
	v_lshl_add_u64 v[226:227], s[74:75], 0, v[162:163]
	global_load_lds_dwordx4 v[226:227], off
	s_waitcnt vmcnt(8)
	s_waitcnt lgkmcnt(0)
	s_barrier
	s_setprio 1
	s_waitcnt lgkmcnt(0)
	v_mfma_f32_16x16x32_bf16 v[140:143], v[56:59], v[172:175], v[140:143]
	v_mfma_f32_16x16x32_bf16 v[136:139], v[64:67], v[172:175], v[136:139]
	v_mfma_f32_16x16x32_bf16 v[124:127], v[56:59], v[180:183], v[124:127]
	v_mfma_f32_16x16x32_bf16 v[120:123], v[64:67], v[180:183], v[120:123]
	v_mfma_f32_16x16x32_bf16 v[108:111], v[56:59], v[188:191], v[108:111]
	v_mfma_f32_16x16x32_bf16 v[104:107], v[64:67], v[188:191], v[104:107]
	v_mfma_f32_16x16x32_bf16 v[92:95], v[56:59], v[212:215], v[92:95]
	v_mfma_f32_16x16x32_bf16 v[88:91], v[64:67], v[212:215], v[88:91]
	v_mfma_f32_16x16x32_bf16 v[140:143], v[60:63], v[176:179], v[140:143]
	v_mfma_f32_16x16x32_bf16 v[136:139], v[68:71], v[176:179], v[136:139]
	v_mfma_f32_16x16x32_bf16 v[124:127], v[60:63], v[184:187], v[124:127]
	v_mfma_f32_16x16x32_bf16 v[120:123], v[68:71], v[184:187], v[120:123]
	v_mfma_f32_16x16x32_bf16 v[108:111], v[60:63], v[208:211], v[108:111]
	v_mfma_f32_16x16x32_bf16 v[104:107], v[68:71], v[208:211], v[104:107]
	v_mfma_f32_16x16x32_bf16 v[92:95], v[60:63], v[218:221], v[92:95]
	v_mfma_f32_16x16x32_bf16 v[88:91], v[68:71], v[218:221], v[88:91]
	s_setprio 0
	s_setprio 1
	v_mfma_f32_16x16x32_bf16 v[132:135], v[144:147], v[172:175], v[132:135]
	v_mfma_f32_16x16x32_bf16 v[128:131], v[152:155], v[172:175], v[128:131]
	v_mfma_f32_16x16x32_bf16 v[116:119], v[144:147], v[180:183], v[116:119]
	v_mfma_f32_16x16x32_bf16 v[112:115], v[152:155], v[180:183], v[112:115]
	v_mfma_f32_16x16x32_bf16 v[100:103], v[144:147], v[188:191], v[100:103]
	v_mfma_f32_16x16x32_bf16 v[96:99], v[152:155], v[188:191], v[96:99]
	v_mfma_f32_16x16x32_bf16 v[84:87], v[144:147], v[212:215], v[84:87]
	v_mfma_f32_16x16x32_bf16 v[80:83], v[152:155], v[212:215], v[80:83]
	v_mfma_f32_16x16x32_bf16 v[132:135], v[148:151], v[176:179], v[132:135]
	v_mfma_f32_16x16x32_bf16 v[128:131], v[156:159], v[176:179], v[128:131]
	v_mfma_f32_16x16x32_bf16 v[116:119], v[148:151], v[184:187], v[116:119]
	v_mfma_f32_16x16x32_bf16 v[112:115], v[156:159], v[184:187], v[112:115]
	v_mfma_f32_16x16x32_bf16 v[100:103], v[148:151], v[208:211], v[100:103]
	v_mfma_f32_16x16x32_bf16 v[96:99], v[156:159], v[208:211], v[96:99]
	v_mfma_f32_16x16x32_bf16 v[84:87], v[148:151], v[218:221], v[84:87]
	v_mfma_f32_16x16x32_bf16 v[80:83], v[156:159], v[218:221], v[80:83]
	s_setprio 0
	s_barrier
; #define PG8_STAGE(bufoff, gbase, voff) do { _Pragma("unroll") for (int _i = 0; _i < 2; ++_i) \
;         __builtin_amdgcn_global_load_lds((const unsigned*)((const char*)(gbase) + (voff)[_i]), (PG8_LAS unsigned*)(lds + (bufoff) + ldsw + _i * (8 * USTR)), 16, 0, 0); } while (0)
; #define PG8_LDA(dst, b, h) do { _Pragma("unroll") for (int m = 0; m < 4; ++m) _Pragma("unroll") for (int k = 0; k < 2; ++k) dst[m][k] = *(const PG8_LAS bf16x8*)(lds + PG8_SA(b, h) + aoff + m * (2 * USTR) + k * 64); } while (0)
; #define PG8_MMA(ai, bj, At, Bt) do { __builtin_amdgcn_s_setprio(1); _Pragma("unroll") for (int m = 0; m < 4; ++m) _Pragma("unroll") for (int n = 0; n < 2; ++n) _Pragma("unroll") for (int k = 0; k < 2; ++k) \
;         acc[ai][bj][m][n] = __builtin_amdgcn_mfma_f32_16x16x32_bf16(Bt[n][k], At[m][k], acc[ai][bj][m][n], 0, 0, 0); __builtin_amdgcn_s_setprio(0); } while (0)
; #define PG8_WAIT_V(n) asm volatile("s_waitcnt vmcnt(" #n ")" ::: "memory")
; #define PG8_WAIT_L(n) asm volatile("s_waitcnt lgkmcnt(" #n ")" ::: "memory")
; #define PG8_BAR __builtin_amdgcn_s_barrier()
; #define PG8_SCHED __builtin_amdgcn_sched_barrier(0)
; template <class Epi, class Sched, bool ALIGN_EPI, bool SP2>
; __device__ __forceinline__ void gemm_phase(PG8_LAS unsigned char* lds, const Gemm g, const Sched& S, const Epi& E, int wid) {
;     ...
;             PG8_LDA(At, 1, 1); PG8_STAGE(PG8_SB(1, 0), b3, voffB); PG8_STAGE(PG8_SB(1, 1), b3 + hstepB, voffB); PG8_STAGE(PG8_SA(1, 0), a3, voffA);
;             PG8_WAIT_V(8); PG8_WAIT_L(0); PG8_BAR; PG8_MMA(1, 0, At, B0); PG8_MMA(1, 1, At, B1); PG8_BAR; PG8_SCHED;
	ds_read_b128 v[172:175], v217 offset:52224
	ds_read_b128 v[176:179], v217 offset:52288
	ds_read_b128 v[180:183], v217 offset:54400
	ds_read_b128 v[184:187], v217 offset:54464
	ds_read_b128 v[188:191], v217 offset:56576
	ds_read_b128 v[208:211], v217 offset:56640
	ds_read_b128 v[212:215], v217 offset:58752
	ds_read_b128 v[218:221], v217 offset:58816
	s_add_i32 s44, s44, s33
	s_mov_b32 m0, s44
	v_lshl_add_u64 v[198:199], v[198:199], 0, s[6:7]
	global_load_lds_dwordx4 v[198:199], off
	s_add_i32 m0, s44, 0x2200
	s_add_u32 s40, s40, 0x40080
	v_lshl_add_u64 v[198:199], v[200:201], 0, s[6:7]
	s_addc_u32 s41, s41, 0
	s_add_i32 s44, s45, s33
	global_load_lds_dwordx4 v[198:199], off
	s_mov_b32 m0, s44
	v_lshl_add_u64 v[198:199], s[40:41], 0, v[192:193]
	global_load_lds_dwordx4 v[198:199], off
	s_add_i32 m0, s44, 0x2200
	v_lshl_add_u64 v[198:199], s[40:41], 0, v[160:161]
	global_load_lds_dwordx4 v[198:199], off
	s_mov_b32 m0, s57
	v_lshl_add_u64 v[198:199], v[222:223], 0, s[6:7]
	global_load_lds_dwordx4 v[198:199], off
	s_mov_b32 m0, s76
	v_lshl_add_u64 v[198:199], v[224:225], 0, s[6:7]
	global_load_lds_dwordx4 v[198:199], off
	s_add_i32 s89, s89, 2
	s_add_u32 s38, s38, 0x100
	s_addc_u32 s39, s39, 0
	s_add_u32 s78, s78, 0x100
	s_addc_u32 s79, s79, 0
	s_waitcnt vmcnt(8)
	s_waitcnt lgkmcnt(0)
	s_barrier
	s_setprio 1
	s_waitcnt lgkmcnt(0)
	v_mfma_f32_16x16x32_bf16 v[76:79], v[56:59], v[172:175], v[76:79]
	v_mfma_f32_16x16x32_bf16 v[72:75], v[64:67], v[172:175], v[72:75]
	v_mfma_f32_16x16x32_bf16 v[44:47], v[56:59], v[180:183], v[44:47]
	v_mfma_f32_16x16x32_bf16 v[40:43], v[64:67], v[180:183], v[40:43]
	v_mfma_f32_16x16x32_bf16 v[24:27], v[56:59], v[188:191], v[24:27]
	v_mfma_f32_16x16x32_bf16 v[28:31], v[64:67], v[188:191], v[28:31]
	v_mfma_f32_16x16x32_bf16 v[4:7], v[56:59], v[212:215], v[4:7]
	v_mfma_f32_16x16x32_bf16 v[12:15], v[64:67], v[212:215], v[12:15]
	v_mfma_f32_16x16x32_bf16 v[76:79], v[60:63], v[176:179], v[76:79]
	v_mfma_f32_16x16x32_bf16 v[72:75], v[68:71], v[176:179], v[72:75]
	v_mfma_f32_16x16x32_bf16 v[44:47], v[60:63], v[184:187], v[44:47]
	v_mfma_f32_16x16x32_bf16 v[40:43], v[68:71], v[184:187], v[40:43]
	v_mfma_f32_16x16x32_bf16 v[24:27], v[60:63], v[208:211], v[24:27]
	v_mfma_f32_16x16x32_bf16 v[28:31], v[68:71], v[208:211], v[28:31]
	v_mfma_f32_16x16x32_bf16 v[4:7], v[60:63], v[218:221], v[4:7]
	v_mfma_f32_16x16x32_bf16 v[12:15], v[68:71], v[218:221], v[12:15]
	s_setprio 0
	s_setprio 1
	v_mfma_f32_16x16x32_bf16 v[48:51], v[144:147], v[172:175], v[48:51]
	v_mfma_f32_16x16x32_bf16 v[68:71], v[148:151], v[176:179], v[48:51]
	v_mfma_f32_16x16x32_bf16 v[48:51], v[152:155], v[172:175], v[52:55]
	v_mfma_f32_16x16x32_bf16 v[36:39], v[144:147], v[180:183], v[36:39]
	v_mfma_f32_16x16x32_bf16 v[32:35], v[152:155], v[180:183], v[32:35]
	v_mfma_f32_16x16x32_bf16 v[20:23], v[144:147], v[188:191], v[20:23]
	v_mfma_f32_16x16x32_bf16 v[16:19], v[152:155], v[188:191], v[16:19]
	v_mfma_f32_16x16x32_bf16 v[8:11], v[144:147], v[212:215], v[8:11]
	v_mfma_f32_16x16x32_bf16 v[0:3], v[152:155], v[212:215], v[0:3]
	v_mfma_f32_16x16x32_bf16 v[64:67], v[156:159], v[176:179], v[48:51]
	v_mfma_f32_16x16x32_bf16 v[36:39], v[148:151], v[184:187], v[36:39]
	v_mfma_f32_16x16x32_bf16 v[32:35], v[156:159], v[184:187], v[32:35]
	v_mfma_f32_16x16x32_bf16 v[20:23], v[148:151], v[208:211], v[20:23]
	v_mfma_f32_16x16x32_bf16 v[16:19], v[156:159], v[208:211], v[16:19]
	v_mfma_f32_16x16x32_bf16 v[8:11], v[148:151], v[218:221], v[8:11]
	v_mfma_f32_16x16x32_bf16 v[0:3], v[156:159], v[218:221], v[0:3]
	s_setprio 0
	s_barrier
	s_cmp_gt_u32 s89, 13
	s_cbranch_scc0 .LBB0_150
	s_and_b64 vcc, exec, s[20:21]
	s_cbranch_vccz .LBB0_153
	s_barrier

; #define PG8_STAGE(bufoff, gbase, voff) do { _Pragma("unroll") for (int _i = 0; _i < 2; ++_i) \
;         __builtin_amdgcn_global_load_lds((const unsigned*)((const char*)(gbase) + (voff)[_i]), (PG8_LAS unsigned*)(lds + (bufoff) + ldsw + _i * (8 * USTR)), 16, 0, 0); } while (0)
; #define PG8_LDA(dst, b, h) do { _Pragma("unroll") for (int m = 0; m < 4; ++m) _Pragma("unroll") for (int k = 0; k < 2; ++k) dst[m][k] = *(const PG8_LAS bf16x8*)(lds + PG8_SA(b, h) + aoff + m * (2 * USTR) + k * 64); } while (0)
; #define PG8_LDB(dst, b, h) do { _Pragma("unroll") for (int n = 0; n < 2; ++n) _Pragma("unroll") for (int k = 0; k < 2; ++k) dst[n][k] = *(const PG8_LAS bf16x8*)(lds + PG8_SB(b, h) + boff + n * (2 * USTR) + k * 64); } while (0)
; #define PG8_MMA(ai, bj, At, Bt) do { __builtin_amdgcn_s_setprio(1); _Pragma("unroll") for (int m = 0; m < 4; ++m) _Pragma("unroll") for (int n = 0; n < 2; ++n) _Pragma("unroll") for (int k = 0; k < 2; ++k) \
;         acc[ai][bj][m][n] = __builtin_amdgcn_mfma_f32_16x16x32_bf16(Bt[n][k], At[m][k], acc[ai][bj][m][n], 0, 0, 0); __builtin_amdgcn_s_setprio(0); } while (0)
; #define PG8_WAIT_V(n) asm volatile("s_waitcnt vmcnt(" #n ")" ::: "memory")
; #define PG8_WAIT_L(n) asm volatile("s_waitcnt lgkmcnt(" #n ")" ::: "memory")
; #define PG8_BAR __builtin_amdgcn_s_barrier()
; #define PG8_SCHED __builtin_amdgcn_sched_barrier(0)
; template <class Epi, class Sched, bool ALIGN_EPI, bool SP2>
; __device__ __forceinline__ void gemm_phase(PG8_LAS unsigned char* lds, const Gemm g, const Sched& S, const Epi& E, int wid) {
;     ...
;             PG8_LDB(B0, 0, 0); PG8_LDB(B1, 0, 1); PG8_SCHED; PG8_LDA(At, 0, 0); PG8_STAGE(PG8_SA(1, 1), a1 + hstepA, voffA);
;             PG8_WAIT_V(8); PG8_WAIT_L(0); PG8_BAR; PG8_MMA(0, 0, At, B0); PG8_MMA(0, 1, At, B1); PG8_BAR; PG8_SCHED;
;             PG8_LDA(At, 0, 1); PG8_STAGE(PG8_SB(0, 0), b2, voffB); PG8_STAGE(PG8_SB(0, 1), b2 + hstepB, voffB); PG8_STAGE(PG8_SA(0, 0), a2, voffA);
;             PG8_WAIT_V(8); PG8_WAIT_L(0); PG8_BAR; PG8_MMA(1, 0, At, B0); PG8_MMA(1, 1, At, B1); PG8_BAR; PG8_SCHED;
.Lhb_down:
	s_add_i32 s69, 0, 0x11000
	s_add_i32 s76, 0, 0x15400
	v_add_u32_e32 v52, s69, v197
	v_add_u32_e32 v156, s76, v197
	ds_read_b128 v[40:43], v52
	ds_read_b128 v[44:47], v52 offset:64
	ds_read_b128 v[48:51], v52 offset:2176
	ds_read_b128 v[52:55], v52 offset:2240
	ds_read_b128 v[144:147], v156
	ds_read_b128 v[148:151], v156 offset:64
	ds_read_b128 v[152:155], v156 offset:2176
	ds_read_b128 v[156:159], v156 offset:2240
	ds_read_b128 v[160:163], v241
	ds_read_b128 v[164:167], v241 offset:64
	ds_read_b128 v[168:171], v241 offset:2176
	ds_read_b128 v[172:175], v241 offset:2240
	ds_read_b128 v[176:179], v241 offset:4352
	ds_read_b128 v[180:183], v241 offset:4416
	ds_read_b128 v[184:187], v241 offset:6528
	ds_read_b128 v[188:191], v241 offset:6592
	s_add_i32 m0, s0, 0xcc00
	v_lshl_add_u64 v[198:199], s[38:39], 0, v[212:213]
	global_load_lds_dwordx4 v[198:199], off
	s_add_i32 m0, s0, 0xee00
	v_lshl_add_u64 v[198:199], s[38:39], 0, v[214:215]
	global_load_lds_dwordx4 v[198:199], off
	s_add_u32 s40, s38, 0xfff50080
	s_addc_u32 s41, s39, -1
	s_cmp_eq_u32 s68, 40
	s_cselect_b32 s43, s23, s41
	s_cselect_b32 s42, s22, s40
	s_cselect_b32 s41, s45, s27
	s_cselect_b32 s40, s44, s26
	s_waitcnt vmcnt(8)
	s_waitcnt lgkmcnt(0)
	s_barrier
	s_setprio 1
	s_waitcnt lgkmcnt(0)
	v_mfma_f32_16x16x32_bf16 v[132:135], v[40:43], v[160:163], 0
	v_mfma_f32_16x16x32_bf16 v[128:131], v[48:51], v[160:163], 0
	v_mfma_f32_16x16x32_bf16 v[124:127], v[40:43], v[168:171], 0
	v_mfma_f32_16x16x32_bf16 v[120:123], v[48:51], v[168:171], 0
	v_mfma_f32_16x16x32_bf16 v[108:111], v[40:43], v[176:179], 0
	v_mfma_f32_16x16x32_bf16 v[104:107], v[48:51], v[176:179], 0
	v_mfma_f32_16x16x32_bf16 v[92:95], v[40:43], v[184:187], 0
	v_mfma_f32_16x16x32_bf16 v[88:91], v[48:51], v[184:187], 0
	v_mfma_f32_16x16x32_bf16 v[132:135], v[44:47], v[164:167], v[132:135]
	v_mfma_f32_16x16x32_bf16 v[128:131], v[52:55], v[164:167], v[128:131]
	v_mfma_f32_16x16x32_bf16 v[124:127], v[44:47], v[172:175], v[124:127]
	v_mfma_f32_16x16x32_bf16 v[120:123], v[52:55], v[172:175], v[120:123]
	v_mfma_f32_16x16x32_bf16 v[108:111], v[44:47], v[180:183], v[108:111]
	v_mfma_f32_16x16x32_bf16 v[104:107], v[52:55], v[180:183], v[104:107]
	v_mfma_f32_16x16x32_bf16 v[92:95], v[44:47], v[188:191], v[92:95]
	v_mfma_f32_16x16x32_bf16 v[88:91], v[52:55], v[188:191], v[88:91]
	s_setprio 0
	s_setprio 1
	v_mfma_f32_16x16x32_bf16 v[140:143], v[144:147], v[160:163], 0
	v_mfma_f32_16x16x32_bf16 v[136:139], v[152:155], v[160:163], 0
	v_mfma_f32_16x16x32_bf16 v[116:119], v[144:147], v[168:171], 0
	v_mfma_f32_16x16x32_bf16 v[112:115], v[152:155], v[168:171], 0
	v_mfma_f32_16x16x32_bf16 v[100:103], v[144:147], v[176:179], 0
	v_mfma_f32_16x16x32_bf16 v[96:99], v[152:155], v[176:179], 0
	v_mfma_f32_16x16x32_bf16 v[84:87], v[144:147], v[184:187], 0
	v_mfma_f32_16x16x32_bf16 v[80:83], v[152:155], v[184:187], 0
	v_mfma_f32_16x16x32_bf16 v[140:143], v[148:151], v[164:167], v[140:143]
	v_mfma_f32_16x16x32_bf16 v[136:139], v[156:159], v[164:167], v[136:139]
	v_mfma_f32_16x16x32_bf16 v[116:119], v[148:151], v[172:175], v[116:119]
	v_mfma_f32_16x16x32_bf16 v[112:115], v[156:159], v[172:175], v[112:115]
	v_mfma_f32_16x16x32_bf16 v[100:103], v[148:151], v[180:183], v[100:103]
	v_mfma_f32_16x16x32_bf16 v[96:99], v[156:159], v[180:183], v[96:99]
	v_mfma_f32_16x16x32_bf16 v[84:87], v[148:151], v[188:191], v[84:87]
	v_mfma_f32_16x16x32_bf16 v[80:83], v[156:159], v[188:191], v[80:83]
	s_setprio 0
	s_barrier
	ds_read_b128 v[160:163], v241 offset:17408
	ds_read_b128 v[164:167], v241 offset:17472
	ds_read_b128 v[168:171], v241 offset:19584
	ds_read_b128 v[172:175], v241 offset:19648
	ds_read_b128 v[176:179], v241 offset:21760
	ds_read_b128 v[180:183], v241 offset:21824
	ds_read_b128 v[184:187], v241 offset:23936
	ds_read_b128 v[188:191], v241 offset:24000
	s_add_i32 s69, s69, s33
	s_mov_b32 m0, s69
	v_lshl_add_u64 v[198:199], s[40:41], 0, v[208:209]
	global_load_lds_dwordx4 v[198:199], off
	s_add_i32 m0, s69, 0x2200
	s_add_u32 s74, s40, 0xb0000
	v_lshl_add_u64 v[200:201], s[40:41], 0, v[210:211]
	s_addc_u32 s75, s41, 0
	s_add_i32 s69, s76, s33
	global_load_lds_dwordx4 v[200:201], off
	v_lshl_add_u64 v[216:217], s[74:75], 0, v[208:209]
	s_mov_b32 m0, s69
	v_lshl_add_u64 v[218:219], s[42:43], 0, v[210:211]
	global_load_lds_dwordx4 v[216:217], off
	s_add_i32 m0, s69, 0x2200
	v_lshl_add_u64 v[216:217], s[74:75], 0, v[210:211]
	global_load_lds_dwordx4 v[216:217], off
	s_mov_b32 m0, s0
	v_lshl_add_u64 v[216:217], s[42:43], 0, v[208:209]
	global_load_lds_dwordx4 v[216:217], off
	s_mov_b32 m0, s5
	s_nop 0
	global_load_lds_dwordx4 v[218:219], off
	s_waitcnt vmcnt(8)
	s_waitcnt lgkmcnt(0)
	s_barrier
; #define PG8_STAGE(bufoff, gbase, voff) do { _Pragma("unroll") for (int _i = 0; _i < 2; ++_i) \
;         __builtin_amdgcn_global_load_lds((const unsigned*)((const char*)(gbase) + (voff)[_i]), (PG8_LAS unsigned*)(lds + (bufoff) + ldsw + _i * (8 * USTR)), 16, 0, 0); } while (0)
; #define PG8_LDA(dst, b, h) do { _Pragma("unroll") for (int m = 0; m < 4; ++m) _Pragma("unroll") for (int k = 0; k < 2; ++k) dst[m][k] = *(const PG8_LAS bf16x8*)(lds + PG8_SA(b, h) + aoff + m * (2 * USTR) + k * 64); } while (0)
; #define PG8_LDB(dst, b, h) do { _Pragma("unroll") for (int n = 0; n < 2; ++n) _Pragma("unroll") for (int k = 0; k < 2; ++k) dst[n][k] = *(const PG8_LAS bf16x8*)(lds + PG8_SB(b, h) + boff + n * (2 * USTR) + k * 64); } while (0)
; #define PG8_MMA(ai, bj, At, Bt) do { __builtin_amdgcn_s_setprio(1); _Pragma("unroll") for (int m = 0; m < 4; ++m) _Pragma("unroll") for (int n = 0; n < 2; ++n) _Pragma("unroll") for (int k = 0; k < 2; ++k) \
;         acc[ai][bj][m][n] = __builtin_amdgcn_mfma_f32_16x16x32_bf16(Bt[n][k], At[m][k], acc[ai][bj][m][n], 0, 0, 0); __builtin_amdgcn_s_setprio(0); } while (0)
; #define PG8_WAIT_V(n) asm volatile("s_waitcnt vmcnt(" #n ")" ::: "memory")
; #define PG8_WAIT_L(n) asm volatile("s_waitcnt lgkmcnt(" #n ")" ::: "memory")
; #define PG8_BAR __builtin_amdgcn_s_barrier()
; #define PG8_SCHED __builtin_amdgcn_sched_barrier(0)
; template <class Epi, class Sched, bool ALIGN_EPI, bool SP2>
; __device__ __forceinline__ void gemm_phase(PG8_LAS unsigned char* lds, const Gemm g, const Sched& S, const Epi& E, int wid) {
;     ...
;             PG8_WAIT_V(8); PG8_WAIT_L(0); PG8_BAR; PG8_MMA(1, 0, At, B0); PG8_MMA(1, 1, At, B1); PG8_BAR; PG8_SCHED;
;             PG8_LDB(B0, 1, 0); PG8_LDB(B1, 1, 1); PG8_SCHED; PG8_LDA(At, 1, 0); PG8_STAGE(PG8_SA(0, 1), a2 + hstepA, voffA);
;             PG8_WAIT_V(8); PG8_WAIT_L(0); PG8_BAR; PG8_MMA(0, 0, At, B0); PG8_MMA(0, 1, At, B1); PG8_BAR; PG8_SCHED;
	s_setprio 1
	s_waitcnt lgkmcnt(0)
	v_mfma_f32_16x16x32_bf16 v[76:79], v[40:43], v[160:163], 0
	v_mfma_f32_16x16x32_bf16 v[72:75], v[48:51], v[160:163], 0
	v_mfma_f32_16x16x32_bf16 v[60:63], v[40:43], v[168:171], 0
	v_mfma_f32_16x16x32_bf16 v[56:59], v[48:51], v[168:171], 0
	v_mfma_f32_16x16x32_bf16 v[24:27], v[40:43], v[176:179], 0
	v_mfma_f32_16x16x32_bf16 v[28:31], v[48:51], v[176:179], 0
	v_mfma_f32_16x16x32_bf16 v[8:11], v[40:43], v[184:187], 0
	v_mfma_f32_16x16x32_bf16 v[12:15], v[48:51], v[184:187], 0
	v_mfma_f32_16x16x32_bf16 v[76:79], v[44:47], v[164:167], v[76:79]
	v_mfma_f32_16x16x32_bf16 v[72:75], v[52:55], v[164:167], v[72:75]
	v_mfma_f32_16x16x32_bf16 v[60:63], v[44:47], v[172:175], v[60:63]
	v_mfma_f32_16x16x32_bf16 v[56:59], v[52:55], v[172:175], v[56:59]
	v_mfma_f32_16x16x32_bf16 v[24:27], v[44:47], v[180:183], v[24:27]
	v_mfma_f32_16x16x32_bf16 v[28:31], v[52:55], v[180:183], v[28:31]
	v_mfma_f32_16x16x32_bf16 v[8:11], v[44:47], v[188:191], v[8:11]
	v_mfma_f32_16x16x32_bf16 v[12:15], v[52:55], v[188:191], v[12:15]
	s_setprio 0
	s_setprio 1
	v_mfma_f32_16x16x32_bf16 v[36:39], v[144:147], v[168:171], 0
	v_mfma_f32_16x16x32_bf16 v[32:35], v[152:155], v[168:171], 0
	v_mfma_f32_16x16x32_bf16 v[20:23], v[144:147], v[176:179], 0
	v_mfma_f32_16x16x32_bf16 v[16:19], v[152:155], v[176:179], 0
	v_mfma_f32_16x16x32_bf16 v[4:7], v[144:147], v[184:187], 0
	v_mfma_f32_16x16x32_bf16 v[0:3], v[152:155], v[184:187], 0
	v_mfma_f32_16x16x32_bf16 v[40:43], v[144:147], v[160:163], 0
	v_mfma_f32_16x16x32_bf16 v[44:47], v[152:155], v[160:163], 0
	v_mfma_f32_16x16x32_bf16 v[36:39], v[148:151], v[172:175], v[36:39]
	v_mfma_f32_16x16x32_bf16 v[32:35], v[156:159], v[172:175], v[32:35]
	v_mfma_f32_16x16x32_bf16 v[20:23], v[148:151], v[180:183], v[20:23]
	v_mfma_f32_16x16x32_bf16 v[16:19], v[156:159], v[180:183], v[16:19]
	v_mfma_f32_16x16x32_bf16 v[4:7], v[148:151], v[188:191], v[4:7]
	v_mfma_f32_16x16x32_bf16 v[0:3], v[156:159], v[188:191], v[0:3]
	v_mfma_f32_16x16x32_bf16 v[40:43], v[148:151], v[164:167], v[40:43]
	v_mfma_f32_16x16x32_bf16 v[44:47], v[156:159], v[164:167], v[44:47]
	s_setprio 0
	s_barrier
	s_add_i32 s69, 0, 0x19800
	s_add_i32 s74, 0, 0x1dc00
	v_add_u32_e32 v68, s69, v197
	v_add_u32_e32 v156, s74, v197
	ds_read_b128 v[48:51], v68
	ds_read_b128 v[52:55], v68 offset:64
	ds_read_b128 v[64:67], v68 offset:2176
	ds_read_b128 v[68:71], v68 offset:2240
	ds_read_b128 v[144:147], v156
	ds_read_b128 v[148:151], v156 offset:64
	ds_read_b128 v[152:155], v156 offset:2176
	ds_read_b128 v[156:159], v156 offset:2240
	ds_read_b128 v[160:163], v241 offset:34816
	ds_read_b128 v[164:167], v241 offset:34880
	ds_read_b128 v[168:171], v241 offset:36992
	ds_read_b128 v[172:175], v241 offset:37056
	ds_read_b128 v[176:179], v241 offset:39168
	ds_read_b128 v[180:183], v241 offset:39232
	ds_read_b128 v[184:187], v241 offset:41344
	ds_read_b128 v[188:191], v241 offset:41408
	s_add_u32 s42, s42, 0xb0000
	s_addc_u32 s43, s43, 0
	s_mov_b32 m0, s29
	v_lshl_add_u64 v[220:221], s[42:43], 0, v[208:209]
	global_load_lds_dwordx4 v[220:221], off
	s_mov_b32 m0, s56
	v_lshl_add_u64 v[220:221], s[42:43], 0, v[210:211]
	global_load_lds_dwordx4 v[220:221], off
	s_waitcnt vmcnt(8)
	s_waitcnt lgkmcnt(0)
	s_barrier
	s_setprio 1
	s_waitcnt lgkmcnt(0)
	v_mfma_f32_16x16x32_bf16 v[132:135], v[48:51], v[160:163], v[132:135]
	v_mfma_f32_16x16x32_bf16 v[128:131], v[64:67], v[160:163], v[128:131]
	v_mfma_f32_16x16x32_bf16 v[124:127], v[48:51], v[168:171], v[124:127]
	v_mfma_f32_16x16x32_bf16 v[120:123], v[64:67], v[168:171], v[120:123]
	v_mfma_f32_16x16x32_bf16 v[108:111], v[48:51], v[176:179], v[108:111]
	v_mfma_f32_16x16x32_bf16 v[104:107], v[64:67], v[176:179], v[104:107]
	v_mfma_f32_16x16x32_bf16 v[92:95], v[48:51], v[184:187], v[92:95]
	v_mfma_f32_16x16x32_bf16 v[88:91], v[64:67], v[184:187], v[88:91]
	v_mfma_f32_16x16x32_bf16 v[132:135], v[52:55], v[164:167], v[132:135]
	v_mfma_f32_16x16x32_bf16 v[128:131], v[68:71], v[164:167], v[128:131]
	v_mfma_f32_16x16x32_bf16 v[124:127], v[52:55], v[172:175], v[124:127]
	v_mfma_f32_16x16x32_bf16 v[120:123], v[68:71], v[172:175], v[120:123]
	v_mfma_f32_16x16x32_bf16 v[108:111], v[52:55], v[180:183], v[108:111]
	v_mfma_f32_16x16x32_bf16 v[104:107], v[68:71], v[180:183], v[104:107]
	v_mfma_f32_16x16x32_bf16 v[92:95], v[52:55], v[188:191], v[92:95]
	v_mfma_f32_16x16x32_bf16 v[88:91], v[68:71], v[188:191], v[88:91]
	s_setprio 0
	s_setprio 1
	v_mfma_f32_16x16x32_bf16 v[140:143], v[144:147], v[160:163], v[140:143]
	v_mfma_f32_16x16x32_bf16 v[136:139], v[152:155], v[160:163], v[136:139]
	v_mfma_f32_16x16x32_bf16 v[116:119], v[144:147], v[168:171], v[116:119]
	v_mfma_f32_16x16x32_bf16 v[112:115], v[152:155], v[168:171], v[112:115]
	v_mfma_f32_16x16x32_bf16 v[100:103], v[144:147], v[176:179], v[100:103]
	v_mfma_f32_16x16x32_bf16 v[96:99], v[152:155], v[176:179], v[96:99]
	v_mfma_f32_16x16x32_bf16 v[84:87], v[144:147], v[184:187], v[84:87]
	v_mfma_f32_16x16x32_bf16 v[80:83], v[152:155], v[184:187], v[80:83]
	v_mfma_f32_16x16x32_bf16 v[140:143], v[148:151], v[164:167], v[140:143]
	v_mfma_f32_16x16x32_bf16 v[136:139], v[156:159], v[164:167], v[136:139]
	v_mfma_f32_16x16x32_bf16 v[116:119], v[148:151], v[172:175], v[116:119]
	v_mfma_f32_16x16x32_bf16 v[112:115], v[156:159], v[172:175], v[112:115]
	v_mfma_f32_16x16x32_bf16 v[100:103], v[148:151], v[180:183], v[100:103]
	v_mfma_f32_16x16x32_bf16 v[96:99], v[156:159], v[180:183], v[96:99]
	v_mfma_f32_16x16x32_bf16 v[84:87], v[148:151], v[188:191], v[84:87]
	v_mfma_f32_16x16x32_bf16 v[80:83], v[156:159], v[188:191], v[80:83]
	s_setprio 0
	s_barrier
; #define PG8_STAGE(bufoff, gbase, voff) do { _Pragma("unroll") for (int _i = 0; _i < 2; ++_i) \
;         __builtin_amdgcn_global_load_lds((const unsigned*)((const char*)(gbase) + (voff)[_i]), (PG8_LAS unsigned*)(lds + (bufoff) + ldsw + _i * (8 * USTR)), 16, 0, 0); } while (0)
; #define PG8_LDA(dst, b, h) do { _Pragma("unroll") for (int m = 0; m < 4; ++m) _Pragma("unroll") for (int k = 0; k < 2; ++k) dst[m][k] = *(const PG8_LAS bf16x8*)(lds + PG8_SA(b, h) + aoff + m * (2 * USTR) + k * 64); } while (0)
; #define PG8_LDB(dst, b, h) do { _Pragma("unroll") for (int n = 0; n < 2; ++n) _Pragma("unroll") for (int k = 0; k < 2; ++k) dst[n][k] = *(const PG8_LAS bf16x8*)(lds + PG8_SB(b, h) + boff + n * (2 * USTR) + k * 64); } while (0)
; #define PG8_MMA(ai, bj, At, Bt) do { __builtin_amdgcn_s_setprio(1); _Pragma("unroll") for (int m = 0; m < 4; ++m) _Pragma("unroll") for (int n = 0; n < 2; ++n) _Pragma("unroll") for (int k = 0; k < 2; ++k) \
;         acc[ai][bj][m][n] = __builtin_amdgcn_mfma_f32_16x16x32_bf16(Bt[n][k], At[m][k], acc[ai][bj][m][n], 0, 0, 0); __builtin_amdgcn_s_setprio(0); } while (0)
; #define PG8_BAR __builtin_amdgcn_s_barrier()
; template <class Epi, class Sched, bool ALIGN_EPI, bool SP2>
; __device__ __forceinline__ void gemm_phase(PG8_LAS unsigned char* lds, const Gemm g, const Sched& S, const Epi& E, int wid) {
;     ...
;             PG8_LDB(B0, 0, 0); PG8_LDB(B1, 0, 1); PG8_SCHED; PG8_LDA(At, 0, 0); PG8_STAGE(PG8_SA(1, 1), a1 + hstepA, voffA);
;             PG8_WAIT_V(8); PG8_WAIT_L(0); PG8_BAR; PG8_MMA(0, 0, At, B0); PG8_MMA(0, 1, At, B1); PG8_BAR; PG8_SCHED;
;             PG8_LDA(At, 0, 1); PG8_STAGE(PG8_SB(0, 0), b2, voffB); PG8_STAGE(PG8_SB(0, 1), b2 + hstepB, voffB); PG8_STAGE(PG8_SA(0, 0), a2, voffA);
;             PG8_WAIT_V(8); PG8_WAIT_L(0); PG8_BAR; PG8_MMA(1, 0, At, B0); PG8_MMA(1, 1, At, B1); PG8_BAR; PG8_SCHED;
;             PG8_LDB(B0, 1, 0); PG8_LDB(B1, 1, 1); PG8_SCHED; PG8_LDA(At, 1, 0); PG8_STAGE(PG8_SA(0, 1), a2 + hstepA, voffA);
;             PG8_WAIT_V(8); PG8_WAIT_L(0); PG8_BAR; PG8_MMA(0, 0, At, B0); PG8_MMA(0, 1, At, B1); PG8_BAR; PG8_SCHED;
;             PG8_LDA(At, 1, 1); PG8_STAGE(PG8_SB(1, 0), b3, voffB); PG8_STAGE(PG8_SB(1, 1), b3 + hstepB, voffB); PG8_STAGE(PG8_SA(1, 0), a3, voffA);
;             PG8_WAIT_V(8); PG8_WAIT_L(0); PG8_BAR; PG8_MMA(1, 0, At, B0); PG8_MMA(1, 1, At, B1); PG8_BAR; PG8_SCHED;
	ds_read_b128 v[160:163], v241 offset:52224
	ds_read_b128 v[164:167], v241 offset:52288
	ds_read_b128 v[168:171], v241 offset:54400
	ds_read_b128 v[172:175], v241 offset:54464
	ds_read_b128 v[176:179], v241 offset:56576
	ds_read_b128 v[180:183], v241 offset:56640
	ds_read_b128 v[184:187], v241 offset:58752
	ds_read_b128 v[188:191], v241 offset:58816
	s_add_i32 s42, s69, s33
	s_mov_b32 m0, s42
	v_lshl_add_u64 v[198:199], v[198:199], 0, s[6:7]
	global_load_lds_dwordx4 v[198:199], off
	s_add_i32 m0, s42, 0x2200
	s_add_u32 s40, s40, 0xb0080
	v_lshl_add_u64 v[198:199], v[200:201], 0, s[6:7]
	s_addc_u32 s41, s41, 0
	s_add_i32 s42, s74, s33
	global_load_lds_dwordx4 v[198:199], off
	s_mov_b32 m0, s42
	v_lshl_add_u64 v[198:199], s[40:41], 0, v[208:209]
	global_load_lds_dwordx4 v[198:199], off
	s_add_i32 m0, s42, 0x2200
	v_lshl_add_u64 v[198:199], s[40:41], 0, v[210:211]
	global_load_lds_dwordx4 v[198:199], off
	s_mov_b32 m0, s57
	v_lshl_add_u64 v[198:199], v[216:217], 0, s[6:7]
	global_load_lds_dwordx4 v[198:199], off
	s_mov_b32 m0, s70
	v_lshl_add_u64 v[198:199], v[218:219], 0, s[6:7]
	global_load_lds_dwordx4 v[198:199], off
	s_add_i32 s68, s68, 2
	s_add_u32 s38, s38, 0x100
	s_addc_u32 s39, s39, 0
	s_add_u32 s26, s26, 0x100
	s_addc_u32 s27, s27, 0
	s_waitcnt vmcnt(8)
	s_waitcnt lgkmcnt(0)
	s_barrier
	s_setprio 1
	s_waitcnt lgkmcnt(0)
	v_mfma_f32_16x16x32_bf16 v[76:79], v[48:51], v[160:163], v[76:79]
	v_mfma_f32_16x16x32_bf16 v[72:75], v[64:67], v[160:163], v[72:75]
	v_mfma_f32_16x16x32_bf16 v[60:63], v[48:51], v[168:171], v[60:63]
	v_mfma_f32_16x16x32_bf16 v[56:59], v[64:67], v[168:171], v[56:59]
	v_mfma_f32_16x16x32_bf16 v[24:27], v[48:51], v[176:179], v[24:27]
	v_mfma_f32_16x16x32_bf16 v[28:31], v[64:67], v[176:179], v[28:31]
	v_mfma_f32_16x16x32_bf16 v[8:11], v[48:51], v[184:187], v[8:11]
	v_mfma_f32_16x16x32_bf16 v[12:15], v[64:67], v[184:187], v[12:15]
	v_mfma_f32_16x16x32_bf16 v[76:79], v[52:55], v[164:167], v[76:79]
	v_mfma_f32_16x16x32_bf16 v[72:75], v[68:71], v[164:167], v[72:75]
	v_mfma_f32_16x16x32_bf16 v[60:63], v[52:55], v[172:175], v[60:63]
	v_mfma_f32_16x16x32_bf16 v[56:59], v[68:71], v[172:175], v[56:59]
	v_mfma_f32_16x16x32_bf16 v[24:27], v[52:55], v[180:183], v[24:27]
	v_mfma_f32_16x16x32_bf16 v[28:31], v[68:71], v[180:183], v[28:31]
	v_mfma_f32_16x16x32_bf16 v[8:11], v[52:55], v[188:191], v[8:11]
	v_mfma_f32_16x16x32_bf16 v[12:15], v[68:71], v[188:191], v[12:15]
	s_setprio 0
	s_setprio 1
	v_mfma_f32_16x16x32_bf16 v[40:43], v[144:147], v[160:163], v[40:43]
	v_mfma_f32_16x16x32_bf16 v[68:71], v[148:151], v[164:167], v[40:43]
	v_mfma_f32_16x16x32_bf16 v[40:43], v[152:155], v[160:163], v[44:47]
	v_mfma_f32_16x16x32_bf16 v[36:39], v[144:147], v[168:171], v[36:39]
	v_mfma_f32_16x16x32_bf16 v[32:35], v[152:155], v[168:171], v[32:35]
	v_mfma_f32_16x16x32_bf16 v[20:23], v[144:147], v[176:179], v[20:23]
	v_mfma_f32_16x16x32_bf16 v[16:19], v[152:155], v[176:179], v[16:19]
	v_mfma_f32_16x16x32_bf16 v[4:7], v[144:147], v[184:187], v[4:7]
	v_mfma_f32_16x16x32_bf16 v[0:3], v[152:155], v[184:187], v[0:3]
	v_mfma_f32_16x16x32_bf16 v[64:67], v[156:159], v[164:167], v[40:43]
	v_mfma_f32_16x16x32_bf16 v[36:39], v[148:151], v[172:175], v[36:39]
	v_mfma_f32_16x16x32_bf16 v[32:35], v[156:159], v[172:175], v[32:35]
	v_mfma_f32_16x16x32_bf16 v[20:23], v[148:151], v[180:183], v[20:23]
	v_mfma_f32_16x16x32_bf16 v[16:19], v[156:159], v[180:183], v[16:19]
	v_mfma_f32_16x16x32_bf16 v[4:7], v[148:151], v[188:191], v[4:7]
	v_mfma_f32_16x16x32_bf16 v[0:3], v[156:159], v[188:191], v[0:3]
	s_setprio 0
	s_barrier
	s_cmp_gt_u32 s68, 41
.LBB0_290:
	s_add_i32 s69, 0, 0x11000
	s_add_i32 s76, 0, 0x15400
	v_add_u32_e32 v52, s69, v197
	v_add_u32_e32 v156, s76, v197
	ds_read_b128 v[40:43], v52
	ds_read_b128 v[44:47], v52 offset:64
	ds_read_b128 v[48:51], v52 offset:2176
	ds_read_b128 v[52:55], v52 offset:2240
	ds_read_b128 v[144:147], v156
	ds_read_b128 v[148:151], v156 offset:64
	ds_read_b128 v[152:155], v156 offset:2176
	ds_read_b128 v[156:159], v156 offset:2240
	ds_read_b128 v[160:163], v241
	ds_read_b128 v[164:167], v241 offset:64
	ds_read_b128 v[168:171], v241 offset:2176
	ds_read_b128 v[172:175], v241 offset:2240
	ds_read_b128 v[176:179], v241 offset:4352
	ds_read_b128 v[180:183], v241 offset:4416
	ds_read_b128 v[184:187], v241 offset:6528
	ds_read_b128 v[188:191], v241 offset:6592
	s_add_i32 m0, s0, 0xcc00
	v_lshl_add_u64 v[198:199], s[38:39], 0, v[212:213]
	global_load_lds_dwordx4 v[198:199], off
	s_add_i32 m0, s0, 0xee00
	v_lshl_add_u64 v[198:199], s[38:39], 0, v[214:215]
	global_load_lds_dwordx4 v[198:199], off
	s_add_u32 s40, s38, 0xfff50080
	s_addc_u32 s41, s39, -1
	s_cmp_eq_u32 s68, 40
	s_cselect_b32 s43, s23, s41
	s_cselect_b32 s42, s22, s40
	s_cselect_b32 s41, s45, s27
	s_cselect_b32 s40, s44, s26
	s_waitcnt vmcnt(8)
	s_waitcnt lgkmcnt(0)
	s_barrier
; #define PG8_STAGE(bufoff, gbase, voff) do { _Pragma("unroll") for (int _i = 0; _i < 2; ++_i) \
;         __builtin_amdgcn_global_load_lds((const unsigned*)((const char*)(gbase) + (voff)[_i]), (PG8_LAS unsigned*)(lds + (bufoff) + ldsw + _i * (8 * USTR)), 16, 0, 0); } while (0)
; #define PG8_LDA(dst, b, h) do { _Pragma("unroll") for (int m = 0; m < 4; ++m) _Pragma("unroll") for (int k = 0; k < 2; ++k) dst[m][k] = *(const PG8_LAS bf16x8*)(lds + PG8_SA(b, h) + aoff + m * (2 * USTR) + k * 64); } while (0)
; #define PG8_MMA(ai, bj, At, Bt) do { __builtin_amdgcn_s_setprio(1); _Pragma("unroll") for (int m = 0; m < 4; ++m) _Pragma("unroll") for (int n = 0; n < 2; ++n) _Pragma("unroll") for (int k = 0; k < 2; ++k) \
;         acc[ai][bj][m][n] = __builtin_amdgcn_mfma_f32_16x16x32_bf16(Bt[n][k], At[m][k], acc[ai][bj][m][n], 0, 0, 0); __builtin_amdgcn_s_setprio(0); } while (0)
; #define PG8_WAIT_V(n) asm volatile("s_waitcnt vmcnt(" #n ")" ::: "memory")
; #define PG8_WAIT_L(n) asm volatile("s_waitcnt lgkmcnt(" #n ")" ::: "memory")
; #define PG8_BAR __builtin_amdgcn_s_barrier()
; #define PG8_SCHED __builtin_amdgcn_sched_barrier(0)
; template <class Epi, class Sched, bool ALIGN_EPI, bool SP2>
; __device__ __forceinline__ void gemm_phase(PG8_LAS unsigned char* lds, const Gemm g, const Sched& S, const Epi& E, int wid) {
;     ...
;             PG8_WAIT_V(8); PG8_WAIT_L(0); PG8_BAR; PG8_MMA(0, 0, At, B0); PG8_MMA(0, 1, At, B1); PG8_BAR; PG8_SCHED;
;             PG8_LDA(At, 0, 1); PG8_STAGE(PG8_SB(0, 0), b2, voffB); PG8_STAGE(PG8_SB(0, 1), b2 + hstepB, voffB); PG8_STAGE(PG8_SA(0, 0), a2, voffA);
;             PG8_WAIT_V(8); PG8_WAIT_L(0); PG8_BAR; PG8_MMA(1, 0, At, B0); PG8_MMA(1, 1, At, B1); PG8_BAR; PG8_SCHED;
	s_setprio 1
	s_waitcnt lgkmcnt(0)
	v_mfma_f32_16x16x32_bf16 v[132:135], v[40:43], v[160:163], v[132:135]
	v_mfma_f32_16x16x32_bf16 v[128:131], v[48:51], v[160:163], v[128:131]
	v_mfma_f32_16x16x32_bf16 v[124:127], v[40:43], v[168:171], v[124:127]
	v_mfma_f32_16x16x32_bf16 v[120:123], v[48:51], v[168:171], v[120:123]
	v_mfma_f32_16x16x32_bf16 v[108:111], v[40:43], v[176:179], v[108:111]
	v_mfma_f32_16x16x32_bf16 v[104:107], v[48:51], v[176:179], v[104:107]
	v_mfma_f32_16x16x32_bf16 v[92:95], v[40:43], v[184:187], v[92:95]
	v_mfma_f32_16x16x32_bf16 v[88:91], v[48:51], v[184:187], v[88:91]
	v_mfma_f32_16x16x32_bf16 v[132:135], v[44:47], v[164:167], v[132:135]
	v_mfma_f32_16x16x32_bf16 v[128:131], v[52:55], v[164:167], v[128:131]
	v_mfma_f32_16x16x32_bf16 v[124:127], v[44:47], v[172:175], v[124:127]
	v_mfma_f32_16x16x32_bf16 v[120:123], v[52:55], v[172:175], v[120:123]
	v_mfma_f32_16x16x32_bf16 v[108:111], v[44:47], v[180:183], v[108:111]
	v_mfma_f32_16x16x32_bf16 v[104:107], v[52:55], v[180:183], v[104:107]
	v_mfma_f32_16x16x32_bf16 v[92:95], v[44:47], v[188:191], v[92:95]
	v_mfma_f32_16x16x32_bf16 v[88:91], v[52:55], v[188:191], v[88:91]
	s_setprio 0
	s_setprio 1
	v_mfma_f32_16x16x32_bf16 v[140:143], v[144:147], v[160:163], v[140:143]
	v_mfma_f32_16x16x32_bf16 v[136:139], v[152:155], v[160:163], v[136:139]
	v_mfma_f32_16x16x32_bf16 v[116:119], v[144:147], v[168:171], v[116:119]
	v_mfma_f32_16x16x32_bf16 v[112:115], v[152:155], v[168:171], v[112:115]
	v_mfma_f32_16x16x32_bf16 v[100:103], v[144:147], v[176:179], v[100:103]
	v_mfma_f32_16x16x32_bf16 v[96:99], v[152:155], v[176:179], v[96:99]
	v_mfma_f32_16x16x32_bf16 v[84:87], v[144:147], v[184:187], v[84:87]
	v_mfma_f32_16x16x32_bf16 v[80:83], v[152:155], v[184:187], v[80:83]
	v_mfma_f32_16x16x32_bf16 v[140:143], v[148:151], v[164:167], v[140:143]
	v_mfma_f32_16x16x32_bf16 v[136:139], v[156:159], v[164:167], v[136:139]
	v_mfma_f32_16x16x32_bf16 v[116:119], v[148:151], v[172:175], v[116:119]
	v_mfma_f32_16x16x32_bf16 v[112:115], v[156:159], v[172:175], v[112:115]
	v_mfma_f32_16x16x32_bf16 v[100:103], v[148:151], v[180:183], v[100:103]
	v_mfma_f32_16x16x32_bf16 v[96:99], v[156:159], v[180:183], v[96:99]
	v_mfma_f32_16x16x32_bf16 v[84:87], v[148:151], v[188:191], v[84:87]
	v_mfma_f32_16x16x32_bf16 v[80:83], v[156:159], v[188:191], v[80:83]
	s_setprio 0
	s_barrier
	ds_read_b128 v[160:163], v241 offset:17408
	ds_read_b128 v[164:167], v241 offset:17472
	ds_read_b128 v[168:171], v241 offset:19584
	ds_read_b128 v[172:175], v241 offset:19648
	ds_read_b128 v[176:179], v241 offset:21760
	ds_read_b128 v[180:183], v241 offset:21824
	ds_read_b128 v[184:187], v241 offset:23936
	ds_read_b128 v[188:191], v241 offset:24000
	s_add_i32 s69, s69, s33
	s_mov_b32 m0, s69
	v_lshl_add_u64 v[198:199], s[40:41], 0, v[208:209]
	global_load_lds_dwordx4 v[198:199], off
	s_add_i32 m0, s69, 0x2200
	s_add_u32 s74, s40, 0xb0000
	v_lshl_add_u64 v[200:201], s[40:41], 0, v[210:211]
	s_addc_u32 s75, s41, 0
	s_add_i32 s69, s76, s33
	global_load_lds_dwordx4 v[200:201], off
	v_lshl_add_u64 v[216:217], s[74:75], 0, v[208:209]
	s_mov_b32 m0, s69
	v_lshl_add_u64 v[218:219], s[42:43], 0, v[210:211]
	global_load_lds_dwordx4 v[216:217], off
	s_add_i32 m0, s69, 0x2200
	v_lshl_add_u64 v[216:217], s[74:75], 0, v[210:211]
	global_load_lds_dwordx4 v[216:217], off
	s_mov_b32 m0, s0
	v_lshl_add_u64 v[216:217], s[42:43], 0, v[208:209]
	global_load_lds_dwordx4 v[216:217], off
	s_mov_b32 m0, s5
	s_nop 0
	global_load_lds_dwordx4 v[218:219], off
	s_waitcnt vmcnt(8)
	s_waitcnt lgkmcnt(0)
	s_barrier
	s_setprio 1
	s_waitcnt lgkmcnt(0)
	v_mfma_f32_16x16x32_bf16 v[76:79], v[40:43], v[160:163], v[76:79]
	v_mfma_f32_16x16x32_bf16 v[72:75], v[48:51], v[160:163], v[72:75]
	v_mfma_f32_16x16x32_bf16 v[60:63], v[40:43], v[168:171], v[60:63]
	v_mfma_f32_16x16x32_bf16 v[56:59], v[48:51], v[168:171], v[56:59]
	v_mfma_f32_16x16x32_bf16 v[24:27], v[40:43], v[176:179], v[24:27]
	v_mfma_f32_16x16x32_bf16 v[28:31], v[48:51], v[176:179], v[28:31]
	v_mfma_f32_16x16x32_bf16 v[8:11], v[40:43], v[184:187], v[8:11]
	v_mfma_f32_16x16x32_bf16 v[12:15], v[48:51], v[184:187], v[12:15]
	v_mfma_f32_16x16x32_bf16 v[76:79], v[44:47], v[164:167], v[76:79]
	v_mfma_f32_16x16x32_bf16 v[72:75], v[52:55], v[164:167], v[72:75]
	v_mfma_f32_16x16x32_bf16 v[60:63], v[44:47], v[172:175], v[60:63]
	v_mfma_f32_16x16x32_bf16 v[56:59], v[52:55], v[172:175], v[56:59]
	v_mfma_f32_16x16x32_bf16 v[24:27], v[44:47], v[180:183], v[24:27]
	v_mfma_f32_16x16x32_bf16 v[28:31], v[52:55], v[180:183], v[28:31]
	v_mfma_f32_16x16x32_bf16 v[8:11], v[44:47], v[188:191], v[8:11]
	v_mfma_f32_16x16x32_bf16 v[12:15], v[52:55], v[188:191], v[12:15]
	s_setprio 0
	s_setprio 1
	v_mfma_f32_16x16x32_bf16 v[36:39], v[144:147], v[168:171], v[36:39]
	v_mfma_f32_16x16x32_bf16 v[32:35], v[152:155], v[168:171], v[32:35]
	v_mfma_f32_16x16x32_bf16 v[20:23], v[144:147], v[176:179], v[20:23]
	v_mfma_f32_16x16x32_bf16 v[16:19], v[152:155], v[176:179], v[16:19]
	v_mfma_f32_16x16x32_bf16 v[4:7], v[144:147], v[184:187], v[4:7]
	v_mfma_f32_16x16x32_bf16 v[0:3], v[152:155], v[184:187], v[0:3]
	v_mfma_f32_16x16x32_bf16 v[40:43], v[144:147], v[160:163], v[68:71]
	v_mfma_f32_16x16x32_bf16 v[44:47], v[152:155], v[160:163], v[64:67]
	v_mfma_f32_16x16x32_bf16 v[36:39], v[148:151], v[172:175], v[36:39]
	v_mfma_f32_16x16x32_bf16 v[32:35], v[156:159], v[172:175], v[32:35]
	v_mfma_f32_16x16x32_bf16 v[20:23], v[148:151], v[180:183], v[20:23]
	v_mfma_f32_16x16x32_bf16 v[16:19], v[156:159], v[180:183], v[16:19]
	v_mfma_f32_16x16x32_bf16 v[4:7], v[148:151], v[188:191], v[4:7]
	v_mfma_f32_16x16x32_bf16 v[0:3], v[156:159], v[188:191], v[0:3]
	v_mfma_f32_16x16x32_bf16 v[40:43], v[148:151], v[164:167], v[40:43]
	v_mfma_f32_16x16x32_bf16 v[44:47], v[156:159], v[164:167], v[44:47]
	s_setprio 0
	s_barrier
; #define PG8_STAGE(bufoff, gbase, voff) do { _Pragma("unroll") for (int _i = 0; _i < 2; ++_i) \
;         __builtin_amdgcn_global_load_lds((const unsigned*)((const char*)(gbase) + (voff)[_i]), (PG8_LAS unsigned*)(lds + (bufoff) + ldsw + _i * (8 * USTR)), 16, 0, 0); } while (0)
; #define PG8_LDA(dst, b, h) do { _Pragma("unroll") for (int m = 0; m < 4; ++m) _Pragma("unroll") for (int k = 0; k < 2; ++k) dst[m][k] = *(const PG8_LAS bf16x8*)(lds + PG8_SA(b, h) + aoff + m * (2 * USTR) + k * 64); } while (0)
; #define PG8_LDB(dst, b, h) do { _Pragma("unroll") for (int n = 0; n < 2; ++n) _Pragma("unroll") for (int k = 0; k < 2; ++k) dst[n][k] = *(const PG8_LAS bf16x8*)(lds + PG8_SB(b, h) + boff + n * (2 * USTR) + k * 64); } while (0)
; #define PG8_MMA(ai, bj, At, Bt) do { __builtin_amdgcn_s_setprio(1); _Pragma("unroll") for (int m = 0; m < 4; ++m) _Pragma("unroll") for (int n = 0; n < 2; ++n) _Pragma("unroll") for (int k = 0; k < 2; ++k) \
;         acc[ai][bj][m][n] = __builtin_amdgcn_mfma_f32_16x16x32_bf16(Bt[n][k], At[m][k], acc[ai][bj][m][n], 0, 0, 0); __builtin_amdgcn_s_setprio(0); } while (0)
; #define PG8_WAIT_V(n) asm volatile("s_waitcnt vmcnt(" #n ")" ::: "memory")
; #define PG8_WAIT_L(n) asm volatile("s_waitcnt lgkmcnt(" #n ")" ::: "memory")
; #define PG8_BAR __builtin_amdgcn_s_barrier()
; #define PG8_SCHED __builtin_amdgcn_sched_barrier(0)
; template <class Epi, class Sched, bool ALIGN_EPI, bool SP2>
; __device__ __forceinline__ void gemm_phase(PG8_LAS unsigned char* lds, const Gemm g, const Sched& S, const Epi& E, int wid) {
;     ...
;             PG8_LDB(B0, 1, 0); PG8_LDB(B1, 1, 1); PG8_SCHED; PG8_LDA(At, 1, 0); PG8_STAGE(PG8_SA(0, 1), a2 + hstepA, voffA);
;             PG8_WAIT_V(8); PG8_WAIT_L(0); PG8_BAR; PG8_MMA(0, 0, At, B0); PG8_MMA(0, 1, At, B1); PG8_BAR; PG8_SCHED;
	s_add_i32 s69, 0, 0x19800
	s_add_i32 s74, 0, 0x1dc00
	v_add_u32_e32 v68, s69, v197
	v_add_u32_e32 v156, s74, v197
	ds_read_b128 v[48:51], v68
	ds_read_b128 v[52:55], v68 offset:64
	ds_read_b128 v[64:67], v68 offset:2176
	ds_read_b128 v[68:71], v68 offset:2240
	ds_read_b128 v[144:147], v156
	ds_read_b128 v[148:151], v156 offset:64
	ds_read_b128 v[152:155], v156 offset:2176
	ds_read_b128 v[156:159], v156 offset:2240
	ds_read_b128 v[160:163], v241 offset:34816
	ds_read_b128 v[164:167], v241 offset:34880
	ds_read_b128 v[168:171], v241 offset:36992
	ds_read_b128 v[172:175], v241 offset:37056
	ds_read_b128 v[176:179], v241 offset:39168
	ds_read_b128 v[180:183], v241 offset:39232
	ds_read_b128 v[184:187], v241 offset:41344
	ds_read_b128 v[188:191], v241 offset:41408
	s_add_u32 s42, s42, 0xb0000
	s_addc_u32 s43, s43, 0
	s_mov_b32 m0, s29
	v_lshl_add_u64 v[220:221], s[42:43], 0, v[208:209]
	global_load_lds_dwordx4 v[220:221], off
	s_mov_b32 m0, s56
	v_lshl_add_u64 v[220:221], s[42:43], 0, v[210:211]
	global_load_lds_dwordx4 v[220:221], off
	s_waitcnt vmcnt(8)
	s_waitcnt lgkmcnt(0)
	s_barrier
	s_setprio 1
	s_waitcnt lgkmcnt(0)
	v_mfma_f32_16x16x32_bf16 v[132:135], v[48:51], v[160:163], v[132:135]
	v_mfma_f32_16x16x32_bf16 v[128:131], v[64:67], v[160:163], v[128:131]
	v_mfma_f32_16x16x32_bf16 v[124:127], v[48:51], v[168:171], v[124:127]
	v_mfma_f32_16x16x32_bf16 v[120:123], v[64:67], v[168:171], v[120:123]
	v_mfma_f32_16x16x32_bf16 v[108:111], v[48:51], v[176:179], v[108:111]
	v_mfma_f32_16x16x32_bf16 v[104:107], v[64:67], v[176:179], v[104:107]
	v_mfma_f32_16x16x32_bf16 v[92:95], v[48:51], v[184:187], v[92:95]
	v_mfma_f32_16x16x32_bf16 v[88:91], v[64:67], v[184:187], v[88:91]
	v_mfma_f32_16x16x32_bf16 v[132:135], v[52:55], v[164:167], v[132:135]
	v_mfma_f32_16x16x32_bf16 v[128:131], v[68:71], v[164:167], v[128:131]
	v_mfma_f32_16x16x32_bf16 v[124:127], v[52:55], v[172:175], v[124:127]
	v_mfma_f32_16x16x32_bf16 v[120:123], v[68:71], v[172:175], v[120:123]
	v_mfma_f32_16x16x32_bf16 v[108:111], v[52:55], v[180:183], v[108:111]
	v_mfma_f32_16x16x32_bf16 v[104:107], v[68:71], v[180:183], v[104:107]
	v_mfma_f32_16x16x32_bf16 v[92:95], v[52:55], v[188:191], v[92:95]
	v_mfma_f32_16x16x32_bf16 v[88:91], v[68:71], v[188:191], v[88:91]
	s_setprio 0
	s_setprio 1
	v_mfma_f32_16x16x32_bf16 v[140:143], v[144:147], v[160:163], v[140:143]
	v_mfma_f32_16x16x32_bf16 v[136:139], v[152:155], v[160:163], v[136:139]
	v_mfma_f32_16x16x32_bf16 v[116:119], v[144:147], v[168:171], v[116:119]
	v_mfma_f32_16x16x32_bf16 v[112:115], v[152:155], v[168:171], v[112:115]
	v_mfma_f32_16x16x32_bf16 v[100:103], v[144:147], v[176:179], v[100:103]
	v_mfma_f32_16x16x32_bf16 v[96:99], v[152:155], v[176:179], v[96:99]
	v_mfma_f32_16x16x32_bf16 v[84:87], v[144:147], v[184:187], v[84:87]
	v_mfma_f32_16x16x32_bf16 v[80:83], v[152:155], v[184:187], v[80:83]
	v_mfma_f32_16x16x32_bf16 v[140:143], v[148:151], v[164:167], v[140:143]
	v_mfma_f32_16x16x32_bf16 v[136:139], v[156:159], v[164:167], v[136:139]
	v_mfma_f32_16x16x32_bf16 v[116:119], v[148:151], v[172:175], v[116:119]
	v_mfma_f32_16x16x32_bf16 v[112:115], v[156:159], v[172:175], v[112:115]
	v_mfma_f32_16x16x32_bf16 v[100:103], v[148:151], v[180:183], v[100:103]
	v_mfma_f32_16x16x32_bf16 v[96:99], v[156:159], v[180:183], v[96:99]
	v_mfma_f32_16x16x32_bf16 v[84:87], v[148:151], v[188:191], v[84:87]
	v_mfma_f32_16x16x32_bf16 v[80:83], v[156:159], v[188:191], v[80:83]
	s_setprio 0
	s_barrier
; #define PG8_STAGE(bufoff, gbase, voff) do { _Pragma("unroll") for (int _i = 0; _i < 2; ++_i) \
;         __builtin_amdgcn_global_load_lds((const unsigned*)((const char*)(gbase) + (voff)[_i]), (PG8_LAS unsigned*)(lds + (bufoff) + ldsw + _i * (8 * USTR)), 16, 0, 0); } while (0)
; #define PG8_LDA(dst, b, h) do { _Pragma("unroll") for (int m = 0; m < 4; ++m) _Pragma("unroll") for (int k = 0; k < 2; ++k) dst[m][k] = *(const PG8_LAS bf16x8*)(lds + PG8_SA(b, h) + aoff + m * (2 * USTR) + k * 64); } while (0)
; #define PG8_MMA(ai, bj, At, Bt) do { __builtin_amdgcn_s_setprio(1); _Pragma("unroll") for (int m = 0; m < 4; ++m) _Pragma("unroll") for (int n = 0; n < 2; ++n) _Pragma("unroll") for (int k = 0; k < 2; ++k) \
;         acc[ai][bj][m][n] = __builtin_amdgcn_mfma_f32_16x16x32_bf16(Bt[n][k], At[m][k], acc[ai][bj][m][n], 0, 0, 0); __builtin_amdgcn_s_setprio(0); } while (0)
; #define PG8_WAIT_V(n) asm volatile("s_waitcnt vmcnt(" #n ")" ::: "memory")
; #define PG8_WAIT_L(n) asm volatile("s_waitcnt lgkmcnt(" #n ")" ::: "memory")
; #define PG8_BAR __builtin_amdgcn_s_barrier()
; #define PG8_SCHED __builtin_amdgcn_sched_barrier(0)
; template <class Epi, class Sched, bool ALIGN_EPI, bool SP2>
; __device__ __forceinline__ void gemm_phase(PG8_LAS unsigned char* lds, const Gemm g, const Sched& S, const Epi& E, int wid) {
;     ...
;             PG8_LDA(At, 1, 1); PG8_STAGE(PG8_SB(1, 0), b3, voffB); PG8_STAGE(PG8_SB(1, 1), b3 + hstepB, voffB); PG8_STAGE(PG8_SA(1, 0), a3, voffA);
;             PG8_WAIT_V(8); PG8_WAIT_L(0); PG8_BAR; PG8_MMA(1, 0, At, B0); PG8_MMA(1, 1, At, B1); PG8_BAR; PG8_SCHED;
;     ...
;         if constexpr (ALIGN_EPI) { if (wr == 0) PG8_BAR; }
	ds_read_b128 v[160:163], v241 offset:52224
	ds_read_b128 v[164:167], v241 offset:52288
	ds_read_b128 v[168:171], v241 offset:54400
	ds_read_b128 v[172:175], v241 offset:54464
	ds_read_b128 v[176:179], v241 offset:56576
	ds_read_b128 v[180:183], v241 offset:56640
	ds_read_b128 v[184:187], v241 offset:58752
	ds_read_b128 v[188:191], v241 offset:58816
	s_add_i32 s42, s69, s33
	s_mov_b32 m0, s42
	v_lshl_add_u64 v[198:199], v[198:199], 0, s[6:7]
	global_load_lds_dwordx4 v[198:199], off
	s_add_i32 m0, s42, 0x2200
	s_add_u32 s40, s40, 0xb0080
	v_lshl_add_u64 v[198:199], v[200:201], 0, s[6:7]
	s_addc_u32 s41, s41, 0
	s_add_i32 s42, s74, s33
	global_load_lds_dwordx4 v[198:199], off
	s_mov_b32 m0, s42
	v_lshl_add_u64 v[198:199], s[40:41], 0, v[208:209]
	global_load_lds_dwordx4 v[198:199], off
	s_add_i32 m0, s42, 0x2200
	v_lshl_add_u64 v[198:199], s[40:41], 0, v[210:211]
	global_load_lds_dwordx4 v[198:199], off
	s_mov_b32 m0, s57
	v_lshl_add_u64 v[198:199], v[216:217], 0, s[6:7]
	global_load_lds_dwordx4 v[198:199], off
	s_mov_b32 m0, s70
	v_lshl_add_u64 v[198:199], v[218:219], 0, s[6:7]
	global_load_lds_dwordx4 v[198:199], off
	s_add_i32 s68, s68, 2
	s_add_u32 s38, s38, 0x100
	s_addc_u32 s39, s39, 0
	s_add_u32 s26, s26, 0x100
	s_addc_u32 s27, s27, 0
	s_waitcnt vmcnt(8)
	s_waitcnt lgkmcnt(0)
	s_barrier
	s_setprio 1
	s_waitcnt lgkmcnt(0)
	v_mfma_f32_16x16x32_bf16 v[76:79], v[48:51], v[160:163], v[76:79]
	v_mfma_f32_16x16x32_bf16 v[72:75], v[64:67], v[160:163], v[72:75]
	v_mfma_f32_16x16x32_bf16 v[60:63], v[48:51], v[168:171], v[60:63]
	v_mfma_f32_16x16x32_bf16 v[56:59], v[64:67], v[168:171], v[56:59]
	v_mfma_f32_16x16x32_bf16 v[24:27], v[48:51], v[176:179], v[24:27]
	v_mfma_f32_16x16x32_bf16 v[28:31], v[64:67], v[176:179], v[28:31]
	v_mfma_f32_16x16x32_bf16 v[8:11], v[48:51], v[184:187], v[8:11]
	v_mfma_f32_16x16x32_bf16 v[12:15], v[64:67], v[184:187], v[12:15]
	v_mfma_f32_16x16x32_bf16 v[76:79], v[52:55], v[164:167], v[76:79]
	v_mfma_f32_16x16x32_bf16 v[72:75], v[68:71], v[164:167], v[72:75]
	v_mfma_f32_16x16x32_bf16 v[60:63], v[52:55], v[172:175], v[60:63]
	v_mfma_f32_16x16x32_bf16 v[56:59], v[68:71], v[172:175], v[56:59]
	v_mfma_f32_16x16x32_bf16 v[24:27], v[52:55], v[180:183], v[24:27]
	v_mfma_f32_16x16x32_bf16 v[28:31], v[68:71], v[180:183], v[28:31]
	v_mfma_f32_16x16x32_bf16 v[8:11], v[52:55], v[188:191], v[8:11]
	v_mfma_f32_16x16x32_bf16 v[12:15], v[68:71], v[188:191], v[12:15]
	s_setprio 0
	s_setprio 1
	v_mfma_f32_16x16x32_bf16 v[40:43], v[144:147], v[160:163], v[40:43]
	v_mfma_f32_16x16x32_bf16 v[68:71], v[148:151], v[164:167], v[40:43]
	v_mfma_f32_16x16x32_bf16 v[40:43], v[152:155], v[160:163], v[44:47]
	v_mfma_f32_16x16x32_bf16 v[36:39], v[144:147], v[168:171], v[36:39]
	v_mfma_f32_16x16x32_bf16 v[32:35], v[152:155], v[168:171], v[32:35]
	v_mfma_f32_16x16x32_bf16 v[20:23], v[144:147], v[176:179], v[20:23]
	v_mfma_f32_16x16x32_bf16 v[16:19], v[152:155], v[176:179], v[16:19]
	v_mfma_f32_16x16x32_bf16 v[4:7], v[144:147], v[184:187], v[4:7]
	v_mfma_f32_16x16x32_bf16 v[0:3], v[152:155], v[184:187], v[0:3]
	v_mfma_f32_16x16x32_bf16 v[64:67], v[156:159], v[164:167], v[40:43]
	v_mfma_f32_16x16x32_bf16 v[36:39], v[148:151], v[172:175], v[36:39]
	v_mfma_f32_16x16x32_bf16 v[32:35], v[156:159], v[172:175], v[32:35]
	v_mfma_f32_16x16x32_bf16 v[20:23], v[148:151], v[180:183], v[20:23]
	v_mfma_f32_16x16x32_bf16 v[16:19], v[156:159], v[180:183], v[16:19]
	v_mfma_f32_16x16x32_bf16 v[4:7], v[148:151], v[188:191], v[4:7]
	v_mfma_f32_16x16x32_bf16 v[0:3], v[156:159], v[188:191], v[0:3]
	s_setprio 0
	s_barrier
	s_cmp_gt_u32 s68, 41
	s_cbranch_scc0 .LBB0_290
	s_and_b64 vcc, exec, s[20:21]
	s_cbranch_vccz .LBB0_293
	s_barrier

; #define PG8_STAGE(bufoff, gbase, voff) do { _Pragma("unroll") for (int _i = 0; _i < 2; ++_i) \
;         __builtin_amdgcn_global_load_lds((const unsigned*)((const char*)(gbase) + (voff)[_i]), (PG8_LAS unsigned*)(lds + (bufoff) + ldsw + _i * (8 * USTR)), 16, 0, 0); } while (0)
; #define PG8_LDA(dst, b, h) do { _Pragma("unroll") for (int m = 0; m < 4; ++m) _Pragma("unroll") for (int k = 0; k < 2; ++k) dst[m][k] = *(const PG8_LAS bf16x8*)(lds + PG8_SA(b, h) + aoff + m * (2 * USTR) + k * 64); } while (0)
; #define PG8_LDB(dst, b, h) do { _Pragma("unroll") for (int n = 0; n < 2; ++n) _Pragma("unroll") for (int k = 0; k < 2; ++k) dst[n][k] = *(const PG8_LAS bf16x8*)(lds + PG8_SB(b, h) + boff + n * (2 * USTR) + k * 64); } while (0)
; #define PG8_MMA(ai, bj, At, Bt) do { __builtin_amdgcn_s_setprio(1); _Pragma("unroll") for (int m = 0; m < 4; ++m) _Pragma("unroll") for (int n = 0; n < 2; ++n) _Pragma("unroll") for (int k = 0; k < 2; ++k) \
;         acc[ai][bj][m][n] = __builtin_amdgcn_mfma_f32_16x16x32_bf16(Bt[n][k], At[m][k], acc[ai][bj][m][n], 0, 0, 0); __builtin_amdgcn_s_setprio(0); } while (0)
; #define PG8_WAIT_V(n) asm volatile("s_waitcnt vmcnt(" #n ")" ::: "memory")
; #define PG8_WAIT_L(n) asm volatile("s_waitcnt lgkmcnt(" #n ")" ::: "memory")
; #define PG8_BAR __builtin_amdgcn_s_barrier()
; #define PG8_SCHED __builtin_amdgcn_sched_barrier(0)
; template <class Epi, class Sched, bool ALIGN_EPI, bool SP2>
; __device__ __forceinline__ void gemm_phase(PG8_LAS unsigned char* lds, const Gemm g, const Sched& S, const Epi& E, int wid) {
;     ...
;             const char* a2 = last ? nA : cA + (size_t)(t + 2) * kstep; const char* b2 = last ? nB : cB + (size_t)(t + 2) * kstep;
;     ...
;             PG8_LDB(B0, 0, 0); PG8_LDB(B1, 0, 1); PG8_SCHED; PG8_LDA(At, 0, 0); PG8_STAGE(PG8_SA(1, 1), a1 + hstepA, voffA);
;             PG8_WAIT_V(8); PG8_WAIT_L(0); PG8_BAR; PG8_MMA(0, 0, At, B0); PG8_MMA(0, 1, At, B1); PG8_BAR; PG8_SCHED;
;             PG8_LDA(At, 0, 1); PG8_STAGE(PG8_SB(0, 0), b2, voffB); PG8_STAGE(PG8_SB(0, 1), b2 + hstepB, voffB); PG8_STAGE(PG8_SA(0, 0), a2, voffA);
;             PG8_WAIT_V(8); PG8_WAIT_L(0); PG8_BAR; PG8_MMA(1, 0, At, B0); PG8_MMA(1, 1, At, B1); PG8_BAR; PG8_SCHED;
.Lhb_up:
	s_add_i32 s77, 0, 0x11000
	v_add_u32_e32 v94, s77, v161
	s_add_i32 s89, 0, 0x15400
	ds_read_b128 v[86:89], v94
	ds_read_b128 v[90:93], v94 offset:64
	ds_read_b128 v[164:167], v94 offset:2176
	ds_read_b128 v[168:171], v94 offset:2240
	v_add_u32_e32 v94, s89, v161
	ds_read_b128 v[172:175], v94
	ds_read_b128 v[176:179], v94 offset:64
	ds_read_b128 v[180:183], v94 offset:2176
	ds_read_b128 v[184:187], v94 offset:2240
	ds_read_b128 v[188:191], v163
	ds_read_b128 v[208:211], v163 offset:64
	ds_read_b128 v[212:215], v163 offset:2176
	ds_read_b128 v[216:219], v163 offset:2240
	ds_read_b128 v[220:223], v163 offset:4352
	ds_read_b128 v[224:227], v163 offset:4416
	ds_read_b128 v[228:231], v163 offset:6528
	ds_read_b128 v[242:245], v163 offset:6592
	s_add_i32 m0, s0, 0xcc00
	v_lshl_add_u64 v[94:95], s[38:39], 0, v[154:155]
	global_load_lds_dwordx4 v[94:95], off
	s_add_i32 m0, s0, 0xee00
	v_lshl_add_u64 v[94:95], s[38:39], 0, v[156:157]
	global_load_lds_dwordx4 v[94:95], off
	s_cmp_eq_u32 s76, 12
	s_cselect_b64 s[68:69], -1, 0
	s_add_u32 s70, s38, 0xfffc0080
	s_addc_u32 s71, s39, -1
	s_and_b64 s[68:69], s[68:69], exec
	s_cselect_b32 s71, s26, s71
	s_cselect_b32 s70, s27, s70
	s_cselect_b32 s69, s41, s75
	s_cselect_b32 s68, s73, s74
	s_waitcnt vmcnt(8)
	s_waitcnt lgkmcnt(0)
	s_barrier
	s_setprio 1
	s_waitcnt lgkmcnt(0)
	v_mfma_f32_16x16x32_bf16 v[140:143], v[86:89], v[188:191], 0
	v_mfma_f32_16x16x32_bf16 v[136:139], v[164:167], v[188:191], 0
	v_mfma_f32_16x16x32_bf16 v[124:127], v[86:89], v[212:215], 0
	v_mfma_f32_16x16x32_bf16 v[120:123], v[164:167], v[212:215], 0
	v_mfma_f32_16x16x32_bf16 v[108:111], v[86:89], v[220:223], 0
	v_mfma_f32_16x16x32_bf16 v[104:107], v[164:167], v[220:223], 0
	v_mfma_f32_16x16x32_bf16 v[76:79], v[86:89], v[228:231], 0
	v_mfma_f32_16x16x32_bf16 v[72:75], v[164:167], v[228:231], 0
	v_mfma_f32_16x16x32_bf16 v[140:143], v[90:93], v[208:211], v[140:143]
	v_mfma_f32_16x16x32_bf16 v[136:139], v[168:171], v[208:211], v[136:139]
	v_mfma_f32_16x16x32_bf16 v[124:127], v[90:93], v[216:219], v[124:127]
	v_mfma_f32_16x16x32_bf16 v[120:123], v[168:171], v[216:219], v[120:123]
	v_mfma_f32_16x16x32_bf16 v[108:111], v[90:93], v[224:227], v[108:111]
	v_mfma_f32_16x16x32_bf16 v[104:107], v[168:171], v[224:227], v[104:107]
	v_mfma_f32_16x16x32_bf16 v[76:79], v[90:93], v[242:245], v[76:79]
	v_mfma_f32_16x16x32_bf16 v[72:75], v[168:171], v[242:245], v[72:75]
	s_setprio 0
	s_setprio 1
	v_mfma_f32_16x16x32_bf16 v[132:135], v[172:175], v[188:191], 0
	v_mfma_f32_16x16x32_bf16 v[128:131], v[180:183], v[188:191], 0
	v_mfma_f32_16x16x32_bf16 v[116:119], v[172:175], v[212:215], 0
	v_mfma_f32_16x16x32_bf16 v[112:115], v[180:183], v[212:215], 0
	v_mfma_f32_16x16x32_bf16 v[100:103], v[172:175], v[220:223], 0
	v_mfma_f32_16x16x32_bf16 v[94:97], v[180:183], v[220:223], 0
	v_mfma_f32_16x16x32_bf16 v[68:71], v[172:175], v[228:231], 0
	v_mfma_f32_16x16x32_bf16 v[64:67], v[180:183], v[228:231], 0
	v_mfma_f32_16x16x32_bf16 v[132:135], v[176:179], v[208:211], v[132:135]
	v_mfma_f32_16x16x32_bf16 v[128:131], v[184:187], v[208:211], v[128:131]
	v_mfma_f32_16x16x32_bf16 v[116:119], v[176:179], v[216:219], v[116:119]
	v_mfma_f32_16x16x32_bf16 v[112:115], v[184:187], v[216:219], v[112:115]
	v_mfma_f32_16x16x32_bf16 v[100:103], v[176:179], v[224:227], v[100:103]
	v_mfma_f32_16x16x32_bf16 v[94:97], v[184:187], v[224:227], v[94:97]
	v_mfma_f32_16x16x32_bf16 v[68:71], v[176:179], v[242:245], v[68:71]
	v_mfma_f32_16x16x32_bf16 v[64:67], v[184:187], v[242:245], v[64:67]
	s_setprio 0
	s_barrier
	ds_read_b128 v[188:191], v163 offset:17408
	ds_read_b128 v[208:211], v163 offset:17472
	ds_read_b128 v[212:215], v163 offset:19584
	ds_read_b128 v[216:219], v163 offset:19648
	ds_read_b128 v[220:223], v163 offset:21760
	ds_read_b128 v[224:227], v163 offset:21824
	ds_read_b128 v[228:231], v163 offset:23936
	ds_read_b128 v[242:245], v163 offset:24000
	s_add_i32 s77, s77, s33
	s_mov_b32 m0, s77
	v_lshl_add_u64 v[158:159], s[68:69], 0, v[192:193]
	global_load_lds_dwordx4 v[158:159], off
	s_add_i32 m0, s77, 0x2200
	s_add_u32 s78, s68, 0x40000
	v_lshl_add_u64 v[198:199], s[68:69], 0, v[144:145]
	s_addc_u32 s79, s69, 0
	s_add_i32 s77, s89, s33
	global_load_lds_dwordx4 v[198:199], off
	v_lshl_add_u64 v[98:99], s[78:79], 0, v[192:193]
	s_mov_b32 m0, s77
	v_lshl_add_u64 v[200:201], s[70:71], 0, v[148:149]
	global_load_lds_dwordx4 v[98:99], off
	v_lshl_add_u64 v[98:99], s[78:79], 0, v[144:145]
	s_add_i32 m0, s77, 0x2200
	v_lshl_add_u64 v[232:233], s[70:71], 0, v[146:147]
	global_load_lds_dwordx4 v[98:99], off
	s_mov_b32 m0, s0
	s_nop 0
	global_load_lds_dwordx4 v[200:201], off
	s_mov_b32 m0, s5
	s_nop 0
	global_load_lds_dwordx4 v[232:233], off
	s_waitcnt vmcnt(8)
	s_waitcnt lgkmcnt(0)
	s_barrier
; #define PG8_STAGE(bufoff, gbase, voff) do { _Pragma("unroll") for (int _i = 0; _i < 2; ++_i) \
;         __builtin_amdgcn_global_load_lds((const unsigned*)((const char*)(gbase) + (voff)[_i]), (PG8_LAS unsigned*)(lds + (bufoff) + ldsw + _i * (8 * USTR)), 16, 0, 0); } while (0)
; #define PG8_LDA(dst, b, h) do { _Pragma("unroll") for (int m = 0; m < 4; ++m) _Pragma("unroll") for (int k = 0; k < 2; ++k) dst[m][k] = *(const PG8_LAS bf16x8*)(lds + PG8_SA(b, h) + aoff + m * (2 * USTR) + k * 64); } while (0)
; #define PG8_LDB(dst, b, h) do { _Pragma("unroll") for (int n = 0; n < 2; ++n) _Pragma("unroll") for (int k = 0; k < 2; ++k) dst[n][k] = *(const PG8_LAS bf16x8*)(lds + PG8_SB(b, h) + boff + n * (2 * USTR) + k * 64); } while (0)
; #define PG8_MMA(ai, bj, At, Bt) do { __builtin_amdgcn_s_setprio(1); _Pragma("unroll") for (int m = 0; m < 4; ++m) _Pragma("unroll") for (int n = 0; n < 2; ++n) _Pragma("unroll") for (int k = 0; k < 2; ++k) \
;         acc[ai][bj][m][n] = __builtin_amdgcn_mfma_f32_16x16x32_bf16(Bt[n][k], At[m][k], acc[ai][bj][m][n], 0, 0, 0); __builtin_amdgcn_s_setprio(0); } while (0)
; #define PG8_WAIT_V(n) asm volatile("s_waitcnt vmcnt(" #n ")" ::: "memory")
; #define PG8_WAIT_L(n) asm volatile("s_waitcnt lgkmcnt(" #n ")" ::: "memory")
; #define PG8_BAR __builtin_amdgcn_s_barrier()
; #define PG8_SCHED __builtin_amdgcn_sched_barrier(0)
; template <class Epi, class Sched, bool ALIGN_EPI, bool SP2>
; __device__ __forceinline__ void gemm_phase(PG8_LAS unsigned char* lds, const Gemm g, const Sched& S, const Epi& E, int wid) {
;     ...
;             PG8_WAIT_V(8); PG8_WAIT_L(0); PG8_BAR; PG8_MMA(1, 0, At, B0); PG8_MMA(1, 1, At, B1); PG8_BAR; PG8_SCHED;
;             PG8_LDB(B0, 1, 0); PG8_LDB(B1, 1, 1); PG8_SCHED; PG8_LDA(At, 1, 0); PG8_STAGE(PG8_SA(0, 1), a2 + hstepA, voffA);
;             PG8_WAIT_V(8); PG8_WAIT_L(0); PG8_BAR; PG8_MMA(0, 0, At, B0); PG8_MMA(0, 1, At, B1); PG8_BAR; PG8_SCHED;
	s_setprio 1
	s_waitcnt lgkmcnt(0)
	v_mfma_f32_16x16x32_bf16 v[60:63], v[86:89], v[188:191], 0
	v_mfma_f32_16x16x32_bf16 v[56:59], v[164:167], v[188:191], 0
	v_mfma_f32_16x16x32_bf16 v[44:47], v[86:89], v[212:215], 0
	v_mfma_f32_16x16x32_bf16 v[40:43], v[164:167], v[212:215], 0
	v_mfma_f32_16x16x32_bf16 v[28:31], v[86:89], v[220:223], 0
	v_mfma_f32_16x16x32_bf16 v[24:27], v[164:167], v[220:223], 0
	v_mfma_f32_16x16x32_bf16 v[12:15], v[86:89], v[228:231], 0
	v_mfma_f32_16x16x32_bf16 v[8:11], v[164:167], v[228:231], 0
	v_mfma_f32_16x16x32_bf16 v[60:63], v[90:93], v[208:211], v[60:63]
	v_mfma_f32_16x16x32_bf16 v[56:59], v[168:171], v[208:211], v[56:59]
	v_mfma_f32_16x16x32_bf16 v[44:47], v[90:93], v[216:219], v[44:47]
	v_mfma_f32_16x16x32_bf16 v[40:43], v[168:171], v[216:219], v[40:43]
	v_mfma_f32_16x16x32_bf16 v[28:31], v[90:93], v[224:227], v[28:31]
	v_mfma_f32_16x16x32_bf16 v[24:27], v[168:171], v[224:227], v[24:27]
	v_mfma_f32_16x16x32_bf16 v[12:15], v[90:93], v[242:245], v[12:15]
	v_mfma_f32_16x16x32_bf16 v[8:11], v[168:171], v[242:245], v[8:11]
	s_setprio 0
	s_setprio 1
	v_mfma_f32_16x16x32_bf16 v[52:55], v[172:175], v[188:191], 0
	v_mfma_f32_16x16x32_bf16 v[48:51], v[180:183], v[188:191], 0
	v_mfma_f32_16x16x32_bf16 v[36:39], v[172:175], v[212:215], 0
	v_mfma_f32_16x16x32_bf16 v[32:35], v[180:183], v[212:215], 0
	v_mfma_f32_16x16x32_bf16 v[20:23], v[172:175], v[220:223], 0
	v_mfma_f32_16x16x32_bf16 v[16:19], v[180:183], v[220:223], 0
	v_mfma_f32_16x16x32_bf16 v[4:7], v[172:175], v[228:231], 0
	v_mfma_f32_16x16x32_bf16 v[0:3], v[180:183], v[228:231], 0
	v_mfma_f32_16x16x32_bf16 v[52:55], v[176:179], v[208:211], v[52:55]
	v_mfma_f32_16x16x32_bf16 v[48:51], v[184:187], v[208:211], v[48:51]
	v_mfma_f32_16x16x32_bf16 v[36:39], v[176:179], v[216:219], v[36:39]
	v_mfma_f32_16x16x32_bf16 v[32:35], v[184:187], v[216:219], v[32:35]
	v_mfma_f32_16x16x32_bf16 v[20:23], v[176:179], v[224:227], v[20:23]
	v_mfma_f32_16x16x32_bf16 v[16:19], v[184:187], v[224:227], v[16:19]
	v_mfma_f32_16x16x32_bf16 v[4:7], v[176:179], v[242:245], v[4:7]
	v_mfma_f32_16x16x32_bf16 v[0:3], v[184:187], v[242:245], v[0:3]
	s_setprio 0
	s_barrier
	s_add_i32 s77, 0, 0x19800
	v_add_u32_e32 v98, s77, v161
	s_add_i32 s78, 0, 0x1dc00
	ds_read_b128 v[86:89], v98
	ds_read_b128 v[90:93], v98 offset:64
	ds_read_b128 v[164:167], v98 offset:2176
	ds_read_b128 v[168:171], v98 offset:2240
	v_add_u32_e32 v98, s78, v161
	ds_read_b128 v[172:175], v98
	ds_read_b128 v[176:179], v98 offset:64
	ds_read_b128 v[180:183], v98 offset:2176
	ds_read_b128 v[184:187], v98 offset:2240
	ds_read_b128 v[188:191], v163 offset:34816
	ds_read_b128 v[208:211], v163 offset:34880
	ds_read_b128 v[212:215], v163 offset:36992
	ds_read_b128 v[216:219], v163 offset:37056
	ds_read_b128 v[220:223], v163 offset:39168
	ds_read_b128 v[224:227], v163 offset:39232
	ds_read_b128 v[228:231], v163 offset:41344
	ds_read_b128 v[242:245], v163 offset:41408
	s_add_u32 s70, s70, 0x40000
	s_addc_u32 s71, s71, 0
	s_mov_b32 m0, s10
	v_lshl_add_u64 v[98:99], s[70:71], 0, v[148:149]
	global_load_lds_dwordx4 v[98:99], off
	s_mov_b32 m0, s29
	v_lshl_add_u64 v[98:99], s[70:71], 0, v[146:147]
	global_load_lds_dwordx4 v[98:99], off
	s_waitcnt vmcnt(8)
	s_waitcnt lgkmcnt(0)
	s_barrier
	s_setprio 1
	s_waitcnt lgkmcnt(0)
	v_mfma_f32_16x16x32_bf16 v[140:143], v[86:89], v[188:191], v[140:143]
	v_mfma_f32_16x16x32_bf16 v[136:139], v[164:167], v[188:191], v[136:139]
	v_mfma_f32_16x16x32_bf16 v[124:127], v[86:89], v[212:215], v[124:127]
	v_mfma_f32_16x16x32_bf16 v[120:123], v[164:167], v[212:215], v[120:123]
	v_mfma_f32_16x16x32_bf16 v[108:111], v[86:89], v[220:223], v[108:111]
	v_mfma_f32_16x16x32_bf16 v[104:107], v[164:167], v[220:223], v[104:107]
	v_mfma_f32_16x16x32_bf16 v[76:79], v[86:89], v[228:231], v[76:79]
	v_mfma_f32_16x16x32_bf16 v[72:75], v[164:167], v[228:231], v[72:75]
	v_mfma_f32_16x16x32_bf16 v[140:143], v[90:93], v[208:211], v[140:143]
	v_mfma_f32_16x16x32_bf16 v[136:139], v[168:171], v[208:211], v[136:139]
	v_mfma_f32_16x16x32_bf16 v[124:127], v[90:93], v[216:219], v[124:127]
	v_mfma_f32_16x16x32_bf16 v[120:123], v[168:171], v[216:219], v[120:123]
	v_mfma_f32_16x16x32_bf16 v[108:111], v[90:93], v[224:227], v[108:111]
	v_mfma_f32_16x16x32_bf16 v[104:107], v[168:171], v[224:227], v[104:107]
	v_mfma_f32_16x16x32_bf16 v[76:79], v[90:93], v[242:245], v[76:79]
	v_mfma_f32_16x16x32_bf16 v[72:75], v[168:171], v[242:245], v[72:75]
	s_setprio 0
	s_setprio 1
	v_mfma_f32_16x16x32_bf16 v[132:135], v[172:175], v[188:191], v[132:135]
	v_mfma_f32_16x16x32_bf16 v[128:131], v[180:183], v[188:191], v[128:131]
	v_mfma_f32_16x16x32_bf16 v[116:119], v[172:175], v[212:215], v[116:119]
	v_mfma_f32_16x16x32_bf16 v[112:115], v[180:183], v[212:215], v[112:115]
	v_mfma_f32_16x16x32_bf16 v[98:101], v[172:175], v[220:223], v[100:103]
	v_mfma_f32_16x16x32_bf16 v[94:97], v[180:183], v[220:223], v[94:97]
	v_mfma_f32_16x16x32_bf16 v[68:71], v[172:175], v[228:231], v[68:71]
	v_mfma_f32_16x16x32_bf16 v[64:67], v[180:183], v[228:231], v[64:67]
	v_mfma_f32_16x16x32_bf16 v[132:135], v[176:179], v[208:211], v[132:135]
	v_mfma_f32_16x16x32_bf16 v[128:131], v[184:187], v[208:211], v[128:131]
	v_mfma_f32_16x16x32_bf16 v[116:119], v[176:179], v[216:219], v[116:119]
	v_mfma_f32_16x16x32_bf16 v[112:115], v[184:187], v[216:219], v[112:115]
	v_mfma_f32_16x16x32_bf16 v[100:103], v[176:179], v[224:227], v[98:101]
	v_mfma_f32_16x16x32_bf16 v[96:99], v[184:187], v[224:227], v[94:97]
	v_mfma_f32_16x16x32_bf16 v[68:71], v[176:179], v[242:245], v[68:71]
	v_mfma_f32_16x16x32_bf16 v[64:67], v[184:187], v[242:245], v[64:67]
	s_setprio 0
	s_barrier
; #define PG8_STAGE(bufoff, gbase, voff) do { _Pragma("unroll") for (int _i = 0; _i < 2; ++_i) \
;         __builtin_amdgcn_global_load_lds((const unsigned*)((const char*)(gbase) + (voff)[_i]), (PG8_LAS unsigned*)(lds + (bufoff) + ldsw + _i * (8 * USTR)), 16, 0, 0); } while (0)
; #define PG8_LDA(dst, b, h) do { _Pragma("unroll") for (int m = 0; m < 4; ++m) _Pragma("unroll") for (int k = 0; k < 2; ++k) dst[m][k] = *(const PG8_LAS bf16x8*)(lds + PG8_SA(b, h) + aoff + m * (2 * USTR) + k * 64); } while (0)
; #define PG8_LDB(dst, b, h) do { _Pragma("unroll") for (int n = 0; n < 2; ++n) _Pragma("unroll") for (int k = 0; k < 2; ++k) dst[n][k] = *(const PG8_LAS bf16x8*)(lds + PG8_SB(b, h) + boff + n * (2 * USTR) + k * 64); } while (0)
; #define PG8_MMA(ai, bj, At, Bt) do { __builtin_amdgcn_s_setprio(1); _Pragma("unroll") for (int m = 0; m < 4; ++m) _Pragma("unroll") for (int n = 0; n < 2; ++n) _Pragma("unroll") for (int k = 0; k < 2; ++k) \
;         acc[ai][bj][m][n] = __builtin_amdgcn_mfma_f32_16x16x32_bf16(Bt[n][k], At[m][k], acc[ai][bj][m][n], 0, 0, 0); __builtin_amdgcn_s_setprio(0); } while (0)
; #define PG8_WAIT_V(n) asm volatile("s_waitcnt vmcnt(" #n ")" ::: "memory")
; #define PG8_WAIT_L(n) asm volatile("s_waitcnt lgkmcnt(" #n ")" ::: "memory")
; #define PG8_BAR __builtin_amdgcn_s_barrier()
; #define PG8_SCHED __builtin_amdgcn_sched_barrier(0)
; template <class Epi, class Sched, bool ALIGN_EPI, bool SP2>
; __device__ __forceinline__ void gemm_phase(PG8_LAS unsigned char* lds, const Gemm g, const Sched& S, const Epi& E, int wid) {
;     ...
;             PG8_LDB(B0, 0, 0); PG8_LDB(B1, 0, 1); PG8_SCHED; PG8_LDA(At, 0, 0); PG8_STAGE(PG8_SA(1, 1), a1 + hstepA, voffA);
;             PG8_WAIT_V(8); PG8_WAIT_L(0); PG8_BAR; PG8_MMA(0, 0, At, B0); PG8_MMA(0, 1, At, B1); PG8_BAR; PG8_SCHED;
;     ...
;             PG8_LDA(At, 1, 1); PG8_STAGE(PG8_SB(1, 0), b3, voffB); PG8_STAGE(PG8_SB(1, 1), b3 + hstepB, voffB); PG8_STAGE(PG8_SA(1, 0), a3, voffA);
;             PG8_WAIT_V(8); PG8_WAIT_L(0); PG8_BAR; PG8_MMA(1, 0, At, B0); PG8_MMA(1, 1, At, B1); PG8_BAR; PG8_SCHED;
	ds_read_b128 v[188:191], v163 offset:52224
	ds_read_b128 v[208:211], v163 offset:52288
	ds_read_b128 v[212:215], v163 offset:54400
	ds_read_b128 v[216:219], v163 offset:54464
	ds_read_b128 v[220:223], v163 offset:56576
	ds_read_b128 v[224:227], v163 offset:56640
	ds_read_b128 v[228:231], v163 offset:58752
	ds_read_b128 v[242:245], v163 offset:58816
	s_add_i32 s70, s77, s33
	s_mov_b32 m0, s70
	v_lshl_add_u64 v[94:95], v[158:159], 0, s[6:7]
	global_load_lds_dwordx4 v[94:95], off
	s_add_i32 m0, s70, 0x2200
	s_add_u32 s68, s68, 0x40080
	v_lshl_add_u64 v[94:95], v[198:199], 0, s[6:7]
	s_addc_u32 s69, s69, 0
	s_add_i32 s70, s78, s33
	global_load_lds_dwordx4 v[94:95], off
	s_mov_b32 m0, s70
	v_lshl_add_u64 v[94:95], s[68:69], 0, v[192:193]
	global_load_lds_dwordx4 v[94:95], off
	s_add_i32 m0, s70, 0x2200
	v_lshl_add_u64 v[94:95], s[68:69], 0, v[144:145]
	global_load_lds_dwordx4 v[94:95], off
	s_mov_b32 m0, s56
	v_lshl_add_u64 v[94:95], v[200:201], 0, s[6:7]
	global_load_lds_dwordx4 v[94:95], off
	s_mov_b32 m0, s57
	v_lshl_add_u64 v[94:95], v[232:233], 0, s[6:7]
	global_load_lds_dwordx4 v[94:95], off
	s_add_i32 s76, s76, 2
	s_add_u32 s38, s38, 0x100
	s_addc_u32 s39, s39, 0
	s_add_u32 s74, s74, 0x100
	s_addc_u32 s75, s75, 0
	s_waitcnt vmcnt(8)
	s_waitcnt lgkmcnt(0)
	s_barrier
	s_setprio 1
	s_waitcnt lgkmcnt(0)
	v_mfma_f32_16x16x32_bf16 v[60:63], v[86:89], v[188:191], v[60:63]
	v_mfma_f32_16x16x32_bf16 v[56:59], v[164:167], v[188:191], v[56:59]
	v_mfma_f32_16x16x32_bf16 v[44:47], v[86:89], v[212:215], v[44:47]
	v_mfma_f32_16x16x32_bf16 v[40:43], v[164:167], v[212:215], v[40:43]
	v_mfma_f32_16x16x32_bf16 v[28:31], v[86:89], v[220:223], v[28:31]
	v_mfma_f32_16x16x32_bf16 v[24:27], v[164:167], v[220:223], v[24:27]
	v_mfma_f32_16x16x32_bf16 v[12:15], v[86:89], v[228:231], v[12:15]
	v_mfma_f32_16x16x32_bf16 v[8:11], v[164:167], v[228:231], v[8:11]
	v_mfma_f32_16x16x32_bf16 v[60:63], v[90:93], v[208:211], v[60:63]
	v_mfma_f32_16x16x32_bf16 v[56:59], v[168:171], v[208:211], v[56:59]
	v_mfma_f32_16x16x32_bf16 v[44:47], v[90:93], v[216:219], v[44:47]
	v_mfma_f32_16x16x32_bf16 v[40:43], v[168:171], v[216:219], v[40:43]
	v_mfma_f32_16x16x32_bf16 v[28:31], v[90:93], v[224:227], v[28:31]
	v_mfma_f32_16x16x32_bf16 v[24:27], v[168:171], v[224:227], v[24:27]
	v_mfma_f32_16x16x32_bf16 v[12:15], v[90:93], v[242:245], v[12:15]
	v_mfma_f32_16x16x32_bf16 v[8:11], v[168:171], v[242:245], v[8:11]
	s_setprio 0
	s_setprio 1
	v_mfma_f32_16x16x32_bf16 v[52:55], v[172:175], v[188:191], v[52:55]
	v_mfma_f32_16x16x32_bf16 v[48:51], v[180:183], v[188:191], v[48:51]
	v_mfma_f32_16x16x32_bf16 v[36:39], v[172:175], v[212:215], v[36:39]
	v_mfma_f32_16x16x32_bf16 v[32:35], v[180:183], v[212:215], v[32:35]
	v_mfma_f32_16x16x32_bf16 v[20:23], v[172:175], v[220:223], v[20:23]
	v_mfma_f32_16x16x32_bf16 v[16:19], v[180:183], v[220:223], v[16:19]
	v_mfma_f32_16x16x32_bf16 v[4:7], v[172:175], v[228:231], v[4:7]
	v_mfma_f32_16x16x32_bf16 v[0:3], v[180:183], v[228:231], v[0:3]
	v_mfma_f32_16x16x32_bf16 v[52:55], v[176:179], v[208:211], v[52:55]
	v_mfma_f32_16x16x32_bf16 v[48:51], v[184:187], v[208:211], v[48:51]
	v_mfma_f32_16x16x32_bf16 v[36:39], v[176:179], v[216:219], v[36:39]
	v_mfma_f32_16x16x32_bf16 v[32:35], v[184:187], v[216:219], v[32:35]
	v_mfma_f32_16x16x32_bf16 v[20:23], v[176:179], v[224:227], v[20:23]
	v_mfma_f32_16x16x32_bf16 v[16:19], v[184:187], v[224:227], v[16:19]
	v_mfma_f32_16x16x32_bf16 v[4:7], v[176:179], v[242:245], v[4:7]
	v_mfma_f32_16x16x32_bf16 v[0:3], v[184:187], v[242:245], v[0:3]
	s_setprio 0
	s_barrier
	s_cmp_gt_u32 s76, 13
	s_branch .LBB0_374
.LBB0_373:
	s_add_i32 s77, 0, 0x11000
	v_add_u32_e32 v94, s77, v161
	s_add_i32 s89, 0, 0x15400
	ds_read_b128 v[86:89], v94
	ds_read_b128 v[90:93], v94 offset:64
	ds_read_b128 v[164:167], v94 offset:2176
	ds_read_b128 v[168:171], v94 offset:2240
	v_add_u32_e32 v94, s89, v161
	ds_read_b128 v[172:175], v94
	ds_read_b128 v[176:179], v94 offset:64
	ds_read_b128 v[180:183], v94 offset:2176
	ds_read_b128 v[184:187], v94 offset:2240
	ds_read_b128 v[188:191], v163
	ds_read_b128 v[208:211], v163 offset:64
	ds_read_b128 v[212:215], v163 offset:2176
	ds_read_b128 v[216:219], v163 offset:2240
	ds_read_b128 v[220:223], v163 offset:4352
	ds_read_b128 v[224:227], v163 offset:4416
	ds_read_b128 v[228:231], v163 offset:6528
	ds_read_b128 v[242:245], v163 offset:6592
	s_add_i32 m0, s0, 0xcc00
	v_lshl_add_u64 v[94:95], s[38:39], 0, v[154:155]
	global_load_lds_dwordx4 v[94:95], off
	s_add_i32 m0, s0, 0xee00
	v_lshl_add_u64 v[94:95], s[38:39], 0, v[156:157]
	global_load_lds_dwordx4 v[94:95], off
	s_add_u32 s70, s38, 0xfffc0080
	s_addc_u32 s71, s39, -1
	s_and_b64 s[68:69], s[68:69], exec
	s_cselect_b32 s71, s26, s71
	s_cselect_b32 s70, s27, s70
	s_cselect_b32 s69, s41, s75
	s_cselect_b32 s68, s73, s74
	s_waitcnt vmcnt(8)
	s_waitcnt lgkmcnt(0)
	s_barrier
; #define PG8_STAGE(bufoff, gbase, voff) do { _Pragma("unroll") for (int _i = 0; _i < 2; ++_i) \
;         __builtin_amdgcn_global_load_lds((const unsigned*)((const char*)(gbase) + (voff)[_i]), (PG8_LAS unsigned*)(lds + (bufoff) + ldsw + _i * (8 * USTR)), 16, 0, 0); } while (0)
; #define PG8_LDA(dst, b, h) do { _Pragma("unroll") for (int m = 0; m < 4; ++m) _Pragma("unroll") for (int k = 0; k < 2; ++k) dst[m][k] = *(const PG8_LAS bf16x8*)(lds + PG8_SA(b, h) + aoff + m * (2 * USTR) + k * 64); } while (0)
; #define PG8_LDB(dst, b, h) do { _Pragma("unroll") for (int n = 0; n < 2; ++n) _Pragma("unroll") for (int k = 0; k < 2; ++k) dst[n][k] = *(const PG8_LAS bf16x8*)(lds + PG8_SB(b, h) + boff + n * (2 * USTR) + k * 64); } while (0)
; #define PG8_MMA(ai, bj, At, Bt) do { __builtin_amdgcn_s_setprio(1); _Pragma("unroll") for (int m = 0; m < 4; ++m) _Pragma("unroll") for (int n = 0; n < 2; ++n) _Pragma("unroll") for (int k = 0; k < 2; ++k) \
;         acc[ai][bj][m][n] = __builtin_amdgcn_mfma_f32_16x16x32_bf16(Bt[n][k], At[m][k], acc[ai][bj][m][n], 0, 0, 0); __builtin_amdgcn_s_setprio(0); } while (0)
; #define PG8_WAIT_V(n) asm volatile("s_waitcnt vmcnt(" #n ")" ::: "memory")
; #define PG8_WAIT_L(n) asm volatile("s_waitcnt lgkmcnt(" #n ")" ::: "memory")
; #define PG8_BAR __builtin_amdgcn_s_barrier()
; #define PG8_SCHED __builtin_amdgcn_sched_barrier(0)
; template <class Epi, class Sched, bool ALIGN_EPI, bool SP2>
; __device__ __forceinline__ void gemm_phase(PG8_LAS unsigned char* lds, const Gemm g, const Sched& S, const Epi& E, int wid) {
;     ...
;             PG8_WAIT_V(8); PG8_WAIT_L(0); PG8_BAR; PG8_MMA(0, 0, At, B0); PG8_MMA(0, 1, At, B1); PG8_BAR; PG8_SCHED;
;             PG8_LDA(At, 0, 1); PG8_STAGE(PG8_SB(0, 0), b2, voffB); PG8_STAGE(PG8_SB(0, 1), b2 + hstepB, voffB); PG8_STAGE(PG8_SA(0, 0), a2, voffA);
;             PG8_WAIT_V(8); PG8_WAIT_L(0); PG8_BAR; PG8_MMA(1, 0, At, B0); PG8_MMA(1, 1, At, B1); PG8_BAR; PG8_SCHED;
;             PG8_LDB(B0, 1, 0); PG8_LDB(B1, 1, 1); PG8_SCHED; PG8_LDA(At, 1, 0); PG8_STAGE(PG8_SA(0, 1), a2 + hstepA, voffA);
;             PG8_WAIT_V(8); PG8_WAIT_L(0); PG8_BAR; PG8_MMA(0, 0, At, B0); PG8_MMA(0, 1, At, B1); PG8_BAR; PG8_SCHED;
	s_setprio 1
	s_waitcnt lgkmcnt(0)
	v_mfma_f32_16x16x32_bf16 v[140:143], v[86:89], v[188:191], v[140:143]
	v_mfma_f32_16x16x32_bf16 v[136:139], v[164:167], v[188:191], v[136:139]
	v_mfma_f32_16x16x32_bf16 v[124:127], v[86:89], v[212:215], v[124:127]
	v_mfma_f32_16x16x32_bf16 v[120:123], v[164:167], v[212:215], v[120:123]
	v_mfma_f32_16x16x32_bf16 v[108:111], v[86:89], v[220:223], v[108:111]
	v_mfma_f32_16x16x32_bf16 v[104:107], v[164:167], v[220:223], v[104:107]
	v_mfma_f32_16x16x32_bf16 v[76:79], v[86:89], v[228:231], v[76:79]
	v_mfma_f32_16x16x32_bf16 v[72:75], v[164:167], v[228:231], v[72:75]
	v_mfma_f32_16x16x32_bf16 v[140:143], v[90:93], v[208:211], v[140:143]
	v_mfma_f32_16x16x32_bf16 v[136:139], v[168:171], v[208:211], v[136:139]
	v_mfma_f32_16x16x32_bf16 v[124:127], v[90:93], v[216:219], v[124:127]
	v_mfma_f32_16x16x32_bf16 v[120:123], v[168:171], v[216:219], v[120:123]
	v_mfma_f32_16x16x32_bf16 v[108:111], v[90:93], v[224:227], v[108:111]
	v_mfma_f32_16x16x32_bf16 v[104:107], v[168:171], v[224:227], v[104:107]
	v_mfma_f32_16x16x32_bf16 v[76:79], v[90:93], v[242:245], v[76:79]
	v_mfma_f32_16x16x32_bf16 v[72:75], v[168:171], v[242:245], v[72:75]
	s_setprio 0
	s_setprio 1
	v_mfma_f32_16x16x32_bf16 v[132:135], v[172:175], v[188:191], v[132:135]
	v_mfma_f32_16x16x32_bf16 v[128:131], v[180:183], v[188:191], v[128:131]
	v_mfma_f32_16x16x32_bf16 v[116:119], v[172:175], v[212:215], v[116:119]
	v_mfma_f32_16x16x32_bf16 v[112:115], v[180:183], v[212:215], v[112:115]
	v_mfma_f32_16x16x32_bf16 v[100:103], v[172:175], v[220:223], v[100:103]
	v_mfma_f32_16x16x32_bf16 v[94:97], v[180:183], v[220:223], v[96:99]
	v_mfma_f32_16x16x32_bf16 v[68:71], v[172:175], v[228:231], v[68:71]
	v_mfma_f32_16x16x32_bf16 v[64:67], v[180:183], v[228:231], v[64:67]
	v_mfma_f32_16x16x32_bf16 v[132:135], v[176:179], v[208:211], v[132:135]
	v_mfma_f32_16x16x32_bf16 v[128:131], v[184:187], v[208:211], v[128:131]
	v_mfma_f32_16x16x32_bf16 v[116:119], v[176:179], v[216:219], v[116:119]
	v_mfma_f32_16x16x32_bf16 v[112:115], v[184:187], v[216:219], v[112:115]
	v_mfma_f32_16x16x32_bf16 v[100:103], v[176:179], v[224:227], v[100:103]
	v_mfma_f32_16x16x32_bf16 v[94:97], v[184:187], v[224:227], v[94:97]
	v_mfma_f32_16x16x32_bf16 v[68:71], v[176:179], v[242:245], v[68:71]
	v_mfma_f32_16x16x32_bf16 v[64:67], v[184:187], v[242:245], v[64:67]
	s_setprio 0
	s_barrier
	ds_read_b128 v[188:191], v163 offset:17408
	ds_read_b128 v[208:211], v163 offset:17472
	ds_read_b128 v[212:215], v163 offset:19584
	ds_read_b128 v[216:219], v163 offset:19648
	ds_read_b128 v[220:223], v163 offset:21760
	ds_read_b128 v[224:227], v163 offset:21824
	ds_read_b128 v[228:231], v163 offset:23936
	ds_read_b128 v[242:245], v163 offset:24000
	s_add_i32 s77, s77, s33
	s_mov_b32 m0, s77
	v_lshl_add_u64 v[158:159], s[68:69], 0, v[192:193]
	global_load_lds_dwordx4 v[158:159], off
	s_add_i32 m0, s77, 0x2200
	s_add_u32 s78, s68, 0x40000
	v_lshl_add_u64 v[198:199], s[68:69], 0, v[144:145]
	s_addc_u32 s79, s69, 0
	s_add_i32 s77, s89, s33
	global_load_lds_dwordx4 v[198:199], off
	v_lshl_add_u64 v[98:99], s[78:79], 0, v[192:193]
	s_mov_b32 m0, s77
	v_lshl_add_u64 v[200:201], s[70:71], 0, v[148:149]
	global_load_lds_dwordx4 v[98:99], off
	v_lshl_add_u64 v[98:99], s[78:79], 0, v[144:145]
	s_add_i32 m0, s77, 0x2200
	v_lshl_add_u64 v[232:233], s[70:71], 0, v[146:147]
	global_load_lds_dwordx4 v[98:99], off
	s_mov_b32 m0, s0
	s_nop 0
	global_load_lds_dwordx4 v[200:201], off
	s_mov_b32 m0, s5
	s_nop 0
	global_load_lds_dwordx4 v[232:233], off
	s_waitcnt vmcnt(8)
	s_waitcnt lgkmcnt(0)
	s_barrier
	s_setprio 1
	s_waitcnt lgkmcnt(0)
	v_mfma_f32_16x16x32_bf16 v[60:63], v[86:89], v[188:191], v[60:63]
	v_mfma_f32_16x16x32_bf16 v[56:59], v[164:167], v[188:191], v[56:59]
	v_mfma_f32_16x16x32_bf16 v[44:47], v[86:89], v[212:215], v[44:47]
	v_mfma_f32_16x16x32_bf16 v[40:43], v[164:167], v[212:215], v[40:43]
	v_mfma_f32_16x16x32_bf16 v[28:31], v[86:89], v[220:223], v[28:31]
	v_mfma_f32_16x16x32_bf16 v[24:27], v[164:167], v[220:223], v[24:27]
	v_mfma_f32_16x16x32_bf16 v[12:15], v[86:89], v[228:231], v[12:15]
	v_mfma_f32_16x16x32_bf16 v[8:11], v[164:167], v[228:231], v[8:11]
	v_mfma_f32_16x16x32_bf16 v[60:63], v[90:93], v[208:211], v[60:63]
	v_mfma_f32_16x16x32_bf16 v[56:59], v[168:171], v[208:211], v[56:59]
	v_mfma_f32_16x16x32_bf16 v[44:47], v[90:93], v[216:219], v[44:47]
	v_mfma_f32_16x16x32_bf16 v[40:43], v[168:171], v[216:219], v[40:43]
	v_mfma_f32_16x16x32_bf16 v[28:31], v[90:93], v[224:227], v[28:31]
	v_mfma_f32_16x16x32_bf16 v[24:27], v[168:171], v[224:227], v[24:27]
	v_mfma_f32_16x16x32_bf16 v[12:15], v[90:93], v[242:245], v[12:15]
	v_mfma_f32_16x16x32_bf16 v[8:11], v[168:171], v[242:245], v[8:11]
	s_setprio 0
	s_setprio 1
	v_mfma_f32_16x16x32_bf16 v[52:55], v[172:175], v[188:191], v[52:55]
	v_mfma_f32_16x16x32_bf16 v[48:51], v[180:183], v[188:191], v[48:51]
	v_mfma_f32_16x16x32_bf16 v[36:39], v[172:175], v[212:215], v[36:39]
	v_mfma_f32_16x16x32_bf16 v[32:35], v[180:183], v[212:215], v[32:35]
	v_mfma_f32_16x16x32_bf16 v[20:23], v[172:175], v[220:223], v[20:23]
	v_mfma_f32_16x16x32_bf16 v[16:19], v[180:183], v[220:223], v[16:19]
	v_mfma_f32_16x16x32_bf16 v[4:7], v[172:175], v[228:231], v[4:7]
	v_mfma_f32_16x16x32_bf16 v[0:3], v[180:183], v[228:231], v[0:3]
	v_mfma_f32_16x16x32_bf16 v[52:55], v[176:179], v[208:211], v[52:55]
	v_mfma_f32_16x16x32_bf16 v[48:51], v[184:187], v[208:211], v[48:51]
	v_mfma_f32_16x16x32_bf16 v[36:39], v[176:179], v[216:219], v[36:39]
	v_mfma_f32_16x16x32_bf16 v[32:35], v[184:187], v[216:219], v[32:35]
	v_mfma_f32_16x16x32_bf16 v[20:23], v[176:179], v[224:227], v[20:23]
	v_mfma_f32_16x16x32_bf16 v[16:19], v[184:187], v[224:227], v[16:19]
	v_mfma_f32_16x16x32_bf16 v[4:7], v[176:179], v[242:245], v[4:7]
	v_mfma_f32_16x16x32_bf16 v[0:3], v[184:187], v[242:245], v[0:3]
	s_setprio 0
	s_barrier
; #define PG8_STAGE(bufoff, gbase, voff) do { _Pragma("unroll") for (int _i = 0; _i < 2; ++_i) \
;         __builtin_amdgcn_global_load_lds((const unsigned*)((const char*)(gbase) + (voff)[_i]), (PG8_LAS unsigned*)(lds + (bufoff) + ldsw + _i * (8 * USTR)), 16, 0, 0); } while (0)
; #define PG8_LDA(dst, b, h) do { _Pragma("unroll") for (int m = 0; m < 4; ++m) _Pragma("unroll") for (int k = 0; k < 2; ++k) dst[m][k] = *(const PG8_LAS bf16x8*)(lds + PG8_SA(b, h) + aoff + m * (2 * USTR) + k * 64); } while (0)
; #define PG8_LDB(dst, b, h) do { _Pragma("unroll") for (int n = 0; n < 2; ++n) _Pragma("unroll") for (int k = 0; k < 2; ++k) dst[n][k] = *(const PG8_LAS bf16x8*)(lds + PG8_SB(b, h) + boff + n * (2 * USTR) + k * 64); } while (0)
; #define PG8_MMA(ai, bj, At, Bt) do { __builtin_amdgcn_s_setprio(1); _Pragma("unroll") for (int m = 0; m < 4; ++m) _Pragma("unroll") for (int n = 0; n < 2; ++n) _Pragma("unroll") for (int k = 0; k < 2; ++k) \
;         acc[ai][bj][m][n] = __builtin_amdgcn_mfma_f32_16x16x32_bf16(Bt[n][k], At[m][k], acc[ai][bj][m][n], 0, 0, 0); __builtin_amdgcn_s_setprio(0); } while (0)
; #define PG8_WAIT_V(n) asm volatile("s_waitcnt vmcnt(" #n ")" ::: "memory")
; #define PG8_WAIT_L(n) asm volatile("s_waitcnt lgkmcnt(" #n ")" ::: "memory")
; #define PG8_BAR __builtin_amdgcn_s_barrier()
; #define PG8_SCHED __builtin_amdgcn_sched_barrier(0)
; template <class Epi, class Sched, bool ALIGN_EPI, bool SP2>
; __device__ __forceinline__ void gemm_phase(PG8_LAS unsigned char* lds, const Gemm g, const Sched& S, const Epi& E, int wid) {
;     ...
;             PG8_LDB(B0, 1, 0); PG8_LDB(B1, 1, 1); PG8_SCHED; PG8_LDA(At, 1, 0); PG8_STAGE(PG8_SA(0, 1), a2 + hstepA, voffA);
;             PG8_WAIT_V(8); PG8_WAIT_L(0); PG8_BAR; PG8_MMA(0, 0, At, B0); PG8_MMA(0, 1, At, B1); PG8_BAR; PG8_SCHED;
;             PG8_LDA(At, 1, 1); PG8_STAGE(PG8_SB(1, 0), b3, voffB); PG8_STAGE(PG8_SB(1, 1), b3 + hstepB, voffB); PG8_STAGE(PG8_SA(1, 0), a3, voffA);
;             PG8_WAIT_V(8); PG8_WAIT_L(0); PG8_BAR; PG8_MMA(1, 0, At, B0); PG8_MMA(1, 1, At, B1); PG8_BAR; PG8_SCHED;
	s_add_i32 s77, 0, 0x19800
	v_add_u32_e32 v98, s77, v161
	s_add_i32 s78, 0, 0x1dc00
	ds_read_b128 v[86:89], v98
	ds_read_b128 v[90:93], v98 offset:64
	ds_read_b128 v[164:167], v98 offset:2176
	ds_read_b128 v[168:171], v98 offset:2240
	v_add_u32_e32 v98, s78, v161
	ds_read_b128 v[172:175], v98
	ds_read_b128 v[176:179], v98 offset:64
	ds_read_b128 v[180:183], v98 offset:2176
	ds_read_b128 v[184:187], v98 offset:2240
	ds_read_b128 v[188:191], v163 offset:34816
	ds_read_b128 v[208:211], v163 offset:34880
	ds_read_b128 v[212:215], v163 offset:36992
	ds_read_b128 v[216:219], v163 offset:37056
	ds_read_b128 v[220:223], v163 offset:39168
	ds_read_b128 v[224:227], v163 offset:39232
	ds_read_b128 v[228:231], v163 offset:41344
	ds_read_b128 v[242:245], v163 offset:41408
	s_add_u32 s70, s70, 0x40000
	s_addc_u32 s71, s71, 0
	s_mov_b32 m0, s10
	v_lshl_add_u64 v[98:99], s[70:71], 0, v[148:149]
	global_load_lds_dwordx4 v[98:99], off
	s_mov_b32 m0, s29
	v_lshl_add_u64 v[98:99], s[70:71], 0, v[146:147]
	global_load_lds_dwordx4 v[98:99], off
	s_waitcnt vmcnt(8)
	s_waitcnt lgkmcnt(0)
	s_barrier
	s_setprio 1
	s_waitcnt lgkmcnt(0)
	v_mfma_f32_16x16x32_bf16 v[140:143], v[86:89], v[188:191], v[140:143]
	v_mfma_f32_16x16x32_bf16 v[136:139], v[164:167], v[188:191], v[136:139]
	v_mfma_f32_16x16x32_bf16 v[124:127], v[86:89], v[212:215], v[124:127]
	v_mfma_f32_16x16x32_bf16 v[120:123], v[164:167], v[212:215], v[120:123]
	v_mfma_f32_16x16x32_bf16 v[108:111], v[86:89], v[220:223], v[108:111]
	v_mfma_f32_16x16x32_bf16 v[104:107], v[164:167], v[220:223], v[104:107]
	v_mfma_f32_16x16x32_bf16 v[76:79], v[86:89], v[228:231], v[76:79]
	v_mfma_f32_16x16x32_bf16 v[72:75], v[164:167], v[228:231], v[72:75]
	v_mfma_f32_16x16x32_bf16 v[140:143], v[90:93], v[208:211], v[140:143]
	v_mfma_f32_16x16x32_bf16 v[136:139], v[168:171], v[208:211], v[136:139]
	v_mfma_f32_16x16x32_bf16 v[124:127], v[90:93], v[216:219], v[124:127]
	v_mfma_f32_16x16x32_bf16 v[120:123], v[168:171], v[216:219], v[120:123]
	v_mfma_f32_16x16x32_bf16 v[108:111], v[90:93], v[224:227], v[108:111]
	v_mfma_f32_16x16x32_bf16 v[104:107], v[168:171], v[224:227], v[104:107]
	v_mfma_f32_16x16x32_bf16 v[76:79], v[90:93], v[242:245], v[76:79]
	v_mfma_f32_16x16x32_bf16 v[72:75], v[168:171], v[242:245], v[72:75]
	s_setprio 0
	s_setprio 1
	v_mfma_f32_16x16x32_bf16 v[132:135], v[172:175], v[188:191], v[132:135]
	v_mfma_f32_16x16x32_bf16 v[128:131], v[180:183], v[188:191], v[128:131]
	v_mfma_f32_16x16x32_bf16 v[116:119], v[172:175], v[212:215], v[116:119]
	v_mfma_f32_16x16x32_bf16 v[112:115], v[180:183], v[212:215], v[112:115]
	v_mfma_f32_16x16x32_bf16 v[98:101], v[172:175], v[220:223], v[100:103]
	v_mfma_f32_16x16x32_bf16 v[94:97], v[180:183], v[220:223], v[94:97]
	v_mfma_f32_16x16x32_bf16 v[68:71], v[172:175], v[228:231], v[68:71]
	v_mfma_f32_16x16x32_bf16 v[64:67], v[180:183], v[228:231], v[64:67]
	v_mfma_f32_16x16x32_bf16 v[132:135], v[176:179], v[208:211], v[132:135]
	v_mfma_f32_16x16x32_bf16 v[128:131], v[184:187], v[208:211], v[128:131]
	v_mfma_f32_16x16x32_bf16 v[116:119], v[176:179], v[216:219], v[116:119]
	v_mfma_f32_16x16x32_bf16 v[112:115], v[184:187], v[216:219], v[112:115]
	v_mfma_f32_16x16x32_bf16 v[100:103], v[176:179], v[224:227], v[98:101]
	v_mfma_f32_16x16x32_bf16 v[96:99], v[184:187], v[224:227], v[94:97]
	v_mfma_f32_16x16x32_bf16 v[68:71], v[176:179], v[242:245], v[68:71]
	v_mfma_f32_16x16x32_bf16 v[64:67], v[184:187], v[242:245], v[64:67]
	s_setprio 0
	s_barrier
	ds_read_b128 v[188:191], v163 offset:52224
	ds_read_b128 v[208:211], v163 offset:52288
	ds_read_b128 v[212:215], v163 offset:54400
	ds_read_b128 v[216:219], v163 offset:54464
	ds_read_b128 v[220:223], v163 offset:56576
	ds_read_b128 v[224:227], v163 offset:56640
	ds_read_b128 v[228:231], v163 offset:58752
	ds_read_b128 v[242:245], v163 offset:58816
	s_add_i32 s70, s77, s33
	s_mov_b32 m0, s70
	v_lshl_add_u64 v[94:95], v[158:159], 0, s[6:7]
	global_load_lds_dwordx4 v[94:95], off
	s_add_i32 m0, s70, 0x2200
	s_add_u32 s68, s68, 0x40080
	v_lshl_add_u64 v[94:95], v[198:199], 0, s[6:7]
	s_addc_u32 s69, s69, 0
	s_add_i32 s70, s78, s33
	global_load_lds_dwordx4 v[94:95], off
	s_mov_b32 m0, s70
	v_lshl_add_u64 v[94:95], s[68:69], 0, v[192:193]
	global_load_lds_dwordx4 v[94:95], off
	s_add_i32 m0, s70, 0x2200
	v_lshl_add_u64 v[94:95], s[68:69], 0, v[144:145]
	global_load_lds_dwordx4 v[94:95], off
	s_mov_b32 m0, s56
	v_lshl_add_u64 v[94:95], v[200:201], 0, s[6:7]
	global_load_lds_dwordx4 v[94:95], off
	s_mov_b32 m0, s57
	v_lshl_add_u64 v[94:95], v[232:233], 0, s[6:7]
	global_load_lds_dwordx4 v[94:95], off
	s_add_i32 s76, s76, 2
	s_add_u32 s38, s38, 0x100
	s_addc_u32 s39, s39, 0
	s_add_u32 s74, s74, 0x100
	s_addc_u32 s75, s75, 0
	s_waitcnt vmcnt(8)
	s_waitcnt lgkmcnt(0)
	s_barrier
	s_setprio 1
	s_waitcnt lgkmcnt(0)
	v_mfma_f32_16x16x32_bf16 v[60:63], v[86:89], v[188:191], v[60:63]
	v_mfma_f32_16x16x32_bf16 v[56:59], v[164:167], v[188:191], v[56:59]
	v_mfma_f32_16x16x32_bf16 v[44:47], v[86:89], v[212:215], v[44:47]
	v_mfma_f32_16x16x32_bf16 v[40:43], v[164:167], v[212:215], v[40:43]
	v_mfma_f32_16x16x32_bf16 v[28:31], v[86:89], v[220:223], v[28:31]
	v_mfma_f32_16x16x32_bf16 v[24:27], v[164:167], v[220:223], v[24:27]
	v_mfma_f32_16x16x32_bf16 v[12:15], v[86:89], v[228:231], v[12:15]
	v_mfma_f32_16x16x32_bf16 v[8:11], v[164:167], v[228:231], v[8:11]
	v_mfma_f32_16x16x32_bf16 v[60:63], v[90:93], v[208:211], v[60:63]
	v_mfma_f32_16x16x32_bf16 v[56:59], v[168:171], v[208:211], v[56:59]
	v_mfma_f32_16x16x32_bf16 v[44:47], v[90:93], v[216:219], v[44:47]
	v_mfma_f32_16x16x32_bf16 v[40:43], v[168:171], v[216:219], v[40:43]
	v_mfma_f32_16x16x32_bf16 v[28:31], v[90:93], v[224:227], v[28:31]
	v_mfma_f32_16x16x32_bf16 v[24:27], v[168:171], v[224:227], v[24:27]
	v_mfma_f32_16x16x32_bf16 v[12:15], v[90:93], v[242:245], v[12:15]
	v_mfma_f32_16x16x32_bf16 v[8:11], v[168:171], v[242:245], v[8:11]
	s_setprio 0
	s_setprio 1
	v_mfma_f32_16x16x32_bf16 v[52:55], v[172:175], v[188:191], v[52:55]
	v_mfma_f32_16x16x32_bf16 v[48:51], v[180:183], v[188:191], v[48:51]
	v_mfma_f32_16x16x32_bf16 v[36:39], v[172:175], v[212:215], v[36:39]
	v_mfma_f32_16x16x32_bf16 v[32:35], v[180:183], v[212:215], v[32:35]
	v_mfma_f32_16x16x32_bf16 v[20:23], v[172:175], v[220:223], v[20:23]
	v_mfma_f32_16x16x32_bf16 v[16:19], v[180:183], v[220:223], v[16:19]
	v_mfma_f32_16x16x32_bf16 v[4:7], v[172:175], v[228:231], v[4:7]
	v_mfma_f32_16x16x32_bf16 v[0:3], v[180:183], v[228:231], v[0:3]
	v_mfma_f32_16x16x32_bf16 v[52:55], v[176:179], v[208:211], v[52:55]
	v_mfma_f32_16x16x32_bf16 v[48:51], v[184:187], v[208:211], v[48:51]
	v_mfma_f32_16x16x32_bf16 v[36:39], v[176:179], v[216:219], v[36:39]
	v_mfma_f32_16x16x32_bf16 v[32:35], v[184:187], v[216:219], v[32:35]
	v_mfma_f32_16x16x32_bf16 v[20:23], v[176:179], v[224:227], v[20:23]
	v_mfma_f32_16x16x32_bf16 v[16:19], v[184:187], v[224:227], v[16:19]
	v_mfma_f32_16x16x32_bf16 v[4:7], v[176:179], v[242:245], v[4:7]
	v_mfma_f32_16x16x32_bf16 v[0:3], v[184:187], v[242:245], v[0:3]
	s_setprio 0
	s_barrier
	s_cmp_gt_u32 s76, 13
	s_cbranch_scc1 .LBB0_377

; #define PG8_STAGE(bufoff, gbase, voff) do { _Pragma("unroll") for (int _i = 0; _i < 2; ++_i) \
;         __builtin_amdgcn_global_load_lds((const unsigned*)((const char*)(gbase) + (voff)[_i]), (PG8_LAS unsigned*)(lds + (bufoff) + ldsw + _i * (8 * USTR)), 16, 0, 0); } while (0)
; #define PG8_LDA(dst, b, h) do { _Pragma("unroll") for (int m = 0; m < 4; ++m) _Pragma("unroll") for (int k = 0; k < 2; ++k) dst[m][k] = *(const PG8_LAS bf16x8*)(lds + PG8_SA(b, h) + aoff + m * (2 * USTR) + k * 64); } while (0)
; #define PG8_LDB(dst, b, h) do { _Pragma("unroll") for (int n = 0; n < 2; ++n) _Pragma("unroll") for (int k = 0; k < 2; ++k) dst[n][k] = *(const PG8_LAS bf16x8*)(lds + PG8_SB(b, h) + boff + n * (2 * USTR) + k * 64); } while (0)
; #define PG8_MMA(ai, bj, At, Bt) do { __builtin_amdgcn_s_setprio(1); _Pragma("unroll") for (int m = 0; m < 4; ++m) _Pragma("unroll") for (int n = 0; n < 2; ++n) _Pragma("unroll") for (int k = 0; k < 2; ++k) \
;         acc[ai][bj][m][n] = __builtin_amdgcn_mfma_f32_16x16x32_bf16(Bt[n][k], At[m][k], acc[ai][bj][m][n], 0, 0, 0); __builtin_amdgcn_s_setprio(0); } while (0)
; #define PG8_WAIT_V(n) asm volatile("s_waitcnt vmcnt(" #n ")" ::: "memory")
; #define PG8_WAIT_L(n) asm volatile("s_waitcnt lgkmcnt(" #n ")" ::: "memory")
; #define PG8_BAR __builtin_amdgcn_s_barrier()
; #define PG8_SCHED __builtin_amdgcn_sched_barrier(0)
; template <class Epi, class Sched, bool ALIGN_EPI, bool SP2>
; __device__ __forceinline__ void gemm_phase(PG8_LAS unsigned char* lds, const Gemm g, const Sched& S, const Epi& E, int wid) {
;     ...
;             const char* a2 = last ? nA : cA + (size_t)(t + 2) * kstep; const char* b2 = last ? nB : cB + (size_t)(t + 2) * kstep;
;     ...
;             PG8_LDB(B0, 0, 0); PG8_LDB(B1, 0, 1); PG8_SCHED; PG8_LDA(At, 0, 0); PG8_STAGE(PG8_SA(1, 1), a1 + hstepA, voffA);
;             PG8_WAIT_V(8); PG8_WAIT_L(0); PG8_BAR; PG8_MMA(0, 0, At, B0); PG8_MMA(0, 1, At, B1); PG8_BAR; PG8_SCHED;
;             PG8_LDA(At, 0, 1); PG8_STAGE(PG8_SB(0, 0), b2, voffB); PG8_STAGE(PG8_SB(0, 1), b2 + hstepB, voffB); PG8_STAGE(PG8_SA(0, 0), a2, voffA);
;             PG8_WAIT_V(8); PG8_WAIT_L(0); PG8_BAR; PG8_MMA(1, 0, At, B0); PG8_MMA(1, 1, At, B1); PG8_BAR; PG8_SCHED;
.Lhb_mixin:
	s_add_i32 s73, 0, 0x11000
	v_add_u32_e32 v30, s73, v197
	s_add_i32 vcc_lo, 0, 0x15400
	ds_read_b128 v[22:25], v30
	ds_read_b128 v[26:29], v30 offset:64
	ds_read_b128 v[158:161], v30 offset:2176
	ds_read_b128 v[162:165], v30 offset:2240
	v_add_u32_e32 v30, vcc_lo, v197
	ds_read_b128 v[166:169], v30
	ds_read_b128 v[170:173], v30 offset:64
	ds_read_b128 v[174:177], v30 offset:2176
	ds_read_b128 v[178:181], v30 offset:2240
	ds_read_b128 v[182:185], v210
	ds_read_b128 v[186:189], v210 offset:64
	ds_read_b128 v[212:215], v210 offset:2176
	ds_read_b128 v[216:219], v210 offset:2240
	ds_read_b128 v[220:223], v210 offset:4352
	ds_read_b128 v[224:227], v210 offset:4416
	ds_read_b128 v[228:231], v210 offset:6528
	ds_read_b128 v[242:245], v210 offset:6592
	s_add_i32 m0, s95, 0xcc00
	v_lshl_add_u64 v[30:31], s[38:39], 0, v[154:155]
	global_load_lds_dwordx4 v[30:31], off
	s_add_i32 m0, s95, 0xee00
	v_lshl_add_u64 v[30:31], s[38:39], 0, v[156:157]
	global_load_lds_dwordx4 v[30:31], off
	s_cmp_eq_u32 s71, 12
	s_cselect_b64 s[40:41], -1, 0
	s_add_u32 s42, s38, 0xfffc0080
	s_addc_u32 s43, s39, -1
	s_and_b64 s[40:41], s[40:41], exec
	s_cselect_b32 s43, s10, s43
	s_cselect_b32 s42, s44, s42
	s_cselect_b32 s41, s45, s70
	s_cselect_b32 s40, s69, s23
	s_waitcnt vmcnt(8)
	s_waitcnt lgkmcnt(0)
	s_barrier
	s_setprio 1
	s_waitcnt lgkmcnt(0)
	v_mfma_f32_16x16x32_bf16 v[140:143], v[22:25], v[182:185], 0
	v_mfma_f32_16x16x32_bf16 v[136:139], v[158:161], v[182:185], 0
	v_mfma_f32_16x16x32_bf16 v[124:127], v[22:25], v[212:215], 0
	v_mfma_f32_16x16x32_bf16 v[120:123], v[158:161], v[212:215], 0
	v_mfma_f32_16x16x32_bf16 v[108:111], v[22:25], v[220:223], 0
	v_mfma_f32_16x16x32_bf16 v[104:107], v[158:161], v[220:223], 0
	v_mfma_f32_16x16x32_bf16 v[92:95], v[22:25], v[228:231], 0
	v_mfma_f32_16x16x32_bf16 v[88:91], v[158:161], v[228:231], 0
	v_mfma_f32_16x16x32_bf16 v[140:143], v[26:29], v[186:189], v[140:143]
	v_mfma_f32_16x16x32_bf16 v[136:139], v[162:165], v[186:189], v[136:139]
	v_mfma_f32_16x16x32_bf16 v[124:127], v[26:29], v[216:219], v[124:127]
	v_mfma_f32_16x16x32_bf16 v[120:123], v[162:165], v[216:219], v[120:123]
	v_mfma_f32_16x16x32_bf16 v[108:111], v[26:29], v[224:227], v[108:111]
	v_mfma_f32_16x16x32_bf16 v[104:107], v[162:165], v[224:227], v[104:107]
	v_mfma_f32_16x16x32_bf16 v[92:95], v[26:29], v[242:245], v[92:95]
	v_mfma_f32_16x16x32_bf16 v[88:91], v[162:165], v[242:245], v[88:91]
	s_setprio 0
	s_setprio 1
	v_mfma_f32_16x16x32_bf16 v[132:135], v[166:169], v[182:185], 0
	v_mfma_f32_16x16x32_bf16 v[128:131], v[174:177], v[182:185], 0
	v_mfma_f32_16x16x32_bf16 v[116:119], v[166:169], v[212:215], 0
	v_mfma_f32_16x16x32_bf16 v[112:115], v[174:177], v[212:215], 0
	v_mfma_f32_16x16x32_bf16 v[100:103], v[166:169], v[220:223], 0
	v_mfma_f32_16x16x32_bf16 v[96:99], v[174:177], v[220:223], 0
	v_mfma_f32_16x16x32_bf16 v[84:87], v[166:169], v[228:231], 0
	v_mfma_f32_16x16x32_bf16 v[80:83], v[174:177], v[228:231], 0
	v_mfma_f32_16x16x32_bf16 v[132:135], v[170:173], v[186:189], v[132:135]
	v_mfma_f32_16x16x32_bf16 v[128:131], v[178:181], v[186:189], v[128:131]
	v_mfma_f32_16x16x32_bf16 v[116:119], v[170:173], v[216:219], v[116:119]
	v_mfma_f32_16x16x32_bf16 v[112:115], v[178:181], v[216:219], v[112:115]
	v_mfma_f32_16x16x32_bf16 v[100:103], v[170:173], v[224:227], v[100:103]
	v_mfma_f32_16x16x32_bf16 v[96:99], v[178:181], v[224:227], v[96:99]
	v_mfma_f32_16x16x32_bf16 v[84:87], v[170:173], v[242:245], v[84:87]
	v_mfma_f32_16x16x32_bf16 v[80:83], v[178:181], v[242:245], v[80:83]
	s_setprio 0
	s_barrier
	ds_read_b128 v[182:185], v210 offset:17408
	ds_read_b128 v[186:189], v210 offset:17472
	ds_read_b128 v[212:215], v210 offset:19584
	ds_read_b128 v[216:219], v210 offset:19648
	ds_read_b128 v[220:223], v210 offset:21760
	ds_read_b128 v[224:227], v210 offset:21824
	ds_read_b128 v[228:231], v210 offset:23936
	ds_read_b128 v[242:245], v210 offset:24000
	s_add_i32 s73, s73, s33
	s_mov_b32 m0, s73
	v_lshl_add_u64 v[190:191], s[40:41], 0, v[192:193]
	global_load_lds_dwordx4 v[190:191], off
	s_add_i32 m0, s73, 0x2200
	s_add_u32 s76, s40, 0x40000
	v_lshl_add_u64 v[198:199], s[40:41], 0, v[146:147]
	s_addc_u32 s77, s41, 0
	s_add_i32 s73, vcc_lo, s33
	global_load_lds_dwordx4 v[198:199], off
	v_lshl_add_u64 v[30:31], s[76:77], 0, v[192:193]
	s_mov_b32 m0, s73
	v_lshl_add_u64 v[200:201], s[42:43], 0, v[150:151]
	global_load_lds_dwordx4 v[30:31], off
	v_lshl_add_u64 v[30:31], s[76:77], 0, v[146:147]
	s_add_i32 m0, s73, 0x2200
	v_lshl_add_u64 v[208:209], s[42:43], 0, v[148:149]
	global_load_lds_dwordx4 v[30:31], off
	s_mov_b32 m0, s95
	s_nop 0
	global_load_lds_dwordx4 v[200:201], off
	s_mov_b32 m0, s5
	s_nop 0
	global_load_lds_dwordx4 v[208:209], off
	s_waitcnt vmcnt(8)
	s_waitcnt lgkmcnt(0)
	s_barrier
; #define PG8_STAGE(bufoff, gbase, voff) do { _Pragma("unroll") for (int _i = 0; _i < 2; ++_i) \
;         __builtin_amdgcn_global_load_lds((const unsigned*)((const char*)(gbase) + (voff)[_i]), (PG8_LAS unsigned*)(lds + (bufoff) + ldsw + _i * (8 * USTR)), 16, 0, 0); } while (0)
; #define PG8_LDA(dst, b, h) do { _Pragma("unroll") for (int m = 0; m < 4; ++m) _Pragma("unroll") for (int k = 0; k < 2; ++k) dst[m][k] = *(const PG8_LAS bf16x8*)(lds + PG8_SA(b, h) + aoff + m * (2 * USTR) + k * 64); } while (0)
; #define PG8_LDB(dst, b, h) do { _Pragma("unroll") for (int n = 0; n < 2; ++n) _Pragma("unroll") for (int k = 0; k < 2; ++k) dst[n][k] = *(const PG8_LAS bf16x8*)(lds + PG8_SB(b, h) + boff + n * (2 * USTR) + k * 64); } while (0)
; #define PG8_MMA(ai, bj, At, Bt) do { __builtin_amdgcn_s_setprio(1); _Pragma("unroll") for (int m = 0; m < 4; ++m) _Pragma("unroll") for (int n = 0; n < 2; ++n) _Pragma("unroll") for (int k = 0; k < 2; ++k) \
;         acc[ai][bj][m][n] = __builtin_amdgcn_mfma_f32_16x16x32_bf16(Bt[n][k], At[m][k], acc[ai][bj][m][n], 0, 0, 0); __builtin_amdgcn_s_setprio(0); } while (0)
; #define PG8_WAIT_V(n) asm volatile("s_waitcnt vmcnt(" #n ")" ::: "memory")
; #define PG8_WAIT_L(n) asm volatile("s_waitcnt lgkmcnt(" #n ")" ::: "memory")
; #define PG8_BAR __builtin_amdgcn_s_barrier()
; #define PG8_SCHED __builtin_amdgcn_sched_barrier(0)
; template <class Epi, class Sched, bool ALIGN_EPI, bool SP2>
; __device__ __forceinline__ void gemm_phase(PG8_LAS unsigned char* lds, const Gemm g, const Sched& S, const Epi& E, int wid) {
;     ...
;             PG8_WAIT_V(8); PG8_WAIT_L(0); PG8_BAR; PG8_MMA(1, 0, At, B0); PG8_MMA(1, 1, At, B1); PG8_BAR; PG8_SCHED;
;             PG8_LDB(B0, 1, 0); PG8_LDB(B1, 1, 1); PG8_SCHED; PG8_LDA(At, 1, 0); PG8_STAGE(PG8_SA(0, 1), a2 + hstepA, voffA);
;             PG8_WAIT_V(8); PG8_WAIT_L(0); PG8_BAR; PG8_MMA(0, 0, At, B0); PG8_MMA(0, 1, At, B1); PG8_BAR; PG8_SCHED;
	s_setprio 1
	s_waitcnt lgkmcnt(0)
	v_mfma_f32_16x16x32_bf16 v[76:79], v[22:25], v[182:185], 0
	v_mfma_f32_16x16x32_bf16 v[72:75], v[158:161], v[182:185], 0
	v_mfma_f32_16x16x32_bf16 v[60:63], v[22:25], v[212:215], 0
	v_mfma_f32_16x16x32_bf16 v[56:59], v[158:161], v[212:215], 0
	v_mfma_f32_16x16x32_bf16 v[44:47], v[22:25], v[220:223], 0
	v_mfma_f32_16x16x32_bf16 v[40:43], v[158:161], v[220:223], 0
	v_mfma_f32_16x16x32_bf16 v[12:15], v[22:25], v[228:231], 0
	v_mfma_f32_16x16x32_bf16 v[8:11], v[158:161], v[228:231], 0
	v_mfma_f32_16x16x32_bf16 v[76:79], v[26:29], v[186:189], v[76:79]
	v_mfma_f32_16x16x32_bf16 v[72:75], v[162:165], v[186:189], v[72:75]
	v_mfma_f32_16x16x32_bf16 v[60:63], v[26:29], v[216:219], v[60:63]
	v_mfma_f32_16x16x32_bf16 v[56:59], v[162:165], v[216:219], v[56:59]
	v_mfma_f32_16x16x32_bf16 v[44:47], v[26:29], v[224:227], v[44:47]
	v_mfma_f32_16x16x32_bf16 v[40:43], v[162:165], v[224:227], v[40:43]
	v_mfma_f32_16x16x32_bf16 v[12:15], v[26:29], v[242:245], v[12:15]
	v_mfma_f32_16x16x32_bf16 v[8:11], v[162:165], v[242:245], v[8:11]
	s_setprio 0
	s_setprio 1
	v_mfma_f32_16x16x32_bf16 v[52:55], v[166:169], v[212:215], 0
	v_mfma_f32_16x16x32_bf16 v[48:51], v[174:177], v[212:215], 0
	v_mfma_f32_16x16x32_bf16 v[36:39], v[166:169], v[220:223], 0
	v_mfma_f32_16x16x32_bf16 v[30:33], v[174:177], v[220:223], 0
	v_mfma_f32_16x16x32_bf16 v[4:7], v[166:169], v[228:231], 0
	v_mfma_f32_16x16x32_bf16 v[0:3], v[174:177], v[228:231], 0
	v_mfma_f32_16x16x32_bf16 v[22:25], v[166:169], v[182:185], 0
	v_mfma_f32_16x16x32_bf16 v[26:29], v[174:177], v[182:185], 0
	v_mfma_f32_16x16x32_bf16 v[52:55], v[170:173], v[216:219], v[52:55]
	v_mfma_f32_16x16x32_bf16 v[48:51], v[178:181], v[216:219], v[48:51]
	v_mfma_f32_16x16x32_bf16 v[36:39], v[170:173], v[224:227], v[36:39]
	v_mfma_f32_16x16x32_bf16 v[30:33], v[178:181], v[224:227], v[30:33]
	v_mfma_f32_16x16x32_bf16 v[4:7], v[170:173], v[242:245], v[4:7]
	v_mfma_f32_16x16x32_bf16 v[0:3], v[178:181], v[242:245], v[0:3]
	v_mfma_f32_16x16x32_bf16 v[22:25], v[170:173], v[186:189], v[22:25]
	v_mfma_f32_16x16x32_bf16 v[26:29], v[178:181], v[186:189], v[26:29]
	s_setprio 0
	s_barrier
	s_add_i32 s73, 0, 0x19800
	v_add_u32_e32 v34, s73, v197
	s_add_i32 s76, 0, 0x1dc00
	ds_read_b128 v[64:67], v34
	ds_read_b128 v[68:71], v34 offset:64
	ds_read_b128 v[158:161], v34 offset:2176
	ds_read_b128 v[162:165], v34 offset:2240
	v_add_u32_e32 v34, s76, v197
	ds_read_b128 v[166:169], v34
	ds_read_b128 v[170:173], v34 offset:64
	ds_read_b128 v[174:177], v34 offset:2176
	ds_read_b128 v[178:181], v34 offset:2240
	ds_read_b128 v[182:185], v210 offset:34816
	ds_read_b128 v[186:189], v210 offset:34880
	ds_read_b128 v[212:215], v210 offset:36992
	ds_read_b128 v[216:219], v210 offset:37056
	ds_read_b128 v[220:223], v210 offset:39168
	ds_read_b128 v[224:227], v210 offset:39232
	ds_read_b128 v[228:231], v210 offset:41344
	ds_read_b128 v[242:245], v210 offset:41408
	s_add_u32 s42, s42, 0x40000
	s_addc_u32 s43, s43, 0
	s_mov_b32 m0, s56
	v_lshl_add_u64 v[34:35], s[42:43], 0, v[150:151]
	global_load_lds_dwordx4 v[34:35], off
	s_mov_b32 m0, s57
	v_lshl_add_u64 v[34:35], s[42:43], 0, v[148:149]
	global_load_lds_dwordx4 v[34:35], off
	s_waitcnt vmcnt(8)
	s_waitcnt lgkmcnt(0)
	s_barrier
	s_setprio 1
	s_waitcnt lgkmcnt(0)
	v_mfma_f32_16x16x32_bf16 v[140:143], v[64:67], v[182:185], v[140:143]
	v_mfma_f32_16x16x32_bf16 v[136:139], v[158:161], v[182:185], v[136:139]
	v_mfma_f32_16x16x32_bf16 v[124:127], v[64:67], v[212:215], v[124:127]
	v_mfma_f32_16x16x32_bf16 v[120:123], v[158:161], v[212:215], v[120:123]
	v_mfma_f32_16x16x32_bf16 v[108:111], v[64:67], v[220:223], v[108:111]
	v_mfma_f32_16x16x32_bf16 v[104:107], v[158:161], v[220:223], v[104:107]
	v_mfma_f32_16x16x32_bf16 v[92:95], v[64:67], v[228:231], v[92:95]
	v_mfma_f32_16x16x32_bf16 v[88:91], v[158:161], v[228:231], v[88:91]
	v_mfma_f32_16x16x32_bf16 v[140:143], v[68:71], v[186:189], v[140:143]
	v_mfma_f32_16x16x32_bf16 v[136:139], v[162:165], v[186:189], v[136:139]
	v_mfma_f32_16x16x32_bf16 v[124:127], v[68:71], v[216:219], v[124:127]
	v_mfma_f32_16x16x32_bf16 v[120:123], v[162:165], v[216:219], v[120:123]
	v_mfma_f32_16x16x32_bf16 v[108:111], v[68:71], v[224:227], v[108:111]
	v_mfma_f32_16x16x32_bf16 v[104:107], v[162:165], v[224:227], v[104:107]
	v_mfma_f32_16x16x32_bf16 v[92:95], v[68:71], v[242:245], v[92:95]
	v_mfma_f32_16x16x32_bf16 v[88:91], v[162:165], v[242:245], v[88:91]
	s_setprio 0
	s_setprio 1
	v_mfma_f32_16x16x32_bf16 v[132:135], v[166:169], v[182:185], v[132:135]
	v_mfma_f32_16x16x32_bf16 v[128:131], v[174:177], v[182:185], v[128:131]
	v_mfma_f32_16x16x32_bf16 v[116:119], v[166:169], v[212:215], v[116:119]
	v_mfma_f32_16x16x32_bf16 v[112:115], v[174:177], v[212:215], v[112:115]
	v_mfma_f32_16x16x32_bf16 v[100:103], v[166:169], v[220:223], v[100:103]
	v_mfma_f32_16x16x32_bf16 v[96:99], v[174:177], v[220:223], v[96:99]
	v_mfma_f32_16x16x32_bf16 v[84:87], v[166:169], v[228:231], v[84:87]
	v_mfma_f32_16x16x32_bf16 v[80:83], v[174:177], v[228:231], v[80:83]
	v_mfma_f32_16x16x32_bf16 v[132:135], v[170:173], v[186:189], v[132:135]
	v_mfma_f32_16x16x32_bf16 v[128:131], v[178:181], v[186:189], v[128:131]
	v_mfma_f32_16x16x32_bf16 v[116:119], v[170:173], v[216:219], v[116:119]
	v_mfma_f32_16x16x32_bf16 v[112:115], v[178:181], v[216:219], v[112:115]
	v_mfma_f32_16x16x32_bf16 v[100:103], v[170:173], v[224:227], v[100:103]
	v_mfma_f32_16x16x32_bf16 v[96:99], v[178:181], v[224:227], v[96:99]
	v_mfma_f32_16x16x32_bf16 v[84:87], v[170:173], v[242:245], v[84:87]
	v_mfma_f32_16x16x32_bf16 v[80:83], v[178:181], v[242:245], v[80:83]
	s_setprio 0
	s_barrier
; #define PG8_STAGE(bufoff, gbase, voff) do { _Pragma("unroll") for (int _i = 0; _i < 2; ++_i) \
;         __builtin_amdgcn_global_load_lds((const unsigned*)((const char*)(gbase) + (voff)[_i]), (PG8_LAS unsigned*)(lds + (bufoff) + ldsw + _i * (8 * USTR)), 16, 0, 0); } while (0)
; #define PG8_LDA(dst, b, h) do { _Pragma("unroll") for (int m = 0; m < 4; ++m) _Pragma("unroll") for (int k = 0; k < 2; ++k) dst[m][k] = *(const PG8_LAS bf16x8*)(lds + PG8_SA(b, h) + aoff + m * (2 * USTR) + k * 64); } while (0)
; #define PG8_LDB(dst, b, h) do { _Pragma("unroll") for (int n = 0; n < 2; ++n) _Pragma("unroll") for (int k = 0; k < 2; ++k) dst[n][k] = *(const PG8_LAS bf16x8*)(lds + PG8_SB(b, h) + boff + n * (2 * USTR) + k * 64); } while (0)
; #define PG8_MMA(ai, bj, At, Bt) do { __builtin_amdgcn_s_setprio(1); _Pragma("unroll") for (int m = 0; m < 4; ++m) _Pragma("unroll") for (int n = 0; n < 2; ++n) _Pragma("unroll") for (int k = 0; k < 2; ++k) \
;         acc[ai][bj][m][n] = __builtin_amdgcn_mfma_f32_16x16x32_bf16(Bt[n][k], At[m][k], acc[ai][bj][m][n], 0, 0, 0); __builtin_amdgcn_s_setprio(0); } while (0)
; #define PG8_WAIT_V(n) asm volatile("s_waitcnt vmcnt(" #n ")" ::: "memory")
; #define PG8_WAIT_L(n) asm volatile("s_waitcnt lgkmcnt(" #n ")" ::: "memory")
; #define PG8_BAR __builtin_amdgcn_s_barrier()
; #define PG8_SCHED __builtin_amdgcn_sched_barrier(0)
; template <class Epi, class Sched, bool ALIGN_EPI, bool SP2>
; __device__ __forceinline__ void gemm_phase(PG8_LAS unsigned char* lds, const Gemm g, const Sched& S, const Epi& E, int wid) {
;     ...
;             PG8_LDB(B0, 0, 0); PG8_LDB(B1, 0, 1); PG8_SCHED; PG8_LDA(At, 0, 0); PG8_STAGE(PG8_SA(1, 1), a1 + hstepA, voffA);
;             PG8_WAIT_V(8); PG8_WAIT_L(0); PG8_BAR; PG8_MMA(0, 0, At, B0); PG8_MMA(0, 1, At, B1); PG8_BAR; PG8_SCHED;
;     ...
;             PG8_LDA(At, 1, 1); PG8_STAGE(PG8_SB(1, 0), b3, voffB); PG8_STAGE(PG8_SB(1, 1), b3 + hstepB, voffB); PG8_STAGE(PG8_SA(1, 0), a3, voffA);
;             PG8_WAIT_V(8); PG8_WAIT_L(0); PG8_BAR; PG8_MMA(1, 0, At, B0); PG8_MMA(1, 1, At, B1); PG8_BAR; PG8_SCHED;
	ds_read_b128 v[182:185], v210 offset:52224
	ds_read_b128 v[186:189], v210 offset:52288
	ds_read_b128 v[212:215], v210 offset:54400
	ds_read_b128 v[216:219], v210 offset:54464
	ds_read_b128 v[220:223], v210 offset:56576
	ds_read_b128 v[224:227], v210 offset:56640
	ds_read_b128 v[228:231], v210 offset:58752
	ds_read_b128 v[242:245], v210 offset:58816
	s_add_i32 s42, s73, s33
	s_mov_b32 m0, s42
	v_lshl_add_u64 v[34:35], v[190:191], 0, s[6:7]
	global_load_lds_dwordx4 v[34:35], off
	s_add_i32 m0, s42, 0x2200
	s_add_u32 s40, s40, 0x40080
	v_lshl_add_u64 v[34:35], v[198:199], 0, s[6:7]
	s_addc_u32 s41, s41, 0
	s_add_i32 s42, s76, s33
	global_load_lds_dwordx4 v[34:35], off
	s_mov_b32 m0, s42
	v_lshl_add_u64 v[34:35], s[40:41], 0, v[192:193]
	global_load_lds_dwordx4 v[34:35], off
	s_add_i32 m0, s42, 0x2200
	v_lshl_add_u64 v[34:35], s[40:41], 0, v[146:147]
	global_load_lds_dwordx4 v[34:35], off
	s_mov_b32 m0, s29
	v_lshl_add_u64 v[34:35], v[200:201], 0, s[6:7]
	global_load_lds_dwordx4 v[34:35], off
	s_mov_b32 m0, s0
	v_lshl_add_u64 v[34:35], v[208:209], 0, s[6:7]
	global_load_lds_dwordx4 v[34:35], off
	s_add_i32 s71, s71, 2
	s_add_u32 s38, s38, 0x100
	s_addc_u32 s39, s39, 0
	s_add_u32 s23, s23, 0x100
	s_addc_u32 s70, s70, 0
	s_waitcnt vmcnt(8)
	s_waitcnt lgkmcnt(0)
	s_barrier
	s_setprio 1
	s_waitcnt lgkmcnt(0)
	v_mfma_f32_16x16x32_bf16 v[76:79], v[64:67], v[182:185], v[76:79]
	v_mfma_f32_16x16x32_bf16 v[72:75], v[158:161], v[182:185], v[72:75]
	v_mfma_f32_16x16x32_bf16 v[60:63], v[64:67], v[212:215], v[60:63]
	v_mfma_f32_16x16x32_bf16 v[56:59], v[158:161], v[212:215], v[56:59]
	v_mfma_f32_16x16x32_bf16 v[44:47], v[64:67], v[220:223], v[44:47]
	v_mfma_f32_16x16x32_bf16 v[40:43], v[158:161], v[220:223], v[40:43]
	v_mfma_f32_16x16x32_bf16 v[12:15], v[64:67], v[228:231], v[12:15]
	v_mfma_f32_16x16x32_bf16 v[8:11], v[158:161], v[228:231], v[8:11]
	v_mfma_f32_16x16x32_bf16 v[76:79], v[68:71], v[186:189], v[76:79]
	v_mfma_f32_16x16x32_bf16 v[72:75], v[162:165], v[186:189], v[72:75]
	v_mfma_f32_16x16x32_bf16 v[60:63], v[68:71], v[216:219], v[60:63]
	v_mfma_f32_16x16x32_bf16 v[56:59], v[162:165], v[216:219], v[56:59]
	v_mfma_f32_16x16x32_bf16 v[44:47], v[68:71], v[224:227], v[44:47]
	v_mfma_f32_16x16x32_bf16 v[40:43], v[162:165], v[224:227], v[40:43]
	v_mfma_f32_16x16x32_bf16 v[12:15], v[68:71], v[242:245], v[12:15]
	v_mfma_f32_16x16x32_bf16 v[8:11], v[162:165], v[242:245], v[8:11]
	s_setprio 0
	s_setprio 1
	v_mfma_f32_16x16x32_bf16 v[22:25], v[166:169], v[182:185], v[22:25]
	v_mfma_f32_16x16x32_bf16 v[68:71], v[170:173], v[186:189], v[22:25]
	v_mfma_f32_16x16x32_bf16 v[22:25], v[174:177], v[182:185], v[26:29]
	v_mfma_f32_16x16x32_bf16 v[64:67], v[178:181], v[186:189], v[22:25]
	v_mfma_f32_16x16x32_bf16 v[22:25], v[166:169], v[212:215], v[52:55]
	v_mfma_f32_16x16x32_bf16 v[52:55], v[170:173], v[216:219], v[22:25]
	v_mfma_f32_16x16x32_bf16 v[22:25], v[174:177], v[212:215], v[48:51]
	v_mfma_f32_16x16x32_bf16 v[48:51], v[178:181], v[216:219], v[22:25]
	v_mfma_f32_16x16x32_bf16 v[22:25], v[166:169], v[220:223], v[36:39]
	v_mfma_f32_16x16x32_bf16 v[36:39], v[170:173], v[224:227], v[22:25]
	v_mfma_f32_16x16x32_bf16 v[22:25], v[174:177], v[220:223], v[30:33]
	v_mfma_f32_16x16x32_bf16 v[4:7], v[166:169], v[228:231], v[4:7]
	v_mfma_f32_16x16x32_bf16 v[0:3], v[174:177], v[228:231], v[0:3]
	v_mfma_f32_16x16x32_bf16 v[32:35], v[178:181], v[224:227], v[22:25]
	v_mfma_f32_16x16x32_bf16 v[4:7], v[170:173], v[242:245], v[4:7]
	v_mfma_f32_16x16x32_bf16 v[0:3], v[178:181], v[242:245], v[0:3]
	s_setprio 0
	s_barrier
	s_cmp_gt_u32 s71, 13
	s_branch .LBB0_394
.LBB0_393:
	s_add_i32 s73, 0, 0x11000
	v_add_u32_e32 v30, s73, v197
	s_add_i32 vcc_lo, 0, 0x15400
	ds_read_b128 v[22:25], v30
	ds_read_b128 v[26:29], v30 offset:64
	ds_read_b128 v[158:161], v30 offset:2176
	ds_read_b128 v[162:165], v30 offset:2240
	v_add_u32_e32 v30, vcc_lo, v197
	ds_read_b128 v[166:169], v30
	ds_read_b128 v[170:173], v30 offset:64
	ds_read_b128 v[174:177], v30 offset:2176
	ds_read_b128 v[178:181], v30 offset:2240
	ds_read_b128 v[182:185], v210
	ds_read_b128 v[186:189], v210 offset:64
	ds_read_b128 v[212:215], v210 offset:2176
	ds_read_b128 v[216:219], v210 offset:2240
	ds_read_b128 v[220:223], v210 offset:4352
	ds_read_b128 v[224:227], v210 offset:4416
	ds_read_b128 v[228:231], v210 offset:6528
	ds_read_b128 v[242:245], v210 offset:6592
	s_add_i32 m0, s95, 0xcc00
	v_lshl_add_u64 v[30:31], s[38:39], 0, v[154:155]
	global_load_lds_dwordx4 v[30:31], off
	s_add_i32 m0, s95, 0xee00
	v_lshl_add_u64 v[30:31], s[38:39], 0, v[156:157]
	global_load_lds_dwordx4 v[30:31], off
	s_add_u32 s42, s38, 0xfffc0080
	s_addc_u32 s43, s39, -1
	s_and_b64 s[40:41], s[40:41], exec
	s_cselect_b32 s43, s10, s43
	s_cselect_b32 s42, s44, s42
	s_cselect_b32 s41, s45, s70
	s_cselect_b32 s40, s69, s23
	s_waitcnt vmcnt(8)
	s_waitcnt lgkmcnt(0)
	s_barrier
; #define PG8_STAGE(bufoff, gbase, voff) do { _Pragma("unroll") for (int _i = 0; _i < 2; ++_i) \
;         __builtin_amdgcn_global_load_lds((const unsigned*)((const char*)(gbase) + (voff)[_i]), (PG8_LAS unsigned*)(lds + (bufoff) + ldsw + _i * (8 * USTR)), 16, 0, 0); } while (0)
; #define PG8_LDA(dst, b, h) do { _Pragma("unroll") for (int m = 0; m < 4; ++m) _Pragma("unroll") for (int k = 0; k < 2; ++k) dst[m][k] = *(const PG8_LAS bf16x8*)(lds + PG8_SA(b, h) + aoff + m * (2 * USTR) + k * 64); } while (0)
; #define PG8_MMA(ai, bj, At, Bt) do { __builtin_amdgcn_s_setprio(1); _Pragma("unroll") for (int m = 0; m < 4; ++m) _Pragma("unroll") for (int n = 0; n < 2; ++n) _Pragma("unroll") for (int k = 0; k < 2; ++k) \
;         acc[ai][bj][m][n] = __builtin_amdgcn_mfma_f32_16x16x32_bf16(Bt[n][k], At[m][k], acc[ai][bj][m][n], 0, 0, 0); __builtin_amdgcn_s_setprio(0); } while (0)
; #define PG8_WAIT_V(n) asm volatile("s_waitcnt vmcnt(" #n ")" ::: "memory")
; #define PG8_WAIT_L(n) asm volatile("s_waitcnt lgkmcnt(" #n ")" ::: "memory")
; #define PG8_BAR __builtin_amdgcn_s_barrier()
; #define PG8_SCHED __builtin_amdgcn_sched_barrier(0)
; template <class Epi, class Sched, bool ALIGN_EPI, bool SP2>
; __device__ __forceinline__ void gemm_phase(PG8_LAS unsigned char* lds, const Gemm g, const Sched& S, const Epi& E, int wid) {
;     ...
;             PG8_WAIT_V(8); PG8_WAIT_L(0); PG8_BAR; PG8_MMA(0, 0, At, B0); PG8_MMA(0, 1, At, B1); PG8_BAR; PG8_SCHED;
;             PG8_LDA(At, 0, 1); PG8_STAGE(PG8_SB(0, 0), b2, voffB); PG8_STAGE(PG8_SB(0, 1), b2 + hstepB, voffB); PG8_STAGE(PG8_SA(0, 0), a2, voffA);
;             PG8_WAIT_V(8); PG8_WAIT_L(0); PG8_BAR; PG8_MMA(1, 0, At, B0); PG8_MMA(1, 1, At, B1); PG8_BAR; PG8_SCHED;
	s_setprio 1
	s_waitcnt lgkmcnt(0)
	v_mfma_f32_16x16x32_bf16 v[140:143], v[22:25], v[182:185], v[140:143]
	v_mfma_f32_16x16x32_bf16 v[136:139], v[158:161], v[182:185], v[136:139]
	v_mfma_f32_16x16x32_bf16 v[124:127], v[22:25], v[212:215], v[124:127]
	v_mfma_f32_16x16x32_bf16 v[120:123], v[158:161], v[212:215], v[120:123]
	v_mfma_f32_16x16x32_bf16 v[108:111], v[22:25], v[220:223], v[108:111]
	v_mfma_f32_16x16x32_bf16 v[104:107], v[158:161], v[220:223], v[104:107]
	v_mfma_f32_16x16x32_bf16 v[92:95], v[22:25], v[228:231], v[92:95]
	v_mfma_f32_16x16x32_bf16 v[88:91], v[158:161], v[228:231], v[88:91]
	v_mfma_f32_16x16x32_bf16 v[140:143], v[26:29], v[186:189], v[140:143]
	v_mfma_f32_16x16x32_bf16 v[136:139], v[162:165], v[186:189], v[136:139]
	v_mfma_f32_16x16x32_bf16 v[124:127], v[26:29], v[216:219], v[124:127]
	v_mfma_f32_16x16x32_bf16 v[120:123], v[162:165], v[216:219], v[120:123]
	v_mfma_f32_16x16x32_bf16 v[108:111], v[26:29], v[224:227], v[108:111]
	v_mfma_f32_16x16x32_bf16 v[104:107], v[162:165], v[224:227], v[104:107]
	v_mfma_f32_16x16x32_bf16 v[92:95], v[26:29], v[242:245], v[92:95]
	v_mfma_f32_16x16x32_bf16 v[88:91], v[162:165], v[242:245], v[88:91]
	s_setprio 0
	s_setprio 1
	v_mfma_f32_16x16x32_bf16 v[132:135], v[166:169], v[182:185], v[132:135]
	v_mfma_f32_16x16x32_bf16 v[128:131], v[174:177], v[182:185], v[128:131]
	v_mfma_f32_16x16x32_bf16 v[116:119], v[166:169], v[212:215], v[116:119]
	v_mfma_f32_16x16x32_bf16 v[112:115], v[174:177], v[212:215], v[112:115]
	v_mfma_f32_16x16x32_bf16 v[100:103], v[166:169], v[220:223], v[100:103]
	v_mfma_f32_16x16x32_bf16 v[96:99], v[174:177], v[220:223], v[96:99]
	v_mfma_f32_16x16x32_bf16 v[84:87], v[166:169], v[228:231], v[84:87]
	v_mfma_f32_16x16x32_bf16 v[80:83], v[174:177], v[228:231], v[80:83]
	v_mfma_f32_16x16x32_bf16 v[132:135], v[170:173], v[186:189], v[132:135]
	v_mfma_f32_16x16x32_bf16 v[128:131], v[178:181], v[186:189], v[128:131]
	v_mfma_f32_16x16x32_bf16 v[116:119], v[170:173], v[216:219], v[116:119]
	v_mfma_f32_16x16x32_bf16 v[112:115], v[178:181], v[216:219], v[112:115]
	v_mfma_f32_16x16x32_bf16 v[100:103], v[170:173], v[224:227], v[100:103]
	v_mfma_f32_16x16x32_bf16 v[96:99], v[178:181], v[224:227], v[96:99]
	v_mfma_f32_16x16x32_bf16 v[84:87], v[170:173], v[242:245], v[84:87]
	v_mfma_f32_16x16x32_bf16 v[80:83], v[178:181], v[242:245], v[80:83]
	s_setprio 0
	s_barrier
	ds_read_b128 v[182:185], v210 offset:17408
	ds_read_b128 v[186:189], v210 offset:17472
	ds_read_b128 v[212:215], v210 offset:19584
	ds_read_b128 v[216:219], v210 offset:19648
	ds_read_b128 v[220:223], v210 offset:21760
	ds_read_b128 v[224:227], v210 offset:21824
	ds_read_b128 v[228:231], v210 offset:23936
	ds_read_b128 v[242:245], v210 offset:24000
	s_add_i32 s73, s73, s33
	s_mov_b32 m0, s73
	v_lshl_add_u64 v[190:191], s[40:41], 0, v[192:193]
	global_load_lds_dwordx4 v[190:191], off
	s_add_i32 m0, s73, 0x2200
	s_add_u32 s76, s40, 0x40000
	v_lshl_add_u64 v[198:199], s[40:41], 0, v[146:147]
	s_addc_u32 s77, s41, 0
	s_add_i32 s73, vcc_lo, s33
	global_load_lds_dwordx4 v[198:199], off
	v_lshl_add_u64 v[30:31], s[76:77], 0, v[192:193]
	s_mov_b32 m0, s73
	v_lshl_add_u64 v[200:201], s[42:43], 0, v[150:151]
	global_load_lds_dwordx4 v[30:31], off
	v_lshl_add_u64 v[30:31], s[76:77], 0, v[146:147]
	s_add_i32 m0, s73, 0x2200
	v_lshl_add_u64 v[208:209], s[42:43], 0, v[148:149]
	global_load_lds_dwordx4 v[30:31], off
	s_mov_b32 m0, s95
	s_nop 0
	global_load_lds_dwordx4 v[200:201], off
	s_mov_b32 m0, s5
	s_nop 0
	global_load_lds_dwordx4 v[208:209], off
	s_waitcnt vmcnt(8)
	s_waitcnt lgkmcnt(0)
	s_barrier
	s_setprio 1
	s_waitcnt lgkmcnt(0)
	v_mfma_f32_16x16x32_bf16 v[76:79], v[22:25], v[182:185], v[76:79]
	v_mfma_f32_16x16x32_bf16 v[72:75], v[158:161], v[182:185], v[72:75]
	v_mfma_f32_16x16x32_bf16 v[60:63], v[22:25], v[212:215], v[60:63]
	v_mfma_f32_16x16x32_bf16 v[56:59], v[158:161], v[212:215], v[56:59]
	v_mfma_f32_16x16x32_bf16 v[44:47], v[22:25], v[220:223], v[44:47]
	v_mfma_f32_16x16x32_bf16 v[40:43], v[158:161], v[220:223], v[40:43]
	v_mfma_f32_16x16x32_bf16 v[12:15], v[22:25], v[228:231], v[12:15]
	v_mfma_f32_16x16x32_bf16 v[8:11], v[158:161], v[228:231], v[8:11]
	v_mfma_f32_16x16x32_bf16 v[76:79], v[26:29], v[186:189], v[76:79]
	v_mfma_f32_16x16x32_bf16 v[72:75], v[162:165], v[186:189], v[72:75]
	v_mfma_f32_16x16x32_bf16 v[60:63], v[26:29], v[216:219], v[60:63]
	v_mfma_f32_16x16x32_bf16 v[56:59], v[162:165], v[216:219], v[56:59]
	v_mfma_f32_16x16x32_bf16 v[44:47], v[26:29], v[224:227], v[44:47]
	v_mfma_f32_16x16x32_bf16 v[40:43], v[162:165], v[224:227], v[40:43]
	v_mfma_f32_16x16x32_bf16 v[12:15], v[26:29], v[242:245], v[12:15]
	v_mfma_f32_16x16x32_bf16 v[8:11], v[162:165], v[242:245], v[8:11]
	s_setprio 0
	s_setprio 1
	v_mfma_f32_16x16x32_bf16 v[52:55], v[166:169], v[212:215], v[52:55]
	v_mfma_f32_16x16x32_bf16 v[48:51], v[174:177], v[212:215], v[48:51]
	v_mfma_f32_16x16x32_bf16 v[36:39], v[166:169], v[220:223], v[36:39]
	v_mfma_f32_16x16x32_bf16 v[30:33], v[174:177], v[220:223], v[32:35]
	v_mfma_f32_16x16x32_bf16 v[4:7], v[166:169], v[228:231], v[4:7]
	v_mfma_f32_16x16x32_bf16 v[0:3], v[174:177], v[228:231], v[0:3]
	v_mfma_f32_16x16x32_bf16 v[22:25], v[166:169], v[182:185], v[68:71]
	v_mfma_f32_16x16x32_bf16 v[26:29], v[174:177], v[182:185], v[64:67]
	v_mfma_f32_16x16x32_bf16 v[52:55], v[170:173], v[216:219], v[52:55]
	v_mfma_f32_16x16x32_bf16 v[48:51], v[178:181], v[216:219], v[48:51]
	v_mfma_f32_16x16x32_bf16 v[36:39], v[170:173], v[224:227], v[36:39]
	v_mfma_f32_16x16x32_bf16 v[30:33], v[178:181], v[224:227], v[30:33]
	v_mfma_f32_16x16x32_bf16 v[4:7], v[170:173], v[242:245], v[4:7]
	v_mfma_f32_16x16x32_bf16 v[0:3], v[178:181], v[242:245], v[0:3]
	v_mfma_f32_16x16x32_bf16 v[22:25], v[170:173], v[186:189], v[22:25]
	v_mfma_f32_16x16x32_bf16 v[26:29], v[178:181], v[186:189], v[26:29]
	s_setprio 0
	s_barrier
; #define PG8_STAGE(bufoff, gbase, voff) do { _Pragma("unroll") for (int _i = 0; _i < 2; ++_i) \
;         __builtin_amdgcn_global_load_lds((const unsigned*)((const char*)(gbase) + (voff)[_i]), (PG8_LAS unsigned*)(lds + (bufoff) + ldsw + _i * (8 * USTR)), 16, 0, 0); } while (0)
; #define PG8_LDA(dst, b, h) do { _Pragma("unroll") for (int m = 0; m < 4; ++m) _Pragma("unroll") for (int k = 0; k < 2; ++k) dst[m][k] = *(const PG8_LAS bf16x8*)(lds + PG8_SA(b, h) + aoff + m * (2 * USTR) + k * 64); } while (0)
; #define PG8_LDB(dst, b, h) do { _Pragma("unroll") for (int n = 0; n < 2; ++n) _Pragma("unroll") for (int k = 0; k < 2; ++k) dst[n][k] = *(const PG8_LAS bf16x8*)(lds + PG8_SB(b, h) + boff + n * (2 * USTR) + k * 64); } while (0)
; #define PG8_MMA(ai, bj, At, Bt) do { __builtin_amdgcn_s_setprio(1); _Pragma("unroll") for (int m = 0; m < 4; ++m) _Pragma("unroll") for (int n = 0; n < 2; ++n) _Pragma("unroll") for (int k = 0; k < 2; ++k) \
;         acc[ai][bj][m][n] = __builtin_amdgcn_mfma_f32_16x16x32_bf16(Bt[n][k], At[m][k], acc[ai][bj][m][n], 0, 0, 0); __builtin_amdgcn_s_setprio(0); } while (0)
; #define PG8_WAIT_V(n) asm volatile("s_waitcnt vmcnt(" #n ")" ::: "memory")
; #define PG8_WAIT_L(n) asm volatile("s_waitcnt lgkmcnt(" #n ")" ::: "memory")
; #define PG8_BAR __builtin_amdgcn_s_barrier()
; #define PG8_SCHED __builtin_amdgcn_sched_barrier(0)
; template <class Epi, class Sched, bool ALIGN_EPI, bool SP2>
; __device__ __forceinline__ void gemm_phase(PG8_LAS unsigned char* lds, const Gemm g, const Sched& S, const Epi& E, int wid) {
;     ...
;             PG8_LDB(B0, 1, 0); PG8_LDB(B1, 1, 1); PG8_SCHED; PG8_LDA(At, 1, 0); PG8_STAGE(PG8_SA(0, 1), a2 + hstepA, voffA);
;             PG8_WAIT_V(8); PG8_WAIT_L(0); PG8_BAR; PG8_MMA(0, 0, At, B0); PG8_MMA(0, 1, At, B1); PG8_BAR; PG8_SCHED;
;             PG8_LDA(At, 1, 1); PG8_STAGE(PG8_SB(1, 0), b3, voffB); PG8_STAGE(PG8_SB(1, 1), b3 + hstepB, voffB); PG8_STAGE(PG8_SA(1, 0), a3, voffA);
;             PG8_WAIT_V(8); PG8_WAIT_L(0); PG8_BAR; PG8_MMA(1, 0, At, B0); PG8_MMA(1, 1, At, B1); PG8_BAR; PG8_SCHED;
	s_add_i32 s73, 0, 0x19800
	v_add_u32_e32 v34, s73, v197
	s_add_i32 s76, 0, 0x1dc00
	ds_read_b128 v[64:67], v34
	ds_read_b128 v[68:71], v34 offset:64
	ds_read_b128 v[158:161], v34 offset:2176
	ds_read_b128 v[162:165], v34 offset:2240
	v_add_u32_e32 v34, s76, v197
	ds_read_b128 v[166:169], v34
	ds_read_b128 v[170:173], v34 offset:64
	ds_read_b128 v[174:177], v34 offset:2176
	ds_read_b128 v[178:181], v34 offset:2240
	ds_read_b128 v[182:185], v210 offset:34816
	ds_read_b128 v[186:189], v210 offset:34880
	ds_read_b128 v[212:215], v210 offset:36992
	ds_read_b128 v[216:219], v210 offset:37056
	ds_read_b128 v[220:223], v210 offset:39168
	ds_read_b128 v[224:227], v210 offset:39232
	ds_read_b128 v[228:231], v210 offset:41344
	ds_read_b128 v[242:245], v210 offset:41408
	s_add_u32 s42, s42, 0x40000
	s_addc_u32 s43, s43, 0
	s_mov_b32 m0, s56
	v_lshl_add_u64 v[34:35], s[42:43], 0, v[150:151]
	global_load_lds_dwordx4 v[34:35], off
	s_mov_b32 m0, s57
	v_lshl_add_u64 v[34:35], s[42:43], 0, v[148:149]
	global_load_lds_dwordx4 v[34:35], off
	s_waitcnt vmcnt(8)
	s_waitcnt lgkmcnt(0)
	s_barrier
	s_setprio 1
	s_waitcnt lgkmcnt(0)
	v_mfma_f32_16x16x32_bf16 v[140:143], v[64:67], v[182:185], v[140:143]
	v_mfma_f32_16x16x32_bf16 v[136:139], v[158:161], v[182:185], v[136:139]
	v_mfma_f32_16x16x32_bf16 v[124:127], v[64:67], v[212:215], v[124:127]
	v_mfma_f32_16x16x32_bf16 v[120:123], v[158:161], v[212:215], v[120:123]
	v_mfma_f32_16x16x32_bf16 v[108:111], v[64:67], v[220:223], v[108:111]
	v_mfma_f32_16x16x32_bf16 v[104:107], v[158:161], v[220:223], v[104:107]
	v_mfma_f32_16x16x32_bf16 v[92:95], v[64:67], v[228:231], v[92:95]
	v_mfma_f32_16x16x32_bf16 v[88:91], v[158:161], v[228:231], v[88:91]
	v_mfma_f32_16x16x32_bf16 v[140:143], v[68:71], v[186:189], v[140:143]
	v_mfma_f32_16x16x32_bf16 v[136:139], v[162:165], v[186:189], v[136:139]
	v_mfma_f32_16x16x32_bf16 v[124:127], v[68:71], v[216:219], v[124:127]
	v_mfma_f32_16x16x32_bf16 v[120:123], v[162:165], v[216:219], v[120:123]
	v_mfma_f32_16x16x32_bf16 v[108:111], v[68:71], v[224:227], v[108:111]
	v_mfma_f32_16x16x32_bf16 v[104:107], v[162:165], v[224:227], v[104:107]
	v_mfma_f32_16x16x32_bf16 v[92:95], v[68:71], v[242:245], v[92:95]
	v_mfma_f32_16x16x32_bf16 v[88:91], v[162:165], v[242:245], v[88:91]
	s_setprio 0
	s_setprio 1
	v_mfma_f32_16x16x32_bf16 v[132:135], v[166:169], v[182:185], v[132:135]
	v_mfma_f32_16x16x32_bf16 v[128:131], v[174:177], v[182:185], v[128:131]
	v_mfma_f32_16x16x32_bf16 v[116:119], v[166:169], v[212:215], v[116:119]
	v_mfma_f32_16x16x32_bf16 v[112:115], v[174:177], v[212:215], v[112:115]
	v_mfma_f32_16x16x32_bf16 v[100:103], v[166:169], v[220:223], v[100:103]
	v_mfma_f32_16x16x32_bf16 v[96:99], v[174:177], v[220:223], v[96:99]
	v_mfma_f32_16x16x32_bf16 v[84:87], v[166:169], v[228:231], v[84:87]
	v_mfma_f32_16x16x32_bf16 v[80:83], v[174:177], v[228:231], v[80:83]
	v_mfma_f32_16x16x32_bf16 v[132:135], v[170:173], v[186:189], v[132:135]
	v_mfma_f32_16x16x32_bf16 v[128:131], v[178:181], v[186:189], v[128:131]
	v_mfma_f32_16x16x32_bf16 v[116:119], v[170:173], v[216:219], v[116:119]
	v_mfma_f32_16x16x32_bf16 v[112:115], v[178:181], v[216:219], v[112:115]
	v_mfma_f32_16x16x32_bf16 v[100:103], v[170:173], v[224:227], v[100:103]
	v_mfma_f32_16x16x32_bf16 v[96:99], v[178:181], v[224:227], v[96:99]
	v_mfma_f32_16x16x32_bf16 v[84:87], v[170:173], v[242:245], v[84:87]
	v_mfma_f32_16x16x32_bf16 v[80:83], v[178:181], v[242:245], v[80:83]
	s_setprio 0
	s_barrier
	ds_read_b128 v[182:185], v210 offset:52224
	ds_read_b128 v[186:189], v210 offset:52288
	ds_read_b128 v[212:215], v210 offset:54400
	ds_read_b128 v[216:219], v210 offset:54464
	ds_read_b128 v[220:223], v210 offset:56576
	ds_read_b128 v[224:227], v210 offset:56640
	ds_read_b128 v[228:231], v210 offset:58752
	ds_read_b128 v[242:245], v210 offset:58816
	s_add_i32 s42, s73, s33
	s_mov_b32 m0, s42
	v_lshl_add_u64 v[34:35], v[190:191], 0, s[6:7]
	global_load_lds_dwordx4 v[34:35], off
	s_add_i32 m0, s42, 0x2200
	s_add_u32 s40, s40, 0x40080
	v_lshl_add_u64 v[34:35], v[198:199], 0, s[6:7]
	s_addc_u32 s41, s41, 0
	s_add_i32 s42, s76, s33
	global_load_lds_dwordx4 v[34:35], off
	s_mov_b32 m0, s42
	v_lshl_add_u64 v[34:35], s[40:41], 0, v[192:193]
	global_load_lds_dwordx4 v[34:35], off
	s_add_i32 m0, s42, 0x2200
	v_lshl_add_u64 v[34:35], s[40:41], 0, v[146:147]
	global_load_lds_dwordx4 v[34:35], off
	s_mov_b32 m0, s29
	v_lshl_add_u64 v[34:35], v[200:201], 0, s[6:7]
	global_load_lds_dwordx4 v[34:35], off
	s_mov_b32 m0, s0
	v_lshl_add_u64 v[34:35], v[208:209], 0, s[6:7]
	global_load_lds_dwordx4 v[34:35], off
	s_add_i32 s71, s71, 2
	s_add_u32 s38, s38, 0x100
	s_addc_u32 s39, s39, 0
	s_add_u32 s23, s23, 0x100
	s_addc_u32 s70, s70, 0
	s_waitcnt vmcnt(8)
	s_waitcnt lgkmcnt(0)
	s_barrier
	s_setprio 1
	s_waitcnt lgkmcnt(0)
	v_mfma_f32_16x16x32_bf16 v[76:79], v[64:67], v[182:185], v[76:79]
	v_mfma_f32_16x16x32_bf16 v[72:75], v[158:161], v[182:185], v[72:75]
	v_mfma_f32_16x16x32_bf16 v[60:63], v[64:67], v[212:215], v[60:63]
	v_mfma_f32_16x16x32_bf16 v[56:59], v[158:161], v[212:215], v[56:59]
	v_mfma_f32_16x16x32_bf16 v[44:47], v[64:67], v[220:223], v[44:47]
	v_mfma_f32_16x16x32_bf16 v[40:43], v[158:161], v[220:223], v[40:43]
	v_mfma_f32_16x16x32_bf16 v[12:15], v[64:67], v[228:231], v[12:15]
	v_mfma_f32_16x16x32_bf16 v[8:11], v[158:161], v[228:231], v[8:11]
	v_mfma_f32_16x16x32_bf16 v[76:79], v[68:71], v[186:189], v[76:79]
	v_mfma_f32_16x16x32_bf16 v[72:75], v[162:165], v[186:189], v[72:75]
	v_mfma_f32_16x16x32_bf16 v[60:63], v[68:71], v[216:219], v[60:63]
	v_mfma_f32_16x16x32_bf16 v[56:59], v[162:165], v[216:219], v[56:59]
	v_mfma_f32_16x16x32_bf16 v[44:47], v[68:71], v[224:227], v[44:47]
	v_mfma_f32_16x16x32_bf16 v[40:43], v[162:165], v[224:227], v[40:43]
	v_mfma_f32_16x16x32_bf16 v[12:15], v[68:71], v[242:245], v[12:15]
	v_mfma_f32_16x16x32_bf16 v[8:11], v[162:165], v[242:245], v[8:11]
	s_setprio 0
	s_setprio 1
	v_mfma_f32_16x16x32_bf16 v[22:25], v[166:169], v[182:185], v[22:25]
	v_mfma_f32_16x16x32_bf16 v[68:71], v[170:173], v[186:189], v[22:25]
	v_mfma_f32_16x16x32_bf16 v[22:25], v[174:177], v[182:185], v[26:29]
	v_mfma_f32_16x16x32_bf16 v[64:67], v[178:181], v[186:189], v[22:25]
	v_mfma_f32_16x16x32_bf16 v[22:25], v[166:169], v[212:215], v[52:55]
	v_mfma_f32_16x16x32_bf16 v[52:55], v[170:173], v[216:219], v[22:25]
	v_mfma_f32_16x16x32_bf16 v[22:25], v[174:177], v[212:215], v[48:51]
	v_mfma_f32_16x16x32_bf16 v[48:51], v[178:181], v[216:219], v[22:25]
	v_mfma_f32_16x16x32_bf16 v[22:25], v[166:169], v[220:223], v[36:39]
	v_mfma_f32_16x16x32_bf16 v[36:39], v[170:173], v[224:227], v[22:25]
	v_mfma_f32_16x16x32_bf16 v[22:25], v[174:177], v[220:223], v[30:33]
	v_mfma_f32_16x16x32_bf16 v[4:7], v[166:169], v[228:231], v[4:7]
	v_mfma_f32_16x16x32_bf16 v[0:3], v[174:177], v[228:231], v[0:3]
	v_mfma_f32_16x16x32_bf16 v[32:35], v[178:181], v[224:227], v[22:25]
	v_mfma_f32_16x16x32_bf16 v[4:7], v[170:173], v[242:245], v[4:7]
	v_mfma_f32_16x16x32_bf16 v[0:3], v[178:181], v[242:245], v[0:3]
	s_setprio 0
	s_barrier
	s_cmp_gt_u32 s71, 13
	s_cbranch_scc1 .LBB0_397
